# phase-1 generic (unfused) epilogue replaced by a hand-written specialised store sequence (per 64-column block: linear column remap, kcmp/vcmp copies, misc block)
# speedup vs baseline: 1.6470x; 1.0148x over previous
; DI void phase_in(const Params& p, int L, char* smem) {
;     ...
; #pragma unroll
;     for (int mt = 0; mt < 4; ++mt)
; #pragma unroll
;       for (int i = 0; i < 16; ++i) {
;         const float rs = rstd_s[wm * 128 + mt * 32 + (i & 3) + 8 * (i >> 2) + 4 * hh];
;         acc[mt][0][i] *= rs; acc[mt][1][i] *= rs;
;       }
;     int grp_;
;     if (cb >= 43) grp_ = 16;
;     else if (cb < 8) grp_ = 1;
;     else if ((cb >= 20 && cb < 24) || cb == 26 || cb == 28 || (cb >= 30 && cb < 38)) grp_ = 2;
;     else if ((cb >= 8 && cb < 12) || cb == 27 || cb == 29 || (cb >= 38 && cb < 42)) grp_ = 4;
;     else grp_ = 8;
;     const bool fused_ = (grp_ == 16) || ((FUSE_MASK & grp_) != 0);
;     if (!fused_) {
;       EPI_BEGINM(acc, 4)
;         const int oc = in_colmap(col);
;         if (oc >= 0 && oc < PJN) {
.LBB0_799:
	s_or_b64 exec, exec, s[2:3]
	s_waitcnt lgkmcnt(0)
	s_barrier
	ds_read_b128 v[128:131], v209 offset:55296
	ds_read_b128 v[132:135], v209 offset:55328
	v_lshl_or_b32 v167, s6, 1, v191
	s_movk_i32 s2, 0xffdc
	s_waitcnt lgkmcnt(1)
	v_mul_f32_e32 v151, v96, v128
	v_mul_f32_e32 v150, v97, v129
	v_mul_f32_e32 v149, v98, v130
	v_mul_f32_e32 v148, v99, v131
	ds_read_b128 v[96:99], v209 offset:55360
	v_mul_f32_e32 v166, v112, v128
	v_mul_f32_e32 v165, v113, v129
	v_mul_f32_e32 v164, v114, v130
	v_mul_f32_e32 v163, v115, v131
	ds_read_b128 v[112:115], v209 offset:55392
	s_waitcnt lgkmcnt(1)
	v_mul_f32_e32 v158, v120, v96
	v_mul_f32_e32 v143, v104, v96
	v_mul_f32_e32 v157, v121, v97
	v_mul_f32_e32 v142, v105, v97
	v_mul_f32_e32 v156, v122, v98
	v_mul_f32_e32 v141, v106, v98
	v_mul_f32_e32 v155, v123, v99
	v_mul_f32_e32 v140, v107, v99
	ds_read_b128 v[96:99], v209 offset:55424
	ds_read_b128 v[104:107], v209 offset:55456
	v_mul_f32_e32 v162, v116, v132
	v_mul_f32_e32 v161, v117, v133
	v_mul_f32_e32 v160, v118, v134
	v_mul_f32_e32 v159, v119, v135
	s_waitcnt lgkmcnt(1)
	v_mul_f32_e32 v119, v64, v96
	v_mul_f32_e32 v118, v65, v97
	v_mul_f32_e32 v117, v66, v98
	v_mul_f32_e32 v116, v67, v99
	ds_read_b128 v[64:67], v209 offset:55488
	v_mul_f32_e32 v144, v103, v135
	v_mul_f32_e32 v154, v124, v112
	v_mul_f32_e32 v139, v108, v112
	v_mul_f32_e32 v153, v125, v113
	v_mul_f32_e32 v138, v109, v113
	v_mul_f32_e32 v152, v126, v114
	v_mul_f32_e32 v137, v110, v114
	v_mul_f32_e32 v103, v127, v115
	v_mul_f32_e32 v136, v111, v115
	s_waitcnt lgkmcnt(1)
	v_mul_f32_e32 v115, v68, v104
	v_mul_f32_e32 v114, v69, v105
	v_mul_f32_e32 v113, v70, v106
	v_mul_f32_e32 v112, v71, v107
	ds_read_b128 v[68:71], v209 offset:55520
	s_waitcnt lgkmcnt(1)
	v_mul_f32_e32 v127, v88, v64
	v_mul_f32_e32 v111, v72, v64
	v_mul_f32_e32 v126, v89, v65
	v_mul_f32_e32 v110, v73, v65
	v_mul_f32_e32 v125, v90, v66
	v_mul_f32_e32 v109, v74, v66
	v_mul_f32_e32 v124, v91, v67
	v_mul_f32_e32 v108, v75, v67
	ds_read_b128 v[64:67], v209 offset:55552
	v_mul_f32_e32 v131, v84, v104
	v_mul_f32_e32 v130, v85, v105
	v_mul_f32_e32 v129, v86, v106
	v_mul_f32_e32 v128, v87, v107
	s_waitcnt lgkmcnt(1)
	v_mul_f32_e32 v123, v92, v68
	v_mul_f32_e32 v107, v76, v68
	v_mul_f32_e32 v122, v93, v69
	v_mul_f32_e32 v106, v77, v69
	v_mul_f32_e32 v121, v94, v70
	v_mul_f32_e32 v105, v78, v70
	v_mul_f32_e32 v120, v95, v71
	v_mul_f32_e32 v104, v79, v71
	ds_read_b128 v[68:71], v209 offset:55584
	v_mul_f32_e32 v147, v100, v132
	v_mul_f32_e32 v146, v101, v133
	v_mul_f32_e32 v133, v82, v98
	v_mul_f32_e32 v132, v83, v99
	s_waitcnt lgkmcnt(1)
	v_mul_f32_e32 v85, v32, v64
	v_mul_f32_e32 v84, v33, v65
	v_mul_f32_e32 v83, v34, v66
	v_mul_f32_e32 v82, v35, v67
	ds_read_b128 v[32:35], v209 offset:55616
	v_mul_f32_e32 v145, v102, v134
	v_mul_f32_e32 v135, v80, v96
	v_mul_f32_e32 v134, v81, v97
	s_waitcnt lgkmcnt(1)
	v_mul_f32_e32 v81, v36, v68
	v_mul_f32_e32 v80, v37, v69
	v_mul_f32_e32 v79, v38, v70
	v_mul_f32_e32 v78, v39, v71
	ds_read_b128 v[36:39], v209 offset:55648
	s_waitcnt lgkmcnt(1)
	v_mul_f32_e32 v93, v56, v32
	v_mul_f32_e32 v77, v40, v32
	v_mul_f32_e32 v92, v57, v33
	v_mul_f32_e32 v76, v41, v33
	v_mul_f32_e32 v91, v58, v34
	v_mul_f32_e32 v75, v42, v34
	v_mul_f32_e32 v90, v59, v35
	v_mul_f32_e32 v74, v43, v35
	ds_read_b128 v[32:35], v209 offset:55680
	v_mul_f32_e32 v95, v54, v70
	v_mul_f32_e32 v94, v55, v71
	s_waitcnt lgkmcnt(1)
	v_mul_f32_e32 v89, v60, v36
	v_mul_f32_e32 v73, v44, v36
	v_mul_f32_e32 v88, v61, v37
	v_mul_f32_e32 v72, v45, v37
	v_mul_f32_e32 v87, v62, v38
	v_mul_f32_e32 v71, v46, v38
	v_mul_f32_e32 v86, v63, v39
	v_mul_f32_e32 v70, v47, v39
	ds_read_b128 v[36:39], v209 offset:55712
	v_mul_f32_e32 v100, v50, v66
	v_mul_f32_e32 v98, v51, v67
	v_mul_f32_e32 v97, v52, v68
	v_mul_f32_e32 v96, v53, v69
	s_waitcnt lgkmcnt(1)
	v_mul_f32_e32 v53, v0, v32
	v_mul_f32_e32 v52, v1, v33
	v_mul_f32_e32 v51, v2, v34
	v_mul_f32_e32 v50, v3, v35
	ds_read_b128 v[0:3], v209 offset:55744
	v_mul_f32_e32 v102, v48, v64
	v_mul_f32_e32 v101, v49, v65
	s_waitcnt lgkmcnt(1)
	v_mul_f32_e32 v49, v4, v36
	v_mul_f32_e32 v48, v5, v37
	v_mul_f32_e32 v47, v6, v38
	v_mul_f32_e32 v46, v7, v39
	ds_read_b128 v[4:7], v209 offset:55776
	s_waitcnt lgkmcnt(1)
	v_mul_f32_e32 v61, v24, v0
	v_mul_f32_e32 v45, v8, v0
	v_subrev_u32_e32 v0, 43, v167
	v_mul_f32_e32 v69, v16, v32
	v_mul_f32_e32 v68, v17, v33
	v_mul_f32_e32 v67, v18, v34
	v_mul_f32_e32 v66, v19, v35
	v_mul_f32_e32 v65, v20, v36
	v_mul_f32_e32 v64, v21, v37
	v_mul_f32_e32 v63, v22, v38
	v_mul_f32_e32 v62, v23, v39
	v_mul_f32_e32 v60, v25, v1
	v_mul_f32_e32 v44, v9, v1
	v_mul_f32_e32 v59, v26, v2
	v_mul_f32_e32 v43, v10, v2
	v_mul_f32_e32 v58, v27, v3
	v_mul_f32_e32 v42, v11, v3
	s_waitcnt lgkmcnt(0)
	v_mul_f32_e32 v57, v28, v4
	v_mul_f32_e32 v41, v12, v4
	v_mul_f32_e32 v56, v29, v5
	v_mul_f32_e32 v40, v13, v5
	v_mul_f32_e32 v55, v30, v6
	v_mul_f32_e32 v39, v14, v6
	v_mul_f32_e32 v54, v31, v7
	v_mul_f32_e32 v38, v15, v7
	v_cmp_lt_u32_e32 vcc, s2, v0
	s_and_saveexec_b64 s[2:3], vcc
	s_xor_b64 s[14:15], exec, s[2:3]
	s_cbranch_execz .LBB0_1713
	v_readfirstlane_b32 s2, v167
	v_add_u32_e32 v0, s34, v206
	v_or_b32_e32 v1, s33, v207
	v_or_b32_e32 v1, v1, v190
	v_mul_lo_u32 v2, v0, s1
	s_cmp_lt_u32 s2, 20
	s_cselect_b32 s3, 0, 32
	s_cmp_lt_u32 s2, 30
	s_cselect_b32 s3, s3, 44
	s_cmp_eq_u32 s2, 42
	s_cbranch_scc1 .Lp1u_misc
; DI void phase_in(const Params& p, int L, char* smem) {
;     ...
;       EPI_BEGINM(acc, 4)
;         const int oc = in_colmap(col);
;         if (oc >= 0 && oc < PJN) {
;           p.proj[(size_t)row * PJ + oc] = f2bf(v);
;           if (oc >= 1952 && oc < 1964) p.small_[row * 16 + (oc - 1952)] = v;
;           if (oc >= 2732) p.small_[row * 16 + 12 + (oc - 2732)] = v;
	v_add_u32_e32 v3, s3, v1
	v_lshl_add_u32 v3, v3, 1, v2
	v_cvt_pk_bf16_f32 v5, v166, v166
	global_store_short v3, v5, s[68:69]
	v_cvt_pk_bf16_f32 v6, v151, v151
	global_store_short v3, v6, s[68:69] offset:64
	v_add_u32_e32 v4, 0x1580, v3
	v_cvt_pk_bf16_f32 v7, v165, v165
	global_store_short v4, v7, s[68:69]
	v_cvt_pk_bf16_f32 v8, v150, v150
	global_store_short v4, v8, s[68:69] offset:64
	v_add_u32_e32 v4, 0x2b00, v3
	v_cvt_pk_bf16_f32 v5, v164, v164
	global_store_short v4, v5, s[68:69]
	v_cvt_pk_bf16_f32 v6, v149, v149
	global_store_short v4, v6, s[68:69] offset:64
	v_add_u32_e32 v4, 0x4080, v3
	v_cvt_pk_bf16_f32 v7, v163, v163
	global_store_short v4, v7, s[68:69]
	v_cvt_pk_bf16_f32 v8, v148, v148
	global_store_short v4, v8, s[68:69] offset:64
	v_add_u32_e32 v4, 0xac00, v3
	v_cvt_pk_bf16_f32 v5, v162, v162
	global_store_short v4, v5, s[68:69]
	v_cvt_pk_bf16_f32 v6, v147, v147
	global_store_short v4, v6, s[68:69] offset:64
	v_add_u32_e32 v4, 0xc180, v3
	v_cvt_pk_bf16_f32 v7, v161, v161
	global_store_short v4, v7, s[68:69]
	v_cvt_pk_bf16_f32 v8, v146, v146
	global_store_short v4, v8, s[68:69] offset:64
	v_add_u32_e32 v4, 0xd700, v3
	v_cvt_pk_bf16_f32 v5, v160, v160
	global_store_short v4, v5, s[68:69]
	v_cvt_pk_bf16_f32 v6, v145, v145
	global_store_short v4, v6, s[68:69] offset:64
	v_add_u32_e32 v4, 0xec80, v3
	v_cvt_pk_bf16_f32 v7, v159, v159
	global_store_short v4, v7, s[68:69]
	v_cvt_pk_bf16_f32 v8, v144, v144
	global_store_short v4, v8, s[68:69] offset:64
	v_add_u32_e32 v4, 0x15800, v3
	v_cvt_pk_bf16_f32 v5, v158, v158
	global_store_short v4, v5, s[68:69]
	v_cvt_pk_bf16_f32 v6, v143, v143
	global_store_short v4, v6, s[68:69] offset:64
	v_add_u32_e32 v4, 0x16d80, v3
	v_cvt_pk_bf16_f32 v7, v157, v157
	global_store_short v4, v7, s[68:69]
	v_cvt_pk_bf16_f32 v8, v142, v142
	global_store_short v4, v8, s[68:69] offset:64
	v_add_u32_e32 v4, 0x18300, v3
	v_cvt_pk_bf16_f32 v5, v156, v156
	global_store_short v4, v5, s[68:69]
	v_cvt_pk_bf16_f32 v6, v141, v141
	global_store_short v4, v6, s[68:69] offset:64
	v_add_u32_e32 v4, 0x19880, v3
	v_cvt_pk_bf16_f32 v7, v155, v155
	global_store_short v4, v7, s[68:69]
	v_cvt_pk_bf16_f32 v8, v140, v140
	global_store_short v4, v8, s[68:69] offset:64
	v_add_u32_e32 v4, 0x20400, v3
	v_cvt_pk_bf16_f32 v5, v154, v154
	global_store_short v4, v5, s[68:69]
	v_cvt_pk_bf16_f32 v6, v139, v139
	global_store_short v4, v6, s[68:69] offset:64
	v_add_u32_e32 v4, 0x21980, v3
	v_cvt_pk_bf16_f32 v7, v153, v153
	global_store_short v4, v7, s[68:69]
	v_cvt_pk_bf16_f32 v8, v138, v138
	global_store_short v4, v8, s[68:69] offset:64
	v_add_u32_e32 v4, 0x22f00, v3
	v_cvt_pk_bf16_f32 v5, v152, v152
	global_store_short v4, v5, s[68:69]
	v_cvt_pk_bf16_f32 v6, v137, v137
	global_store_short v4, v6, s[68:69] offset:64
	v_add_u32_e32 v4, 0x24480, v3
	v_cvt_pk_bf16_f32 v7, v103, v103
	global_store_short v4, v7, s[68:69]
	v_cvt_pk_bf16_f32 v8, v136, v136
	global_store_short v4, v8, s[68:69] offset:64
	v_add_u32_e32 v4, 0x2b000, v3
	v_cvt_pk_bf16_f32 v5, v135, v135
	global_store_short v4, v5, s[68:69]
	v_cvt_pk_bf16_f32 v6, v119, v119
	global_store_short v4, v6, s[68:69] offset:64
	v_add_u32_e32 v4, 0x2c580, v3
	v_cvt_pk_bf16_f32 v7, v134, v134
	global_store_short v4, v7, s[68:69]
	v_cvt_pk_bf16_f32 v8, v118, v118
	global_store_short v4, v8, s[68:69] offset:64
	v_add_u32_e32 v4, 0x2db00, v3
	v_cvt_pk_bf16_f32 v5, v133, v133
	global_store_short v4, v5, s[68:69]
	v_cvt_pk_bf16_f32 v6, v117, v117
	global_store_short v4, v6, s[68:69] offset:64
	v_add_u32_e32 v4, 0x2f080, v3
	v_cvt_pk_bf16_f32 v7, v132, v132
	global_store_short v4, v7, s[68:69]
	v_cvt_pk_bf16_f32 v8, v116, v116
	global_store_short v4, v8, s[68:69] offset:64
	v_add_u32_e32 v4, 0x35c00, v3
	v_cvt_pk_bf16_f32 v5, v131, v131
	global_store_short v4, v5, s[68:69]
	v_cvt_pk_bf16_f32 v6, v115, v115
	global_store_short v4, v6, s[68:69] offset:64
	v_add_u32_e32 v4, 0x37180, v3
	v_cvt_pk_bf16_f32 v7, v130, v130
	global_store_short v4, v7, s[68:69]
	v_cvt_pk_bf16_f32 v8, v114, v114
	global_store_short v4, v8, s[68:69] offset:64
	v_add_u32_e32 v4, 0x38700, v3
	v_cvt_pk_bf16_f32 v5, v129, v129
	global_store_short v4, v5, s[68:69]
	v_cvt_pk_bf16_f32 v6, v113, v113
	global_store_short v4, v6, s[68:69] offset:64
	v_add_u32_e32 v4, 0x39c80, v3
	v_cvt_pk_bf16_f32 v7, v128, v128
	global_store_short v4, v7, s[68:69]
	v_cvt_pk_bf16_f32 v8, v112, v112
	global_store_short v4, v8, s[68:69] offset:64
	v_add_u32_e32 v4, 0x40800, v3
	v_cvt_pk_bf16_f32 v5, v127, v127
	global_store_short v4, v5, s[68:69]
	v_cvt_pk_bf16_f32 v6, v111, v111
	global_store_short v4, v6, s[68:69] offset:64
	v_add_u32_e32 v4, 0x41d80, v3
	v_cvt_pk_bf16_f32 v7, v126, v126
	global_store_short v4, v7, s[68:69]
	v_cvt_pk_bf16_f32 v8, v110, v110
	global_store_short v4, v8, s[68:69] offset:64
	v_add_u32_e32 v4, 0x43300, v3
	v_cvt_pk_bf16_f32 v5, v125, v125
	global_store_short v4, v5, s[68:69]
	v_cvt_pk_bf16_f32 v6, v109, v109
	global_store_short v4, v6, s[68:69] offset:64
	v_add_u32_e32 v4, 0x44880, v3
	v_cvt_pk_bf16_f32 v7, v124, v124
	global_store_short v4, v7, s[68:69]
	v_cvt_pk_bf16_f32 v8, v108, v108
	global_store_short v4, v8, s[68:69] offset:64
	v_add_u32_e32 v4, 0x4b400, v3
	v_cvt_pk_bf16_f32 v5, v123, v123
	global_store_short v4, v5, s[68:69]
	v_cvt_pk_bf16_f32 v6, v107, v107
	global_store_short v4, v6, s[68:69] offset:64
	v_add_u32_e32 v4, 0x4c980, v3
	v_cvt_pk_bf16_f32 v7, v122, v122
	global_store_short v4, v7, s[68:69]
	v_cvt_pk_bf16_f32 v8, v106, v106
	global_store_short v4, v8, s[68:69] offset:64
	v_add_u32_e32 v4, 0x4df00, v3
	v_cvt_pk_bf16_f32 v5, v121, v121
	global_store_short v4, v5, s[68:69]
	v_cvt_pk_bf16_f32 v6, v105, v105
; DI void phase_in(const Params& p, int L, char* smem) {
;     ...
;       EPI_BEGINM(acc, 4)
;         const int oc = in_colmap(col);
;         if (oc >= 0 && oc < PJN) {
;           p.proj[(size_t)row * PJ + oc] = f2bf(v);
;           if (oc >= 1952 && oc < 1964) p.small_[row * 16 + (oc - 1952)] = v;
;           if (oc >= 2732) p.small_[row * 16 + 12 + (oc - 2732)] = v;
;           if (oc >= 1568 && oc < 1632) p.kcmp[(size_t)row * 64 + (oc - 1568)] = f2bf(v);
;           if (oc >= 1632 && oc < 1696) p.vcmp[(size_t)row * 64 + (oc - 1632)] = f2bf(v);
	global_store_short v4, v6, s[68:69] offset:64
	v_add_u32_e32 v4, 0x4f480, v3
	v_cvt_pk_bf16_f32 v7, v120, v120
	global_store_short v4, v7, s[68:69]
	v_cvt_pk_bf16_f32 v8, v104, v104
	global_store_short v4, v8, s[68:69] offset:64
	v_add_u32_e32 v4, 0x56000, v3
	v_cvt_pk_bf16_f32 v5, v102, v102
	global_store_short v4, v5, s[68:69]
	v_cvt_pk_bf16_f32 v6, v85, v85
	global_store_short v4, v6, s[68:69] offset:64
	v_add_u32_e32 v4, 0x57580, v3
	v_cvt_pk_bf16_f32 v7, v101, v101
	global_store_short v4, v7, s[68:69]
	v_cvt_pk_bf16_f32 v8, v84, v84
	global_store_short v4, v8, s[68:69] offset:64
	v_add_u32_e32 v4, 0x58b00, v3
	v_cvt_pk_bf16_f32 v5, v100, v100
	global_store_short v4, v5, s[68:69]
	v_cvt_pk_bf16_f32 v6, v83, v83
	global_store_short v4, v6, s[68:69] offset:64
	v_add_u32_e32 v4, 0x5a080, v3
	v_cvt_pk_bf16_f32 v7, v98, v98
	global_store_short v4, v7, s[68:69]
	v_cvt_pk_bf16_f32 v8, v82, v82
	global_store_short v4, v8, s[68:69] offset:64
	v_add_u32_e32 v4, 0x60c00, v3
	v_cvt_pk_bf16_f32 v5, v97, v97
	global_store_short v4, v5, s[68:69]
	v_cvt_pk_bf16_f32 v6, v81, v81
	global_store_short v4, v6, s[68:69] offset:64
	v_add_u32_e32 v4, 0x62180, v3
	v_cvt_pk_bf16_f32 v7, v96, v96
	global_store_short v4, v7, s[68:69]
	v_cvt_pk_bf16_f32 v8, v80, v80
	global_store_short v4, v8, s[68:69] offset:64
	v_add_u32_e32 v4, 0x63700, v3
	v_cvt_pk_bf16_f32 v5, v95, v95
	global_store_short v4, v5, s[68:69]
	v_cvt_pk_bf16_f32 v6, v79, v79
	global_store_short v4, v6, s[68:69] offset:64
	v_add_u32_e32 v4, 0x64c80, v3
	v_cvt_pk_bf16_f32 v7, v94, v94
	global_store_short v4, v7, s[68:69]
	v_cvt_pk_bf16_f32 v8, v78, v78
	global_store_short v4, v8, s[68:69] offset:64
	v_add_u32_e32 v4, 0x6b800, v3
	v_cvt_pk_bf16_f32 v5, v93, v93
	global_store_short v4, v5, s[68:69]
	v_cvt_pk_bf16_f32 v6, v77, v77
	global_store_short v4, v6, s[68:69] offset:64
	v_add_u32_e32 v4, 0x6cd80, v3
	v_cvt_pk_bf16_f32 v7, v92, v92
	global_store_short v4, v7, s[68:69]
	v_cvt_pk_bf16_f32 v8, v76, v76
	global_store_short v4, v8, s[68:69] offset:64
	v_add_u32_e32 v4, 0x6e300, v3
	v_cvt_pk_bf16_f32 v5, v91, v91
	global_store_short v4, v5, s[68:69]
	v_cvt_pk_bf16_f32 v6, v75, v75
	global_store_short v4, v6, s[68:69] offset:64
	v_add_u32_e32 v4, 0x6f880, v3
	v_cvt_pk_bf16_f32 v7, v90, v90
	global_store_short v4, v7, s[68:69]
	v_cvt_pk_bf16_f32 v8, v74, v74
	global_store_short v4, v8, s[68:69] offset:64
	v_add_u32_e32 v4, 0x76400, v3
	v_cvt_pk_bf16_f32 v5, v89, v89
	global_store_short v4, v5, s[68:69]
	v_cvt_pk_bf16_f32 v6, v73, v73
	global_store_short v4, v6, s[68:69] offset:64
	v_add_u32_e32 v4, 0x77980, v3
	v_cvt_pk_bf16_f32 v7, v88, v88
	global_store_short v4, v7, s[68:69]
	v_cvt_pk_bf16_f32 v8, v72, v72
	global_store_short v4, v8, s[68:69] offset:64
	v_add_u32_e32 v4, 0x78f00, v3
	v_cvt_pk_bf16_f32 v5, v87, v87
	global_store_short v4, v5, s[68:69]
	v_cvt_pk_bf16_f32 v6, v71, v71
	global_store_short v4, v6, s[68:69] offset:64
	v_add_u32_e32 v4, 0x7a480, v3
	v_cvt_pk_bf16_f32 v7, v86, v86
	global_store_short v4, v7, s[68:69]
	v_cvt_pk_bf16_f32 v8, v70, v70
	global_store_short v4, v8, s[68:69] offset:64
	v_add_u32_e32 v4, 0x81000, v3
	v_cvt_pk_bf16_f32 v5, v69, v69
	global_store_short v4, v5, s[68:69]
	v_cvt_pk_bf16_f32 v6, v53, v53
	global_store_short v4, v6, s[68:69] offset:64
	v_add_u32_e32 v4, 0x82580, v3
	v_cvt_pk_bf16_f32 v7, v68, v68
	global_store_short v4, v7, s[68:69]
	v_cvt_pk_bf16_f32 v8, v52, v52
	global_store_short v4, v8, s[68:69] offset:64
	v_add_u32_e32 v4, 0x83b00, v3
	v_cvt_pk_bf16_f32 v5, v67, v67
	global_store_short v4, v5, s[68:69]
	v_cvt_pk_bf16_f32 v6, v51, v51
	global_store_short v4, v6, s[68:69] offset:64
	v_add_u32_e32 v4, 0x85080, v3
	v_cvt_pk_bf16_f32 v7, v66, v66
	global_store_short v4, v7, s[68:69]
	v_cvt_pk_bf16_f32 v8, v50, v50
	global_store_short v4, v8, s[68:69] offset:64
	v_add_u32_e32 v4, 0x8bc00, v3
	v_cvt_pk_bf16_f32 v5, v65, v65
	global_store_short v4, v5, s[68:69]
	v_cvt_pk_bf16_f32 v6, v49, v49
	global_store_short v4, v6, s[68:69] offset:64
	v_add_u32_e32 v4, 0x8d180, v3
	v_cvt_pk_bf16_f32 v7, v64, v64
	global_store_short v4, v7, s[68:69]
	v_cvt_pk_bf16_f32 v8, v48, v48
	global_store_short v4, v8, s[68:69] offset:64
	v_add_u32_e32 v4, 0x8e700, v3
	v_cvt_pk_bf16_f32 v5, v63, v63
	global_store_short v4, v5, s[68:69]
	v_cvt_pk_bf16_f32 v6, v47, v47
	global_store_short v4, v6, s[68:69] offset:64
	v_add_u32_e32 v4, 0x8fc80, v3
	v_cvt_pk_bf16_f32 v7, v62, v62
	global_store_short v4, v7, s[68:69]
	v_cvt_pk_bf16_f32 v8, v46, v46
	global_store_short v4, v8, s[68:69] offset:64
	v_add_u32_e32 v4, 0x96800, v3
	v_cvt_pk_bf16_f32 v5, v61, v61
	global_store_short v4, v5, s[68:69]
	v_cvt_pk_bf16_f32 v6, v45, v45
	global_store_short v4, v6, s[68:69] offset:64
	v_add_u32_e32 v4, 0x97d80, v3
	v_cvt_pk_bf16_f32 v7, v60, v60
	global_store_short v4, v7, s[68:69]
	v_cvt_pk_bf16_f32 v8, v44, v44
	global_store_short v4, v8, s[68:69] offset:64
	v_add_u32_e32 v4, 0x99300, v3
	v_cvt_pk_bf16_f32 v5, v59, v59
	global_store_short v4, v5, s[68:69]
	v_cvt_pk_bf16_f32 v6, v43, v43
	global_store_short v4, v6, s[68:69] offset:64
	v_add_u32_e32 v4, 0x9a880, v3
	v_cvt_pk_bf16_f32 v7, v58, v58
	global_store_short v4, v7, s[68:69]
	v_cvt_pk_bf16_f32 v8, v42, v42
	global_store_short v4, v8, s[68:69] offset:64
	v_add_u32_e32 v4, 0xa1400, v3
	v_cvt_pk_bf16_f32 v5, v57, v57
	global_store_short v4, v5, s[68:69]
	v_cvt_pk_bf16_f32 v6, v41, v41
	global_store_short v4, v6, s[68:69] offset:64
	v_add_u32_e32 v4, 0xa2980, v3
	v_cvt_pk_bf16_f32 v7, v56, v56
	global_store_short v4, v7, s[68:69]
	v_cvt_pk_bf16_f32 v8, v40, v40
	global_store_short v4, v8, s[68:69] offset:64
	v_add_u32_e32 v4, 0xa3f00, v3
	v_cvt_pk_bf16_f32 v5, v55, v55
	global_store_short v4, v5, s[68:69]
	v_cvt_pk_bf16_f32 v6, v39, v39
	global_store_short v4, v6, s[68:69] offset:64
	v_add_u32_e32 v4, 0xa5480, v3
	v_cvt_pk_bf16_f32 v7, v54, v54
	global_store_short v4, v7, s[68:69]
	v_cvt_pk_bf16_f32 v8, v38, v38
	global_store_short v4, v8, s[68:69] offset:64
	s_cmp_eq_u32 s2, 24
	s_cbranch_scc1 .Lp1u_kc
	s_cmp_eq_u32 s2, 25
	s_cbranch_scc0 .Lp1u_end
	s_mov_b64 s[4:5], s[46:47]
	s_movk_i32 s3, 0x640
	s_branch .Lp1u_kv
; DI void phase_in(const Params& p, int L, char* smem) {
;     ...
;           if (oc >= 1568 && oc < 1632) p.kcmp[(size_t)row * 64 + (oc - 1568)] = f2bf(v);
;           if (oc >= 1632 && oc < 1696) p.vcmp[(size_t)row * 64 + (oc - 1632)] = f2bf(v);
.Lp1u_kc:
	s_mov_b64 s[4:5], s[44:45]
	s_movk_i32 s3, 0x600
.Lp1u_kv:
	v_subrev_u32_e32 v3, s3, v1
	v_lshlrev_b32_e32 v3, 1, v3
	v_lshl_add_u32 v3, v0, 7, v3
	v_cvt_pk_bf16_f32 v5, v166, v166
	global_store_short v3, v5, s[4:5]
	v_cvt_pk_bf16_f32 v6, v151, v151
	global_store_short v3, v6, s[4:5] offset:64
	v_add_u32_e32 v4, 0x80, v3
	v_cvt_pk_bf16_f32 v7, v165, v165
	global_store_short v4, v7, s[4:5]
	v_cvt_pk_bf16_f32 v8, v150, v150
	global_store_short v4, v8, s[4:5] offset:64
	v_add_u32_e32 v4, 0x100, v3
	v_cvt_pk_bf16_f32 v5, v164, v164
	global_store_short v4, v5, s[4:5]
	v_cvt_pk_bf16_f32 v6, v149, v149
	global_store_short v4, v6, s[4:5] offset:64
	v_add_u32_e32 v4, 0x180, v3
	v_cvt_pk_bf16_f32 v7, v163, v163
	global_store_short v4, v7, s[4:5]
	v_cvt_pk_bf16_f32 v8, v148, v148
	global_store_short v4, v8, s[4:5] offset:64
	v_add_u32_e32 v4, 0x400, v3
	v_cvt_pk_bf16_f32 v5, v162, v162
	global_store_short v4, v5, s[4:5]
	v_cvt_pk_bf16_f32 v6, v147, v147
	global_store_short v4, v6, s[4:5] offset:64
	v_add_u32_e32 v4, 0x480, v3
	v_cvt_pk_bf16_f32 v7, v161, v161
	global_store_short v4, v7, s[4:5]
	v_cvt_pk_bf16_f32 v8, v146, v146
	global_store_short v4, v8, s[4:5] offset:64
	v_add_u32_e32 v4, 0x500, v3
	v_cvt_pk_bf16_f32 v5, v160, v160
	global_store_short v4, v5, s[4:5]
	v_cvt_pk_bf16_f32 v6, v145, v145
	global_store_short v4, v6, s[4:5] offset:64
	v_add_u32_e32 v4, 0x580, v3
	v_cvt_pk_bf16_f32 v7, v159, v159
	global_store_short v4, v7, s[4:5]
	v_cvt_pk_bf16_f32 v8, v144, v144
	global_store_short v4, v8, s[4:5] offset:64
	v_add_u32_e32 v4, 0x800, v3
	v_cvt_pk_bf16_f32 v5, v158, v158
	global_store_short v4, v5, s[4:5]
	v_cvt_pk_bf16_f32 v6, v143, v143
	global_store_short v4, v6, s[4:5] offset:64
	v_add_u32_e32 v4, 0x880, v3
	v_cvt_pk_bf16_f32 v7, v157, v157
	global_store_short v4, v7, s[4:5]
	v_cvt_pk_bf16_f32 v8, v142, v142
	global_store_short v4, v8, s[4:5] offset:64
	v_add_u32_e32 v4, 0x900, v3
	v_cvt_pk_bf16_f32 v5, v156, v156
	global_store_short v4, v5, s[4:5]
	v_cvt_pk_bf16_f32 v6, v141, v141
	global_store_short v4, v6, s[4:5] offset:64
	v_add_u32_e32 v4, 0x980, v3
	v_cvt_pk_bf16_f32 v7, v155, v155
	global_store_short v4, v7, s[4:5]
	v_cvt_pk_bf16_f32 v8, v140, v140
	global_store_short v4, v8, s[4:5] offset:64
	v_add_u32_e32 v4, 0xc00, v3
	v_cvt_pk_bf16_f32 v5, v154, v154
	global_store_short v4, v5, s[4:5]
	v_cvt_pk_bf16_f32 v6, v139, v139
	global_store_short v4, v6, s[4:5] offset:64
	v_add_u32_e32 v4, 0xc80, v3
	v_cvt_pk_bf16_f32 v7, v153, v153
	global_store_short v4, v7, s[4:5]
	v_cvt_pk_bf16_f32 v8, v138, v138
	global_store_short v4, v8, s[4:5] offset:64
	v_add_u32_e32 v4, 0xd00, v3
	v_cvt_pk_bf16_f32 v5, v152, v152
	global_store_short v4, v5, s[4:5]
	v_cvt_pk_bf16_f32 v6, v137, v137
	global_store_short v4, v6, s[4:5] offset:64
	v_add_u32_e32 v4, 0xd80, v3
	v_cvt_pk_bf16_f32 v7, v103, v103
	global_store_short v4, v7, s[4:5]
	v_cvt_pk_bf16_f32 v8, v136, v136
	global_store_short v4, v8, s[4:5] offset:64
	v_add_u32_e32 v4, 0x1000, v3
	v_cvt_pk_bf16_f32 v5, v135, v135
	global_store_short v4, v5, s[4:5]
	v_cvt_pk_bf16_f32 v6, v119, v119
	global_store_short v4, v6, s[4:5] offset:64
	v_add_u32_e32 v4, 0x1080, v3
	v_cvt_pk_bf16_f32 v7, v134, v134
	global_store_short v4, v7, s[4:5]
	v_cvt_pk_bf16_f32 v8, v118, v118
	global_store_short v4, v8, s[4:5] offset:64
	v_add_u32_e32 v4, 0x1100, v3
	v_cvt_pk_bf16_f32 v5, v133, v133
	global_store_short v4, v5, s[4:5]
	v_cvt_pk_bf16_f32 v6, v117, v117
	global_store_short v4, v6, s[4:5] offset:64
	v_add_u32_e32 v4, 0x1180, v3
	v_cvt_pk_bf16_f32 v7, v132, v132
	global_store_short v4, v7, s[4:5]
	v_cvt_pk_bf16_f32 v8, v116, v116
	global_store_short v4, v8, s[4:5] offset:64
	v_add_u32_e32 v4, 0x1400, v3
	v_cvt_pk_bf16_f32 v5, v131, v131
	global_store_short v4, v5, s[4:5]
	v_cvt_pk_bf16_f32 v6, v115, v115
	global_store_short v4, v6, s[4:5] offset:64
	v_add_u32_e32 v4, 0x1480, v3
	v_cvt_pk_bf16_f32 v7, v130, v130
	global_store_short v4, v7, s[4:5]
	v_cvt_pk_bf16_f32 v8, v114, v114
	global_store_short v4, v8, s[4:5] offset:64
	v_add_u32_e32 v4, 0x1500, v3
	v_cvt_pk_bf16_f32 v5, v129, v129
	global_store_short v4, v5, s[4:5]
	v_cvt_pk_bf16_f32 v6, v113, v113
	global_store_short v4, v6, s[4:5] offset:64
	v_add_u32_e32 v4, 0x1580, v3
	v_cvt_pk_bf16_f32 v7, v128, v128
	global_store_short v4, v7, s[4:5]
	v_cvt_pk_bf16_f32 v8, v112, v112
	global_store_short v4, v8, s[4:5] offset:64
	v_add_u32_e32 v4, 0x1800, v3
	v_cvt_pk_bf16_f32 v5, v127, v127
	global_store_short v4, v5, s[4:5]
	v_cvt_pk_bf16_f32 v6, v111, v111
	global_store_short v4, v6, s[4:5] offset:64
	v_add_u32_e32 v4, 0x1880, v3
	v_cvt_pk_bf16_f32 v7, v126, v126
	global_store_short v4, v7, s[4:5]
	v_cvt_pk_bf16_f32 v8, v110, v110
	global_store_short v4, v8, s[4:5] offset:64
	v_add_u32_e32 v4, 0x1900, v3
	v_cvt_pk_bf16_f32 v5, v125, v125
	global_store_short v4, v5, s[4:5]
	v_cvt_pk_bf16_f32 v6, v109, v109
	global_store_short v4, v6, s[4:5] offset:64
	v_add_u32_e32 v4, 0x1980, v3
	v_cvt_pk_bf16_f32 v7, v124, v124
	global_store_short v4, v7, s[4:5]
	v_cvt_pk_bf16_f32 v8, v108, v108
	global_store_short v4, v8, s[4:5] offset:64
	v_add_u32_e32 v4, 0x1c00, v3
	v_cvt_pk_bf16_f32 v5, v123, v123
	global_store_short v4, v5, s[4:5]
	v_cvt_pk_bf16_f32 v6, v107, v107
	global_store_short v4, v6, s[4:5] offset:64
	v_add_u32_e32 v4, 0x1c80, v3
	v_cvt_pk_bf16_f32 v7, v122, v122
	global_store_short v4, v7, s[4:5]
	v_cvt_pk_bf16_f32 v8, v106, v106
	global_store_short v4, v8, s[4:5] offset:64
	v_add_u32_e32 v4, 0x1d00, v3
	v_cvt_pk_bf16_f32 v5, v121, v121
	global_store_short v4, v5, s[4:5]
	v_cvt_pk_bf16_f32 v6, v105, v105
	global_store_short v4, v6, s[4:5] offset:64
; DI void phase_in(const Params& p, int L, char* smem) {
;     ...
;           if (oc >= 1568 && oc < 1632) p.kcmp[(size_t)row * 64 + (oc - 1568)] = f2bf(v);
;           if (oc >= 1632 && oc < 1696) p.vcmp[(size_t)row * 64 + (oc - 1632)] = f2bf(v);
	v_add_u32_e32 v4, 0x1d80, v3
	v_cvt_pk_bf16_f32 v7, v120, v120
	global_store_short v4, v7, s[4:5]
	v_cvt_pk_bf16_f32 v8, v104, v104
	global_store_short v4, v8, s[4:5] offset:64
	v_add_u32_e32 v4, 0x2000, v3
	v_cvt_pk_bf16_f32 v5, v102, v102
	global_store_short v4, v5, s[4:5]
	v_cvt_pk_bf16_f32 v6, v85, v85
	global_store_short v4, v6, s[4:5] offset:64
	v_add_u32_e32 v4, 0x2080, v3
	v_cvt_pk_bf16_f32 v7, v101, v101
	global_store_short v4, v7, s[4:5]
	v_cvt_pk_bf16_f32 v8, v84, v84
	global_store_short v4, v8, s[4:5] offset:64
	v_add_u32_e32 v4, 0x2100, v3
	v_cvt_pk_bf16_f32 v5, v100, v100
	global_store_short v4, v5, s[4:5]
	v_cvt_pk_bf16_f32 v6, v83, v83
	global_store_short v4, v6, s[4:5] offset:64
	v_add_u32_e32 v4, 0x2180, v3
	v_cvt_pk_bf16_f32 v7, v98, v98
	global_store_short v4, v7, s[4:5]
	v_cvt_pk_bf16_f32 v8, v82, v82
	global_store_short v4, v8, s[4:5] offset:64
	v_add_u32_e32 v4, 0x2400, v3
	v_cvt_pk_bf16_f32 v5, v97, v97
	global_store_short v4, v5, s[4:5]
	v_cvt_pk_bf16_f32 v6, v81, v81
	global_store_short v4, v6, s[4:5] offset:64
	v_add_u32_e32 v4, 0x2480, v3
	v_cvt_pk_bf16_f32 v7, v96, v96
	global_store_short v4, v7, s[4:5]
	v_cvt_pk_bf16_f32 v8, v80, v80
	global_store_short v4, v8, s[4:5] offset:64
	v_add_u32_e32 v4, 0x2500, v3
	v_cvt_pk_bf16_f32 v5, v95, v95
	global_store_short v4, v5, s[4:5]
	v_cvt_pk_bf16_f32 v6, v79, v79
	global_store_short v4, v6, s[4:5] offset:64
	v_add_u32_e32 v4, 0x2580, v3
	v_cvt_pk_bf16_f32 v7, v94, v94
	global_store_short v4, v7, s[4:5]
	v_cvt_pk_bf16_f32 v8, v78, v78
	global_store_short v4, v8, s[4:5] offset:64
	v_add_u32_e32 v4, 0x2800, v3
	v_cvt_pk_bf16_f32 v5, v93, v93
	global_store_short v4, v5, s[4:5]
	v_cvt_pk_bf16_f32 v6, v77, v77
	global_store_short v4, v6, s[4:5] offset:64
	v_add_u32_e32 v4, 0x2880, v3
	v_cvt_pk_bf16_f32 v7, v92, v92
	global_store_short v4, v7, s[4:5]
	v_cvt_pk_bf16_f32 v8, v76, v76
	global_store_short v4, v8, s[4:5] offset:64
	v_add_u32_e32 v4, 0x2900, v3
	v_cvt_pk_bf16_f32 v5, v91, v91
	global_store_short v4, v5, s[4:5]
	v_cvt_pk_bf16_f32 v6, v75, v75
	global_store_short v4, v6, s[4:5] offset:64
	v_add_u32_e32 v4, 0x2980, v3
	v_cvt_pk_bf16_f32 v7, v90, v90
	global_store_short v4, v7, s[4:5]
	v_cvt_pk_bf16_f32 v8, v74, v74
	global_store_short v4, v8, s[4:5] offset:64
	v_add_u32_e32 v4, 0x2c00, v3
	v_cvt_pk_bf16_f32 v5, v89, v89
	global_store_short v4, v5, s[4:5]
	v_cvt_pk_bf16_f32 v6, v73, v73
	global_store_short v4, v6, s[4:5] offset:64
	v_add_u32_e32 v4, 0x2c80, v3
	v_cvt_pk_bf16_f32 v7, v88, v88
	global_store_short v4, v7, s[4:5]
	v_cvt_pk_bf16_f32 v8, v72, v72
	global_store_short v4, v8, s[4:5] offset:64
	v_add_u32_e32 v4, 0x2d00, v3
	v_cvt_pk_bf16_f32 v5, v87, v87
	global_store_short v4, v5, s[4:5]
	v_cvt_pk_bf16_f32 v6, v71, v71
	global_store_short v4, v6, s[4:5] offset:64
	v_add_u32_e32 v4, 0x2d80, v3
	v_cvt_pk_bf16_f32 v7, v86, v86
	global_store_short v4, v7, s[4:5]
	v_cvt_pk_bf16_f32 v8, v70, v70
	global_store_short v4, v8, s[4:5] offset:64
	v_add_u32_e32 v4, 0x3000, v3
	v_cvt_pk_bf16_f32 v5, v69, v69
	global_store_short v4, v5, s[4:5]
	v_cvt_pk_bf16_f32 v6, v53, v53
	global_store_short v4, v6, s[4:5] offset:64
	v_add_u32_e32 v4, 0x3080, v3
	v_cvt_pk_bf16_f32 v7, v68, v68
	global_store_short v4, v7, s[4:5]
	v_cvt_pk_bf16_f32 v8, v52, v52
	global_store_short v4, v8, s[4:5] offset:64
	v_add_u32_e32 v4, 0x3100, v3
	v_cvt_pk_bf16_f32 v5, v67, v67
	global_store_short v4, v5, s[4:5]
	v_cvt_pk_bf16_f32 v6, v51, v51
	global_store_short v4, v6, s[4:5] offset:64
	v_add_u32_e32 v4, 0x3180, v3
	v_cvt_pk_bf16_f32 v7, v66, v66
	global_store_short v4, v7, s[4:5]
	v_cvt_pk_bf16_f32 v8, v50, v50
	global_store_short v4, v8, s[4:5] offset:64
	v_add_u32_e32 v4, 0x3400, v3
	v_cvt_pk_bf16_f32 v5, v65, v65
	global_store_short v4, v5, s[4:5]
	v_cvt_pk_bf16_f32 v6, v49, v49
	global_store_short v4, v6, s[4:5] offset:64
	v_add_u32_e32 v4, 0x3480, v3
	v_cvt_pk_bf16_f32 v7, v64, v64
	global_store_short v4, v7, s[4:5]
	v_cvt_pk_bf16_f32 v8, v48, v48
	global_store_short v4, v8, s[4:5] offset:64
	v_add_u32_e32 v4, 0x3500, v3
	v_cvt_pk_bf16_f32 v5, v63, v63
	global_store_short v4, v5, s[4:5]
	v_cvt_pk_bf16_f32 v6, v47, v47
	global_store_short v4, v6, s[4:5] offset:64
	v_add_u32_e32 v4, 0x3580, v3
	v_cvt_pk_bf16_f32 v7, v62, v62
	global_store_short v4, v7, s[4:5]
	v_cvt_pk_bf16_f32 v8, v46, v46
	global_store_short v4, v8, s[4:5] offset:64
	v_add_u32_e32 v4, 0x3800, v3
	v_cvt_pk_bf16_f32 v5, v61, v61
	global_store_short v4, v5, s[4:5]
	v_cvt_pk_bf16_f32 v6, v45, v45
	global_store_short v4, v6, s[4:5] offset:64
	v_add_u32_e32 v4, 0x3880, v3
	v_cvt_pk_bf16_f32 v7, v60, v60
	global_store_short v4, v7, s[4:5]
	v_cvt_pk_bf16_f32 v8, v44, v44
	global_store_short v4, v8, s[4:5] offset:64
	v_add_u32_e32 v4, 0x3900, v3
	v_cvt_pk_bf16_f32 v5, v59, v59
	global_store_short v4, v5, s[4:5]
	v_cvt_pk_bf16_f32 v6, v43, v43
	global_store_short v4, v6, s[4:5] offset:64
	v_add_u32_e32 v4, 0x3980, v3
	v_cvt_pk_bf16_f32 v7, v58, v58
	global_store_short v4, v7, s[4:5]
	v_cvt_pk_bf16_f32 v8, v42, v42
	global_store_short v4, v8, s[4:5] offset:64
	v_add_u32_e32 v4, 0x3c00, v3
	v_cvt_pk_bf16_f32 v5, v57, v57
	global_store_short v4, v5, s[4:5]
	v_cvt_pk_bf16_f32 v6, v41, v41
	global_store_short v4, v6, s[4:5] offset:64
	v_add_u32_e32 v4, 0x3c80, v3
	v_cvt_pk_bf16_f32 v7, v56, v56
	global_store_short v4, v7, s[4:5]
	v_cvt_pk_bf16_f32 v8, v40, v40
	global_store_short v4, v8, s[4:5] offset:64
	v_add_u32_e32 v4, 0x3d00, v3
	v_cvt_pk_bf16_f32 v5, v55, v55
	global_store_short v4, v5, s[4:5]
	v_cvt_pk_bf16_f32 v6, v39, v39
	global_store_short v4, v6, s[4:5] offset:64
	v_add_u32_e32 v4, 0x3d80, v3
	v_cvt_pk_bf16_f32 v7, v54, v54
	global_store_short v4, v7, s[4:5]
	v_cvt_pk_bf16_f32 v8, v38, v38
	global_store_short v4, v8, s[4:5] offset:64
	s_branch .Lp1u_end
; DI void phase_in(const Params& p, int L, char* smem) {
;     ...
;       EPI_BEGINM(acc, 4)
;         const int oc = in_colmap(col);
;         if (oc >= 0 && oc < PJN) {
;           p.proj[(size_t)row * PJ + oc] = f2bf(v);
;           if (oc >= 1952 && oc < 1964) p.small_[row * 16 + (oc - 1952)] = v;
;           if (oc >= 2732) p.small_[row * 16 + 12 + (oc - 2732)] = v;
.Lp1u_misc:
	v_add_u32_e32 v3, 0x500, v190
	v_lshl_add_u32 v3, v3, 1, v2
	v_cvt_pk_bf16_f32 v5, v166, v166
	global_store_short v3, v5, s[68:69]
	v_add_u32_e32 v4, 0x1580, v3
	v_cvt_pk_bf16_f32 v6, v165, v165
	global_store_short v4, v6, s[68:69]
	v_add_u32_e32 v4, 0x2b00, v3
	v_cvt_pk_bf16_f32 v7, v164, v164
	global_store_short v4, v7, s[68:69]
	v_add_u32_e32 v4, 0x4080, v3
	v_cvt_pk_bf16_f32 v8, v163, v163
	global_store_short v4, v8, s[68:69]
	v_add_u32_e32 v4, 0xac00, v3
	v_cvt_pk_bf16_f32 v5, v162, v162
	global_store_short v4, v5, s[68:69]
	v_add_u32_e32 v4, 0xc180, v3
	v_cvt_pk_bf16_f32 v6, v161, v161
	global_store_short v4, v6, s[68:69]
	v_add_u32_e32 v4, 0xd700, v3
	v_cvt_pk_bf16_f32 v7, v160, v160
	global_store_short v4, v7, s[68:69]
	v_add_u32_e32 v4, 0xec80, v3
	v_cvt_pk_bf16_f32 v8, v159, v159
	global_store_short v4, v8, s[68:69]
	v_add_u32_e32 v4, 0x15800, v3
	v_cvt_pk_bf16_f32 v5, v158, v158
	global_store_short v4, v5, s[68:69]
	v_add_u32_e32 v4, 0x16d80, v3
	v_cvt_pk_bf16_f32 v6, v157, v157
	global_store_short v4, v6, s[68:69]
	v_add_u32_e32 v4, 0x18300, v3
	v_cvt_pk_bf16_f32 v7, v156, v156
	global_store_short v4, v7, s[68:69]
	v_add_u32_e32 v4, 0x19880, v3
	v_cvt_pk_bf16_f32 v8, v155, v155
	global_store_short v4, v8, s[68:69]
	v_add_u32_e32 v4, 0x20400, v3
	v_cvt_pk_bf16_f32 v5, v154, v154
	global_store_short v4, v5, s[68:69]
	v_add_u32_e32 v4, 0x21980, v3
	v_cvt_pk_bf16_f32 v6, v153, v153
	global_store_short v4, v6, s[68:69]
	v_add_u32_e32 v4, 0x22f00, v3
	v_cvt_pk_bf16_f32 v7, v152, v152
	global_store_short v4, v7, s[68:69]
	v_add_u32_e32 v4, 0x24480, v3
	v_cvt_pk_bf16_f32 v8, v103, v103
	global_store_short v4, v8, s[68:69]
	v_add_u32_e32 v4, 0x2b000, v3
	v_cvt_pk_bf16_f32 v5, v135, v135
	global_store_short v4, v5, s[68:69]
	v_add_u32_e32 v4, 0x2c580, v3
	v_cvt_pk_bf16_f32 v6, v134, v134
	global_store_short v4, v6, s[68:69]
	v_add_u32_e32 v4, 0x2db00, v3
	v_cvt_pk_bf16_f32 v7, v133, v133
	global_store_short v4, v7, s[68:69]
	v_add_u32_e32 v4, 0x2f080, v3
	v_cvt_pk_bf16_f32 v8, v132, v132
	global_store_short v4, v8, s[68:69]
	v_add_u32_e32 v4, 0x35c00, v3
	v_cvt_pk_bf16_f32 v5, v131, v131
	global_store_short v4, v5, s[68:69]
	v_add_u32_e32 v4, 0x37180, v3
	v_cvt_pk_bf16_f32 v6, v130, v130
	global_store_short v4, v6, s[68:69]
	v_add_u32_e32 v4, 0x38700, v3
	v_cvt_pk_bf16_f32 v7, v129, v129
	global_store_short v4, v7, s[68:69]
	v_add_u32_e32 v4, 0x39c80, v3
	v_cvt_pk_bf16_f32 v8, v128, v128
	global_store_short v4, v8, s[68:69]
	v_add_u32_e32 v4, 0x40800, v3
	v_cvt_pk_bf16_f32 v5, v127, v127
	global_store_short v4, v5, s[68:69]
	v_add_u32_e32 v4, 0x41d80, v3
	v_cvt_pk_bf16_f32 v6, v126, v126
	global_store_short v4, v6, s[68:69]
	v_add_u32_e32 v4, 0x43300, v3
	v_cvt_pk_bf16_f32 v7, v125, v125
	global_store_short v4, v7, s[68:69]
	v_add_u32_e32 v4, 0x44880, v3
	v_cvt_pk_bf16_f32 v8, v124, v124
	global_store_short v4, v8, s[68:69]
	v_add_u32_e32 v4, 0x4b400, v3
	v_cvt_pk_bf16_f32 v5, v123, v123
	global_store_short v4, v5, s[68:69]
	v_add_u32_e32 v4, 0x4c980, v3
	v_cvt_pk_bf16_f32 v6, v122, v122
	global_store_short v4, v6, s[68:69]
	v_add_u32_e32 v4, 0x4df00, v3
	v_cvt_pk_bf16_f32 v7, v121, v121
	global_store_short v4, v7, s[68:69]
	v_add_u32_e32 v4, 0x4f480, v3
	v_cvt_pk_bf16_f32 v8, v120, v120
	global_store_short v4, v8, s[68:69]
	v_add_u32_e32 v4, 0x56000, v3
	v_cvt_pk_bf16_f32 v5, v102, v102
	global_store_short v4, v5, s[68:69]
	v_add_u32_e32 v4, 0x57580, v3
	v_cvt_pk_bf16_f32 v6, v101, v101
	global_store_short v4, v6, s[68:69]
	v_add_u32_e32 v4, 0x58b00, v3
	v_cvt_pk_bf16_f32 v7, v100, v100
	global_store_short v4, v7, s[68:69]
	v_add_u32_e32 v4, 0x5a080, v3
	v_cvt_pk_bf16_f32 v8, v98, v98
	global_store_short v4, v8, s[68:69]
	v_add_u32_e32 v4, 0x60c00, v3
	v_cvt_pk_bf16_f32 v5, v97, v97
	global_store_short v4, v5, s[68:69]
	v_add_u32_e32 v4, 0x62180, v3
	v_cvt_pk_bf16_f32 v6, v96, v96
	global_store_short v4, v6, s[68:69]
	v_add_u32_e32 v4, 0x63700, v3
	v_cvt_pk_bf16_f32 v7, v95, v95
	global_store_short v4, v7, s[68:69]
	v_add_u32_e32 v4, 0x64c80, v3
	v_cvt_pk_bf16_f32 v8, v94, v94
	global_store_short v4, v8, s[68:69]
	v_add_u32_e32 v4, 0x6b800, v3
	v_cvt_pk_bf16_f32 v5, v93, v93
	global_store_short v4, v5, s[68:69]
	v_add_u32_e32 v4, 0x6cd80, v3
	v_cvt_pk_bf16_f32 v6, v92, v92
	global_store_short v4, v6, s[68:69]
	v_add_u32_e32 v4, 0x6e300, v3
	v_cvt_pk_bf16_f32 v7, v91, v91
	global_store_short v4, v7, s[68:69]
	v_add_u32_e32 v4, 0x6f880, v3
	v_cvt_pk_bf16_f32 v8, v90, v90
	global_store_short v4, v8, s[68:69]
	v_add_u32_e32 v4, 0x76400, v3
	v_cvt_pk_bf16_f32 v5, v89, v89
	global_store_short v4, v5, s[68:69]
	v_add_u32_e32 v4, 0x77980, v3
	v_cvt_pk_bf16_f32 v6, v88, v88
	global_store_short v4, v6, s[68:69]
	v_add_u32_e32 v4, 0x78f00, v3
	v_cvt_pk_bf16_f32 v7, v87, v87
	global_store_short v4, v7, s[68:69]
	v_add_u32_e32 v4, 0x7a480, v3
	v_cvt_pk_bf16_f32 v8, v86, v86
	global_store_short v4, v8, s[68:69]
	v_add_u32_e32 v4, 0x81000, v3
	v_cvt_pk_bf16_f32 v5, v69, v69
	global_store_short v4, v5, s[68:69]
	v_add_u32_e32 v4, 0x82580, v3
	v_cvt_pk_bf16_f32 v6, v68, v68
	global_store_short v4, v6, s[68:69]
	v_add_u32_e32 v4, 0x83b00, v3
	v_cvt_pk_bf16_f32 v7, v67, v67
	global_store_short v4, v7, s[68:69]
	v_add_u32_e32 v4, 0x85080, v3
	v_cvt_pk_bf16_f32 v8, v66, v66
	global_store_short v4, v8, s[68:69]
	v_add_u32_e32 v4, 0x8bc00, v3
	v_cvt_pk_bf16_f32 v5, v65, v65
	global_store_short v4, v5, s[68:69]
	v_add_u32_e32 v4, 0x8d180, v3
	v_cvt_pk_bf16_f32 v6, v64, v64
	global_store_short v4, v6, s[68:69]
	v_add_u32_e32 v4, 0x8e700, v3
	v_cvt_pk_bf16_f32 v7, v63, v63
	global_store_short v4, v7, s[68:69]
	v_add_u32_e32 v4, 0x8fc80, v3
; DI void phase_in(const Params& p, int L, char* smem) {
;     ...
;       EPI_BEGINM(acc, 4)
;         const int oc = in_colmap(col);
;         if (oc >= 0 && oc < PJN) {
;           p.proj[(size_t)row * PJ + oc] = f2bf(v);
;           if (oc >= 1952 && oc < 1964) p.small_[row * 16 + (oc - 1952)] = v;
;           if (oc >= 2732) p.small_[row * 16 + 12 + (oc - 2732)] = v;
	v_cvt_pk_bf16_f32 v8, v62, v62
	global_store_short v4, v8, s[68:69]
	v_add_u32_e32 v4, 0x96800, v3
	v_cvt_pk_bf16_f32 v5, v61, v61
	global_store_short v4, v5, s[68:69]
	v_add_u32_e32 v4, 0x97d80, v3
	v_cvt_pk_bf16_f32 v6, v60, v60
	global_store_short v4, v6, s[68:69]
	v_add_u32_e32 v4, 0x99300, v3
	v_cvt_pk_bf16_f32 v7, v59, v59
	global_store_short v4, v7, s[68:69]
	v_add_u32_e32 v4, 0x9a880, v3
	v_cvt_pk_bf16_f32 v8, v58, v58
	global_store_short v4, v8, s[68:69]
	v_add_u32_e32 v4, 0xa1400, v3
	v_cvt_pk_bf16_f32 v5, v57, v57
	global_store_short v4, v5, s[68:69]
	v_add_u32_e32 v4, 0xa2980, v3
	v_cvt_pk_bf16_f32 v6, v56, v56
	global_store_short v4, v6, s[68:69]
	v_add_u32_e32 v4, 0xa3f00, v3
	v_cvt_pk_bf16_f32 v7, v55, v55
	global_store_short v4, v7, s[68:69]
	v_add_u32_e32 v4, 0xa5480, v3
	v_cvt_pk_bf16_f32 v8, v54, v54
	global_store_short v4, v8, s[68:69]
	v_mov_b32_e32 v9, 0x7a0
	v_mov_b32_e32 v10, 0xaa0
	v_cmp_gt_u32_e32 vcc, 12, v190
	v_cndmask_b32_e32 v9, v10, v9, vcc
	v_add_u32_e32 v9, v9, v190
	v_lshl_add_u32 v3, v9, 1, v2
	v_lshl_add_u32 v9, v0, 4, v190
	v_lshlrev_b32_e32 v9, 2, v9
	v_cmp_gt_u32_e32 vcc, 16, v190
	s_and_saveexec_b64 s[4:5], vcc
	v_cvt_pk_bf16_f32 v5, v151, v151
	global_store_short v3, v5, s[68:69]
	global_store_dword v9, v151, s[82:83]
	v_add_u32_e32 v4, 0x1580, v3
	v_add_u32_e32 v10, 0x40, v9
	v_cvt_pk_bf16_f32 v6, v150, v150
	global_store_short v4, v6, s[68:69]
	global_store_dword v10, v150, s[82:83]
	v_add_u32_e32 v4, 0x2b00, v3
	v_add_u32_e32 v10, 0x80, v9
	v_cvt_pk_bf16_f32 v7, v149, v149
	global_store_short v4, v7, s[68:69]
	global_store_dword v10, v149, s[82:83]
	v_add_u32_e32 v4, 0x4080, v3
	v_add_u32_e32 v10, 0xc0, v9
	v_cvt_pk_bf16_f32 v8, v148, v148
	global_store_short v4, v8, s[68:69]
	global_store_dword v10, v148, s[82:83]
	v_add_u32_e32 v4, 0xac00, v3
	v_add_u32_e32 v10, 0x200, v9
	v_cvt_pk_bf16_f32 v5, v147, v147
	global_store_short v4, v5, s[68:69]
	global_store_dword v10, v147, s[82:83]
	v_add_u32_e32 v4, 0xc180, v3
	v_add_u32_e32 v10, 0x240, v9
	v_cvt_pk_bf16_f32 v6, v146, v146
	global_store_short v4, v6, s[68:69]
	global_store_dword v10, v146, s[82:83]
	v_add_u32_e32 v4, 0xd700, v3
	v_add_u32_e32 v10, 0x280, v9
	v_cvt_pk_bf16_f32 v7, v145, v145
	global_store_short v4, v7, s[68:69]
	global_store_dword v10, v145, s[82:83]
	v_add_u32_e32 v4, 0xec80, v3
	v_add_u32_e32 v10, 0x2c0, v9
	v_cvt_pk_bf16_f32 v8, v144, v144
	global_store_short v4, v8, s[68:69]
	global_store_dword v10, v144, s[82:83]
	v_add_u32_e32 v4, 0x15800, v3
	v_add_u32_e32 v10, 0x400, v9
	v_cvt_pk_bf16_f32 v5, v143, v143
	global_store_short v4, v5, s[68:69]
	global_store_dword v10, v143, s[82:83]
	v_add_u32_e32 v4, 0x16d80, v3
	v_add_u32_e32 v10, 0x440, v9
	v_cvt_pk_bf16_f32 v6, v142, v142
	global_store_short v4, v6, s[68:69]
	global_store_dword v10, v142, s[82:83]
	v_add_u32_e32 v4, 0x18300, v3
	v_add_u32_e32 v10, 0x480, v9
	v_cvt_pk_bf16_f32 v7, v141, v141
	global_store_short v4, v7, s[68:69]
	global_store_dword v10, v141, s[82:83]
	v_add_u32_e32 v4, 0x19880, v3
	v_add_u32_e32 v10, 0x4c0, v9
	v_cvt_pk_bf16_f32 v8, v140, v140
	global_store_short v4, v8, s[68:69]
	global_store_dword v10, v140, s[82:83]
	v_add_u32_e32 v4, 0x20400, v3
	v_add_u32_e32 v10, 0x600, v9
	v_cvt_pk_bf16_f32 v5, v139, v139
	global_store_short v4, v5, s[68:69]
	global_store_dword v10, v139, s[82:83]
	v_add_u32_e32 v4, 0x21980, v3
	v_add_u32_e32 v10, 0x640, v9
	v_cvt_pk_bf16_f32 v6, v138, v138
	global_store_short v4, v6, s[68:69]
	global_store_dword v10, v138, s[82:83]
	v_add_u32_e32 v4, 0x22f00, v3
	v_add_u32_e32 v10, 0x680, v9
	v_cvt_pk_bf16_f32 v7, v137, v137
	global_store_short v4, v7, s[68:69]
	global_store_dword v10, v137, s[82:83]
	v_add_u32_e32 v4, 0x24480, v3
	v_add_u32_e32 v10, 0x6c0, v9
	v_cvt_pk_bf16_f32 v8, v136, v136
	global_store_short v4, v8, s[68:69]
	global_store_dword v10, v136, s[82:83]
	v_add_u32_e32 v4, 0x2b000, v3
	v_add_u32_e32 v10, 0x800, v9
	v_cvt_pk_bf16_f32 v5, v119, v119
	global_store_short v4, v5, s[68:69]
	global_store_dword v10, v119, s[82:83]
	v_add_u32_e32 v4, 0x2c580, v3
	v_add_u32_e32 v10, 0x840, v9
	v_cvt_pk_bf16_f32 v6, v118, v118
	global_store_short v4, v6, s[68:69]
	global_store_dword v10, v118, s[82:83]
	v_add_u32_e32 v4, 0x2db00, v3
	v_add_u32_e32 v10, 0x880, v9
	v_cvt_pk_bf16_f32 v7, v117, v117
	global_store_short v4, v7, s[68:69]
	global_store_dword v10, v117, s[82:83]
	v_add_u32_e32 v4, 0x2f080, v3
	v_add_u32_e32 v10, 0x8c0, v9
	v_cvt_pk_bf16_f32 v8, v116, v116
	global_store_short v4, v8, s[68:69]
	global_store_dword v10, v116, s[82:83]
	v_add_u32_e32 v4, 0x35c00, v3
	v_add_u32_e32 v10, 0xa00, v9
	v_cvt_pk_bf16_f32 v5, v115, v115
	global_store_short v4, v5, s[68:69]
	global_store_dword v10, v115, s[82:83]
	v_add_u32_e32 v4, 0x37180, v3
	v_add_u32_e32 v10, 0xa40, v9
	v_cvt_pk_bf16_f32 v6, v114, v114
	global_store_short v4, v6, s[68:69]
	global_store_dword v10, v114, s[82:83]
	v_add_u32_e32 v4, 0x38700, v3
	v_add_u32_e32 v10, 0xa80, v9
	v_cvt_pk_bf16_f32 v7, v113, v113
	global_store_short v4, v7, s[68:69]
	global_store_dword v10, v113, s[82:83]
	v_add_u32_e32 v4, 0x39c80, v3
	v_add_u32_e32 v10, 0xac0, v9
	v_cvt_pk_bf16_f32 v8, v112, v112
	global_store_short v4, v8, s[68:69]
	global_store_dword v10, v112, s[82:83]
	v_add_u32_e32 v4, 0x40800, v3
	v_add_u32_e32 v10, 0xc00, v9
	v_cvt_pk_bf16_f32 v5, v111, v111
	global_store_short v4, v5, s[68:69]
	global_store_dword v10, v111, s[82:83]
	v_add_u32_e32 v4, 0x41d80, v3
	v_add_u32_e32 v10, 0xc40, v9
	v_cvt_pk_bf16_f32 v6, v110, v110
	global_store_short v4, v6, s[68:69]
	global_store_dword v10, v110, s[82:83]
	v_add_u32_e32 v4, 0x43300, v3
	v_add_u32_e32 v10, 0xc80, v9
; DI void phase_in(const Params& p, int L, char* smem) {
;     ...
;       EPI_BEGINM(acc, 4)
;         const int oc = in_colmap(col);
;         if (oc >= 0 && oc < PJN) {
;           p.proj[(size_t)row * PJ + oc] = f2bf(v);
;           if (oc >= 1952 && oc < 1964) p.small_[row * 16 + (oc - 1952)] = v;
;           if (oc >= 2732) p.small_[row * 16 + 12 + (oc - 2732)] = v;
	v_cvt_pk_bf16_f32 v7, v109, v109
	global_store_short v4, v7, s[68:69]
	global_store_dword v10, v109, s[82:83]
	v_add_u32_e32 v4, 0x44880, v3
	v_add_u32_e32 v10, 0xcc0, v9
	v_cvt_pk_bf16_f32 v8, v108, v108
	global_store_short v4, v8, s[68:69]
	global_store_dword v10, v108, s[82:83]
	v_add_u32_e32 v4, 0x4b400, v3
	v_add_u32_e32 v10, 0xe00, v9
	v_cvt_pk_bf16_f32 v5, v107, v107
	global_store_short v4, v5, s[68:69]
	global_store_dword v10, v107, s[82:83]
	v_add_u32_e32 v4, 0x4c980, v3
	v_add_u32_e32 v10, 0xe40, v9
	v_cvt_pk_bf16_f32 v6, v106, v106
	global_store_short v4, v6, s[68:69]
	global_store_dword v10, v106, s[82:83]
	v_add_u32_e32 v4, 0x4df00, v3
	v_add_u32_e32 v10, 0xe80, v9
	v_cvt_pk_bf16_f32 v7, v105, v105
	global_store_short v4, v7, s[68:69]
	global_store_dword v10, v105, s[82:83]
	v_add_u32_e32 v4, 0x4f480, v3
	v_add_u32_e32 v10, 0xec0, v9
	v_cvt_pk_bf16_f32 v8, v104, v104
	global_store_short v4, v8, s[68:69]
	global_store_dword v10, v104, s[82:83]
	v_add_u32_e32 v4, 0x56000, v3
	v_add_u32_e32 v10, 0x1000, v9
	v_cvt_pk_bf16_f32 v5, v85, v85
	global_store_short v4, v5, s[68:69]
	global_store_dword v10, v85, s[82:83]
	v_add_u32_e32 v4, 0x57580, v3
	v_add_u32_e32 v10, 0x1040, v9
	v_cvt_pk_bf16_f32 v6, v84, v84
	global_store_short v4, v6, s[68:69]
	global_store_dword v10, v84, s[82:83]
	v_add_u32_e32 v4, 0x58b00, v3
	v_add_u32_e32 v10, 0x1080, v9
	v_cvt_pk_bf16_f32 v7, v83, v83
	global_store_short v4, v7, s[68:69]
	global_store_dword v10, v83, s[82:83]
	v_add_u32_e32 v4, 0x5a080, v3
	v_add_u32_e32 v10, 0x10c0, v9
	v_cvt_pk_bf16_f32 v8, v82, v82
	global_store_short v4, v8, s[68:69]
	global_store_dword v10, v82, s[82:83]
	v_add_u32_e32 v4, 0x60c00, v3
	v_add_u32_e32 v10, 0x1200, v9
	v_cvt_pk_bf16_f32 v5, v81, v81
	global_store_short v4, v5, s[68:69]
	global_store_dword v10, v81, s[82:83]
	v_add_u32_e32 v4, 0x62180, v3
	v_add_u32_e32 v10, 0x1240, v9
	v_cvt_pk_bf16_f32 v6, v80, v80
	global_store_short v4, v6, s[68:69]
	global_store_dword v10, v80, s[82:83]
	v_add_u32_e32 v4, 0x63700, v3
	v_add_u32_e32 v10, 0x1280, v9
	v_cvt_pk_bf16_f32 v7, v79, v79
	global_store_short v4, v7, s[68:69]
	global_store_dword v10, v79, s[82:83]
	v_add_u32_e32 v4, 0x64c80, v3
	v_add_u32_e32 v10, 0x12c0, v9
	v_cvt_pk_bf16_f32 v8, v78, v78
	global_store_short v4, v8, s[68:69]
	global_store_dword v10, v78, s[82:83]
	v_add_u32_e32 v4, 0x6b800, v3
	v_add_u32_e32 v10, 0x1400, v9
	v_cvt_pk_bf16_f32 v5, v77, v77
	global_store_short v4, v5, s[68:69]
	global_store_dword v10, v77, s[82:83]
	v_add_u32_e32 v4, 0x6cd80, v3
	v_add_u32_e32 v10, 0x1440, v9
	v_cvt_pk_bf16_f32 v6, v76, v76
	global_store_short v4, v6, s[68:69]
	global_store_dword v10, v76, s[82:83]
	v_add_u32_e32 v4, 0x6e300, v3
	v_add_u32_e32 v10, 0x1480, v9
	v_cvt_pk_bf16_f32 v7, v75, v75
	global_store_short v4, v7, s[68:69]
	global_store_dword v10, v75, s[82:83]
	v_add_u32_e32 v4, 0x6f880, v3
	v_add_u32_e32 v10, 0x14c0, v9
	v_cvt_pk_bf16_f32 v8, v74, v74
	global_store_short v4, v8, s[68:69]
	global_store_dword v10, v74, s[82:83]
	v_add_u32_e32 v4, 0x76400, v3
	v_add_u32_e32 v10, 0x1600, v9
	v_cvt_pk_bf16_f32 v5, v73, v73
	global_store_short v4, v5, s[68:69]
	global_store_dword v10, v73, s[82:83]
	v_add_u32_e32 v4, 0x77980, v3
	v_add_u32_e32 v10, 0x1640, v9
	v_cvt_pk_bf16_f32 v6, v72, v72
	global_store_short v4, v6, s[68:69]
	global_store_dword v10, v72, s[82:83]
	v_add_u32_e32 v4, 0x78f00, v3
	v_add_u32_e32 v10, 0x1680, v9
	v_cvt_pk_bf16_f32 v7, v71, v71
	global_store_short v4, v7, s[68:69]
	global_store_dword v10, v71, s[82:83]
	v_add_u32_e32 v4, 0x7a480, v3
	v_add_u32_e32 v10, 0x16c0, v9
	v_cvt_pk_bf16_f32 v8, v70, v70
	global_store_short v4, v8, s[68:69]
	global_store_dword v10, v70, s[82:83]
	v_add_u32_e32 v4, 0x81000, v3
	v_add_u32_e32 v10, 0x1800, v9
	v_cvt_pk_bf16_f32 v5, v53, v53
	global_store_short v4, v5, s[68:69]
	global_store_dword v10, v53, s[82:83]
	v_add_u32_e32 v4, 0x82580, v3
	v_add_u32_e32 v10, 0x1840, v9
	v_cvt_pk_bf16_f32 v6, v52, v52
	global_store_short v4, v6, s[68:69]
	global_store_dword v10, v52, s[82:83]
	v_add_u32_e32 v4, 0x83b00, v3
	v_add_u32_e32 v10, 0x1880, v9
	v_cvt_pk_bf16_f32 v7, v51, v51
	global_store_short v4, v7, s[68:69]
	global_store_dword v10, v51, s[82:83]
	v_add_u32_e32 v4, 0x85080, v3
	v_add_u32_e32 v10, 0x18c0, v9
	v_cvt_pk_bf16_f32 v8, v50, v50
	global_store_short v4, v8, s[68:69]
	global_store_dword v10, v50, s[82:83]
	v_add_u32_e32 v4, 0x8bc00, v3
	v_add_u32_e32 v10, 0x1a00, v9
	v_cvt_pk_bf16_f32 v5, v49, v49
	global_store_short v4, v5, s[68:69]
	global_store_dword v10, v49, s[82:83]
	v_add_u32_e32 v4, 0x8d180, v3
	v_add_u32_e32 v10, 0x1a40, v9
	v_cvt_pk_bf16_f32 v6, v48, v48
	global_store_short v4, v6, s[68:69]
	global_store_dword v10, v48, s[82:83]
	v_add_u32_e32 v4, 0x8e700, v3
	v_add_u32_e32 v10, 0x1a80, v9
	v_cvt_pk_bf16_f32 v7, v47, v47
	global_store_short v4, v7, s[68:69]
	global_store_dword v10, v47, s[82:83]
	v_add_u32_e32 v4, 0x8fc80, v3
	v_add_u32_e32 v10, 0x1ac0, v9
	v_cvt_pk_bf16_f32 v8, v46, v46
	global_store_short v4, v8, s[68:69]
	global_store_dword v10, v46, s[82:83]
	v_add_u32_e32 v4, 0x96800, v3
	v_add_u32_e32 v10, 0x1c00, v9
	v_cvt_pk_bf16_f32 v5, v45, v45
	global_store_short v4, v5, s[68:69]
	global_store_dword v10, v45, s[82:83]
	v_add_u32_e32 v4, 0x97d80, v3
	v_add_u32_e32 v10, 0x1c40, v9
	v_cvt_pk_bf16_f32 v6, v44, v44
	global_store_short v4, v6, s[68:69]
	global_store_dword v10, v44, s[82:83]
	v_add_u32_e32 v4, 0x99300, v3
	v_add_u32_e32 v10, 0x1c80, v9
	v_cvt_pk_bf16_f32 v7, v43, v43
	global_store_short v4, v7, s[68:69]
	global_store_dword v10, v43, s[82:83]
	v_add_u32_e32 v4, 0x9a880, v3
	v_add_u32_e32 v10, 0x1cc0, v9
	v_cvt_pk_bf16_f32 v8, v42, v42
	global_store_short v4, v8, s[68:69]
	global_store_dword v10, v42, s[82:83]
	v_add_u32_e32 v4, 0xa1400, v3
	v_add_u32_e32 v10, 0x1e00, v9
	v_cvt_pk_bf16_f32 v5, v41, v41
	global_store_short v4, v5, s[68:69]
	global_store_dword v10, v41, s[82:83]
	v_add_u32_e32 v4, 0xa2980, v3
	v_add_u32_e32 v10, 0x1e40, v9
	v_cvt_pk_bf16_f32 v6, v40, v40
	global_store_short v4, v6, s[68:69]
	global_store_dword v10, v40, s[82:83]
	v_add_u32_e32 v4, 0xa3f00, v3
	v_add_u32_e32 v10, 0x1e80, v9
	v_cvt_pk_bf16_f32 v7, v39, v39
	global_store_short v4, v7, s[68:69]
	global_store_dword v10, v39, s[82:83]
	v_add_u32_e32 v4, 0xa5480, v3
	v_add_u32_e32 v10, 0x1ec0, v9
	v_cvt_pk_bf16_f32 v8, v38, v38
	global_store_short v4, v8, s[68:69]
	global_store_dword v10, v38, s[82:83]
	s_mov_b64 exec, s[4:5]
; DI void phase_in(const Params& p, int L, char* smem) {
;     ...
;     } else if (cb < 8 || (cb >= 20 && cb < 24) || cb == 26 || cb == 28 || (cb >= 30 && cb < 38)) {
;       const float* g = nullptr; float sc = 1.f; bfu* dst;
;       if (cb < 4)       { sc = 0.125f; dst = p.q_sb + ((size_t)(b * 4 + cb) * S) * 64; }
;       else if (cb < 8)  { dst = p.k_sb + ((size_t)(b * 4 + cb - 4) * S) * 64; }
;       else if (cb < 24) { g = p.nsa_qn_g + L * 64; sc = 0.125f; dst = p.q_nsa + ((size_t)(b * 4 + cb - 20) * S) * 64; }
;       else if (cb == 26) { g = p.nsa_kn_g + (L * 3 + 1) * 64; dst = p.ks + ((size_t)b * S) * 64; }
;       else if (cb == 28) { g = p.nsa_kn_g + (L * 3 + 2) * 64; dst = p.kw + ((size_t)b * S) * 64; }
;       else if (cb < 34) { g = p.fox_qn_g + L * 64; sc = 0.125f; dst = p.q_fox + ((size_t)(b * 4 + cb - 30) * S) * 64; }
;       else              { g = p.fox_kn_g + L * 64; dst = p.k_fox + ((size_t)(b * 4 + cb - 34) * S) * 64; }
;       float g0 = sc, g1 = sc;
;       if (g) { g0 = g[r] * sc; g1 = g[32 + r] * sc; }
; #pragma unroll
;       for (int mt = 0; mt < 4; ++mt)
; #pragma unroll
;         for (int i = 0; i < 16; ++i) {
;           float v0 = acc[mt][0][i], v1 = acc[mt][1][i];
;           float rs = 1.f;
;           if (g) {
;             float ss = v0 * v0 + v1 * v1;
;             ss += __shfl_xor(ss, 1); ss += __shfl_xor(ss, 2); ss += __shfl_xor(ss, 4); ss += __shfl_xor(ss, 8); ss += __shfl_xor(ss, 16);
;             rs = rsqrtf(ss * (1.f / 64.f) + EPS);
;           }
;           const int sq = sb + mt * 32 + (i & 3) + 8 * (i >> 2) + 4 * hh;
;           dst[(size_t)sq * 64 + r] = f2bf(v0 * rs * g0);
;           dst[(size_t)sq * 64 + 32 + r] = f2bf(v1 * rs * g1);
;         }
.Lp1u_end:
.LBB0_1713:
	s_andn2_saveexec_b64 s[2:3], s[14:15]
	s_cbranch_execz .LBB0_780
	v_cmp_gt_i32_e32 vcc, 43, v167
	s_and_saveexec_b64 s[4:5], vcc
	s_xor_b64 s[4:5], exec, s[4:5]
	s_cbranch_execz .LBB0_1716
	s_ashr_i32 s7, s23, 1
	v_readlane_b32 s16, v254, 2
	v_readlane_b32 s17, v254, 3
	v_readlane_b32 s19, v254, 5
	v_add_u32_e32 v0, -4, v167
	v_cmp_gt_i32_e32 vcc, 4, v167
	v_readlane_b32 s18, v254, 4
	v_mov_b32_e32 v1, s19
	v_mov_b32_e32 v2, s17
	v_cndmask_b32_e32 v0, v0, v167, vcc
	v_cndmask_b32_e32 v3, v1, v2, vcc
	v_mov_b32_e32 v1, s18
	v_mov_b32_e32 v2, s16
	v_add_u32_e32 v0, s7, v0
	v_cndmask_b32_e32 v2, v1, v2, vcc
	v_mov_b32_e32 v1, 0x3e000000
	v_cndmask_b32_e32 v4, 1.0, v1, vcc
	v_ashrrev_i32_e32 v1, 31, v0
	s_and_b32 s6, s34, 0x700
	v_lshlrev_b64 v[0:1], 18, v[0:1]
	v_lshl_add_u64 v[0:1], v[2:3], 0, v[0:1]
	v_add_u32_e32 v2, s6, v206
	v_mul_f32_e32 v3, v4, v166
	v_mov_b32_e32 v193, v189
	v_cvt_pk_bf16_f32 v5, v3, s0
	v_ashrrev_i32_e32 v3, 31, v2
	v_lshl_add_u64 v[0:1], v[0:1], 0, v[192:193]
	v_lshlrev_b64 v[6:7], 7, v[2:3]
	v_mul_f32_e32 v3, v4, v151
	v_lshl_add_u64 v[6:7], v[0:1], 0, v[6:7]
	v_cvt_pk_bf16_f32 v3, v3, s0
	global_store_short v[6:7], v5, off
	global_store_short v[6:7], v3, off offset:64
	v_or_b32_e32 v6, 1, v2
	v_ashrrev_i32_e32 v7, 31, v6
	v_mul_f32_e32 v3, v4, v165
	v_lshlrev_b64 v[6:7], 7, v[6:7]
	v_cvt_pk_bf16_f32 v3, v3, s0
	v_lshl_add_u64 v[6:7], v[0:1], 0, v[6:7]
	global_store_short v[6:7], v3, off
	v_mul_f32_e32 v3, v4, v150
	v_cvt_pk_bf16_f32 v3, v3, s0
	global_store_short v[6:7], v3, off offset:64
	v_or_b32_e32 v6, 2, v2
	v_ashrrev_i32_e32 v7, 31, v6
	v_mul_f32_e32 v3, v4, v164
	v_lshlrev_b64 v[6:7], 7, v[6:7]
	v_cvt_pk_bf16_f32 v3, v3, s0
	v_lshl_add_u64 v[6:7], v[0:1], 0, v[6:7]
	global_store_short v[6:7], v3, off
	v_mul_f32_e32 v3, v4, v149
	v_cvt_pk_bf16_f32 v3, v3, s0
	global_store_short v[6:7], v3, off offset:64
	v_or_b32_e32 v6, 3, v2
	v_ashrrev_i32_e32 v7, 31, v6
	v_mul_f32_e32 v3, v4, v163
	v_lshlrev_b64 v[6:7], 7, v[6:7]
	v_cvt_pk_bf16_f32 v3, v3, s0
	v_lshl_add_u64 v[6:7], v[0:1], 0, v[6:7]
	global_store_short v[6:7], v3, off
	v_mul_f32_e32 v3, v4, v148
	v_cvt_pk_bf16_f32 v3, v3, s0
	global_store_short v[6:7], v3, off offset:64
	v_or_b32_e32 v6, 8, v2
	v_ashrrev_i32_e32 v7, 31, v6
	v_mul_f32_e32 v3, v4, v162
	v_lshlrev_b64 v[6:7], 7, v[6:7]
	v_cvt_pk_bf16_f32 v3, v3, s0
	v_lshl_add_u64 v[6:7], v[0:1], 0, v[6:7]
	global_store_short v[6:7], v3, off
	v_mul_f32_e32 v3, v4, v147
	v_cvt_pk_bf16_f32 v3, v3, s0
	global_store_short v[6:7], v3, off offset:64
	v_or_b32_e32 v6, 9, v2
	v_ashrrev_i32_e32 v7, 31, v6
	v_mul_f32_e32 v3, v4, v161
	v_lshlrev_b64 v[6:7], 7, v[6:7]
	v_cvt_pk_bf16_f32 v3, v3, s0
	v_lshl_add_u64 v[6:7], v[0:1], 0, v[6:7]
	global_store_short v[6:7], v3, off
	v_mul_f32_e32 v3, v4, v146
	v_cvt_pk_bf16_f32 v3, v3, s0
	global_store_short v[6:7], v3, off offset:64
	v_or_b32_e32 v6, 10, v2
	v_ashrrev_i32_e32 v7, 31, v6
	v_mul_f32_e32 v3, v4, v160
	v_lshlrev_b64 v[6:7], 7, v[6:7]
	v_cvt_pk_bf16_f32 v3, v3, s0
	v_lshl_add_u64 v[6:7], v[0:1], 0, v[6:7]
	global_store_short v[6:7], v3, off
	v_mul_f32_e32 v3, v4, v145
	v_cvt_pk_bf16_f32 v3, v3, s0
	global_store_short v[6:7], v3, off offset:64
	v_or_b32_e32 v6, 11, v2
	v_ashrrev_i32_e32 v7, 31, v6
	v_mul_f32_e32 v3, v4, v159
	v_lshlrev_b64 v[6:7], 7, v[6:7]
	v_cvt_pk_bf16_f32 v3, v3, s0
	v_lshl_add_u64 v[6:7], v[0:1], 0, v[6:7]
	global_store_short v[6:7], v3, off
	v_mul_f32_e32 v3, v4, v144
	v_cvt_pk_bf16_f32 v3, v3, s0
	global_store_short v[6:7], v3, off offset:64
	v_or_b32_e32 v6, 16, v2
	v_ashrrev_i32_e32 v7, 31, v6
	v_mul_f32_e32 v3, v4, v158
	v_lshlrev_b64 v[6:7], 7, v[6:7]
	v_cvt_pk_bf16_f32 v3, v3, s0
	v_lshl_add_u64 v[6:7], v[0:1], 0, v[6:7]
	global_store_short v[6:7], v3, off
	v_mul_f32_e32 v3, v4, v143
	v_cvt_pk_bf16_f32 v3, v3, s0
	global_store_short v[6:7], v3, off offset:64
	v_or_b32_e32 v6, 17, v2
	v_ashrrev_i32_e32 v7, 31, v6
	v_mul_f32_e32 v3, v4, v157
	v_lshlrev_b64 v[6:7], 7, v[6:7]
	v_cvt_pk_bf16_f32 v3, v3, s0
	v_lshl_add_u64 v[6:7], v[0:1], 0, v[6:7]
	global_store_short v[6:7], v3, off
	v_mul_f32_e32 v3, v4, v142
	v_cvt_pk_bf16_f32 v3, v3, s0
	global_store_short v[6:7], v3, off offset:64
	v_or_b32_e32 v6, 18, v2
	v_ashrrev_i32_e32 v7, 31, v6
	v_mul_f32_e32 v3, v4, v156
	v_lshlrev_b64 v[6:7], 7, v[6:7]
	v_cvt_pk_bf16_f32 v3, v3, s0
	v_lshl_add_u64 v[6:7], v[0:1], 0, v[6:7]
	global_store_short v[6:7], v3, off
	v_mul_f32_e32 v3, v4, v141
	v_cvt_pk_bf16_f32 v3, v3, s0
	global_store_short v[6:7], v3, off offset:64
	v_or_b32_e32 v6, 19, v2
	v_ashrrev_i32_e32 v7, 31, v6
	v_mul_f32_e32 v3, v4, v155
	v_lshlrev_b64 v[6:7], 7, v[6:7]
	v_cvt_pk_bf16_f32 v3, v3, s0
	v_lshl_add_u64 v[6:7], v[0:1], 0, v[6:7]
	global_store_short v[6:7], v3, off
	v_mul_f32_e32 v3, v4, v140
	v_cvt_pk_bf16_f32 v3, v3, s0
	global_store_short v[6:7], v3, off offset:64
	v_or_b32_e32 v6, 24, v2
	v_ashrrev_i32_e32 v7, 31, v6
	v_mul_f32_e32 v3, v4, v154
	v_lshlrev_b64 v[6:7], 7, v[6:7]
	v_cvt_pk_bf16_f32 v3, v3, s0
	v_lshl_add_u64 v[6:7], v[0:1], 0, v[6:7]
	global_store_short v[6:7], v3, off
	v_mul_f32_e32 v3, v4, v139
	v_cvt_pk_bf16_f32 v3, v3, s0
	global_store_short v[6:7], v3, off offset:64
	v_or_b32_e32 v6, 25, v2
	v_ashrrev_i32_e32 v7, 31, v6
	v_mul_f32_e32 v3, v4, v153
	v_lshlrev_b64 v[6:7], 7, v[6:7]
	v_cvt_pk_bf16_f32 v3, v3, s0
	v_lshl_add_u64 v[6:7], v[0:1], 0, v[6:7]
	global_store_short v[6:7], v3, off
	v_mul_f32_e32 v3, v4, v138
	v_cvt_pk_bf16_f32 v3, v3, s0
	global_store_short v[6:7], v3, off offset:64
	v_or_b32_e32 v6, 26, v2
	v_ashrrev_i32_e32 v7, 31, v6
	v_mul_f32_e32 v3, v4, v152
	v_lshlrev_b64 v[6:7], 7, v[6:7]
	v_cvt_pk_bf16_f32 v3, v3, s0
; DI void phase_in(const Params& p, int L, char* smem) {
;     ...
;       float g0 = sc, g1 = sc;
;       if (g) { g0 = g[r] * sc; g1 = g[32 + r] * sc; }
; #pragma unroll
;       for (int mt = 0; mt < 4; ++mt)
; #pragma unroll
;         for (int i = 0; i < 16; ++i) {
;           float v0 = acc[mt][0][i], v1 = acc[mt][1][i];
;           float rs = 1.f;
;           if (g) {
;             float ss = v0 * v0 + v1 * v1;
;             ss += __shfl_xor(ss, 1); ss += __shfl_xor(ss, 2); ss += __shfl_xor(ss, 4); ss += __shfl_xor(ss, 8); ss += __shfl_xor(ss, 16);
;             rs = rsqrtf(ss * (1.f / 64.f) + EPS);
;           }
;           const int sq = sb + mt * 32 + (i & 3) + 8 * (i >> 2) + 4 * hh;
;           dst[(size_t)sq * 64 + r] = f2bf(v0 * rs * g0);
;           dst[(size_t)sq * 64 + 32 + r] = f2bf(v1 * rs * g1);
;         }
	v_lshl_add_u64 v[6:7], v[0:1], 0, v[6:7]
	global_store_short v[6:7], v3, off
	v_mul_f32_e32 v3, v4, v137
	v_cvt_pk_bf16_f32 v3, v3, s0
	global_store_short v[6:7], v3, off offset:64
	v_or_b32_e32 v6, 27, v2
	v_ashrrev_i32_e32 v7, 31, v6
	v_mul_f32_e32 v3, v4, v103
	v_lshlrev_b64 v[6:7], 7, v[6:7]
	v_cvt_pk_bf16_f32 v3, v3, s0
	v_lshl_add_u64 v[6:7], v[0:1], 0, v[6:7]
	global_store_short v[6:7], v3, off
	v_mul_f32_e32 v3, v4, v136
	v_cvt_pk_bf16_f32 v3, v3, s0
	global_store_short v[6:7], v3, off offset:64
	v_or_b32_e32 v6, 32, v2
	v_ashrrev_i32_e32 v7, 31, v6
	v_mul_f32_e32 v3, v4, v135
	v_lshlrev_b64 v[6:7], 7, v[6:7]
	v_cvt_pk_bf16_f32 v3, v3, s0
	v_lshl_add_u64 v[6:7], v[0:1], 0, v[6:7]
	global_store_short v[6:7], v3, off
	v_mul_f32_e32 v3, v4, v119
	v_cvt_pk_bf16_f32 v3, v3, s0
	global_store_short v[6:7], v3, off offset:64
	v_or_b32_e32 v6, 33, v2
	v_ashrrev_i32_e32 v7, 31, v6
	v_mul_f32_e32 v3, v4, v134
	v_lshlrev_b64 v[6:7], 7, v[6:7]
	v_cvt_pk_bf16_f32 v3, v3, s0
	v_lshl_add_u64 v[6:7], v[0:1], 0, v[6:7]
	global_store_short v[6:7], v3, off
	v_mul_f32_e32 v3, v4, v118
	v_cvt_pk_bf16_f32 v3, v3, s0
	global_store_short v[6:7], v3, off offset:64
	v_or_b32_e32 v6, 34, v2
	v_ashrrev_i32_e32 v7, 31, v6
	v_mul_f32_e32 v3, v4, v133
	v_lshlrev_b64 v[6:7], 7, v[6:7]
	v_cvt_pk_bf16_f32 v3, v3, s0
	v_lshl_add_u64 v[6:7], v[0:1], 0, v[6:7]
	global_store_short v[6:7], v3, off
	v_mul_f32_e32 v3, v4, v117
	v_cvt_pk_bf16_f32 v3, v3, s0
	global_store_short v[6:7], v3, off offset:64
	v_or_b32_e32 v6, 35, v2
	v_ashrrev_i32_e32 v7, 31, v6
	v_mul_f32_e32 v3, v4, v132
	v_lshlrev_b64 v[6:7], 7, v[6:7]
	v_cvt_pk_bf16_f32 v3, v3, s0
	v_lshl_add_u64 v[6:7], v[0:1], 0, v[6:7]
	global_store_short v[6:7], v3, off
	v_mul_f32_e32 v3, v4, v116
	v_cvt_pk_bf16_f32 v3, v3, s0
	global_store_short v[6:7], v3, off offset:64
	v_or_b32_e32 v6, 40, v2
	v_ashrrev_i32_e32 v7, 31, v6
	v_mul_f32_e32 v3, v4, v131
	v_lshlrev_b64 v[6:7], 7, v[6:7]
	v_cvt_pk_bf16_f32 v3, v3, s0
	v_lshl_add_u64 v[6:7], v[0:1], 0, v[6:7]
	global_store_short v[6:7], v3, off
	v_mul_f32_e32 v3, v4, v115
	v_cvt_pk_bf16_f32 v3, v3, s0
	global_store_short v[6:7], v3, off offset:64
	v_or_b32_e32 v6, 41, v2
	v_ashrrev_i32_e32 v7, 31, v6
	v_mul_f32_e32 v3, v4, v130
	v_lshlrev_b64 v[6:7], 7, v[6:7]
	v_cvt_pk_bf16_f32 v3, v3, s0
	v_lshl_add_u64 v[6:7], v[0:1], 0, v[6:7]
	global_store_short v[6:7], v3, off
	v_mul_f32_e32 v3, v4, v114
	v_cvt_pk_bf16_f32 v3, v3, s0
	global_store_short v[6:7], v3, off offset:64
	v_or_b32_e32 v6, 42, v2
	v_ashrrev_i32_e32 v7, 31, v6
	v_mul_f32_e32 v3, v4, v129
	v_lshlrev_b64 v[6:7], 7, v[6:7]
	v_cvt_pk_bf16_f32 v3, v3, s0
	v_lshl_add_u64 v[6:7], v[0:1], 0, v[6:7]
	global_store_short v[6:7], v3, off
	v_mul_f32_e32 v3, v4, v113
	v_cvt_pk_bf16_f32 v3, v3, s0
	global_store_short v[6:7], v3, off offset:64
	v_or_b32_e32 v6, 43, v2
	v_ashrrev_i32_e32 v7, 31, v6
	v_mul_f32_e32 v3, v4, v128
	v_lshlrev_b64 v[6:7], 7, v[6:7]
	v_cvt_pk_bf16_f32 v3, v3, s0
	v_lshl_add_u64 v[6:7], v[0:1], 0, v[6:7]
	global_store_short v[6:7], v3, off
	v_mul_f32_e32 v3, v4, v112
	v_cvt_pk_bf16_f32 v3, v3, s0
	global_store_short v[6:7], v3, off offset:64
	v_or_b32_e32 v6, 48, v2
	v_ashrrev_i32_e32 v7, 31, v6
	v_mul_f32_e32 v3, v4, v127
	v_lshlrev_b64 v[6:7], 7, v[6:7]
	v_cvt_pk_bf16_f32 v3, v3, s0
	v_lshl_add_u64 v[6:7], v[0:1], 0, v[6:7]
	global_store_short v[6:7], v3, off
	v_mul_f32_e32 v3, v4, v111
	v_cvt_pk_bf16_f32 v3, v3, s0
	global_store_short v[6:7], v3, off offset:64
	v_or_b32_e32 v6, 49, v2
	v_ashrrev_i32_e32 v7, 31, v6
	v_mul_f32_e32 v3, v4, v126
	v_lshlrev_b64 v[6:7], 7, v[6:7]
	v_cvt_pk_bf16_f32 v3, v3, s0
	v_lshl_add_u64 v[6:7], v[0:1], 0, v[6:7]
	global_store_short v[6:7], v3, off
	v_mul_f32_e32 v3, v4, v110
	v_cvt_pk_bf16_f32 v3, v3, s0
	global_store_short v[6:7], v3, off offset:64
	v_or_b32_e32 v6, 50, v2
	v_ashrrev_i32_e32 v7, 31, v6
	v_mul_f32_e32 v3, v4, v125
	v_lshlrev_b64 v[6:7], 7, v[6:7]
	v_cvt_pk_bf16_f32 v3, v3, s0
	v_lshl_add_u64 v[6:7], v[0:1], 0, v[6:7]
	global_store_short v[6:7], v3, off
	v_mul_f32_e32 v3, v4, v109
	v_cvt_pk_bf16_f32 v3, v3, s0
	global_store_short v[6:7], v3, off offset:64
	v_or_b32_e32 v6, 51, v2
	v_ashrrev_i32_e32 v7, 31, v6
	v_mul_f32_e32 v3, v4, v124
	v_lshlrev_b64 v[6:7], 7, v[6:7]
	v_cvt_pk_bf16_f32 v3, v3, s0
	v_lshl_add_u64 v[6:7], v[0:1], 0, v[6:7]
	global_store_short v[6:7], v3, off
	v_mul_f32_e32 v3, v4, v108
	v_cvt_pk_bf16_f32 v3, v3, s0
	global_store_short v[6:7], v3, off offset:64
	v_or_b32_e32 v6, 56, v2
	v_ashrrev_i32_e32 v7, 31, v6
	v_mul_f32_e32 v3, v4, v123
	v_lshlrev_b64 v[6:7], 7, v[6:7]
	v_cvt_pk_bf16_f32 v3, v3, s0
	v_lshl_add_u64 v[6:7], v[0:1], 0, v[6:7]
	global_store_short v[6:7], v3, off
	v_mul_f32_e32 v3, v4, v107
	v_cvt_pk_bf16_f32 v3, v3, s0
	global_store_short v[6:7], v3, off offset:64
	v_or_b32_e32 v6, 57, v2
	v_ashrrev_i32_e32 v7, 31, v6
	v_mul_f32_e32 v3, v4, v122
	v_lshlrev_b64 v[6:7], 7, v[6:7]
	v_cvt_pk_bf16_f32 v3, v3, s0
	v_lshl_add_u64 v[6:7], v[0:1], 0, v[6:7]
	global_store_short v[6:7], v3, off
	v_mul_f32_e32 v3, v4, v106
	v_cvt_pk_bf16_f32 v3, v3, s0
	global_store_short v[6:7], v3, off offset:64
	v_or_b32_e32 v6, 58, v2
	v_ashrrev_i32_e32 v7, 31, v6
	v_mul_f32_e32 v3, v4, v121
	v_lshlrev_b64 v[6:7], 7, v[6:7]
	v_cvt_pk_bf16_f32 v3, v3, s0
	v_lshl_add_u64 v[6:7], v[0:1], 0, v[6:7]
	global_store_short v[6:7], v3, off
	v_mul_f32_e32 v3, v4, v105
	v_cvt_pk_bf16_f32 v3, v3, s0
	global_store_short v[6:7], v3, off offset:64
	v_or_b32_e32 v6, 59, v2
	v_ashrrev_i32_e32 v7, 31, v6
	v_mul_f32_e32 v3, v4, v120
	v_lshlrev_b64 v[6:7], 7, v[6:7]
	v_cvt_pk_bf16_f32 v3, v3, s0
	v_lshl_add_u64 v[6:7], v[0:1], 0, v[6:7]
	global_store_short v[6:7], v3, off
; DI void phase_in(const Params& p, int L, char* smem) {
;     ...
;       float g0 = sc, g1 = sc;
;       if (g) { g0 = g[r] * sc; g1 = g[32 + r] * sc; }
; #pragma unroll
;       for (int mt = 0; mt < 4; ++mt)
; #pragma unroll
;         for (int i = 0; i < 16; ++i) {
;           float v0 = acc[mt][0][i], v1 = acc[mt][1][i];
;           float rs = 1.f;
;           if (g) {
;             float ss = v0 * v0 + v1 * v1;
;             ss += __shfl_xor(ss, 1); ss += __shfl_xor(ss, 2); ss += __shfl_xor(ss, 4); ss += __shfl_xor(ss, 8); ss += __shfl_xor(ss, 16);
;             rs = rsqrtf(ss * (1.f / 64.f) + EPS);
;           }
;           const int sq = sb + mt * 32 + (i & 3) + 8 * (i >> 2) + 4 * hh;
;           dst[(size_t)sq * 64 + r] = f2bf(v0 * rs * g0);
;           dst[(size_t)sq * 64 + 32 + r] = f2bf(v1 * rs * g1);
;         }
	v_mul_f32_e32 v3, v4, v104
	v_cvt_pk_bf16_f32 v3, v3, s0
	global_store_short v[6:7], v3, off offset:64
	v_or_b32_e32 v6, 64, v2
	v_ashrrev_i32_e32 v7, 31, v6
	v_mul_f32_e32 v3, v4, v102
	v_lshlrev_b64 v[6:7], 7, v[6:7]
	v_cvt_pk_bf16_f32 v3, v3, s0
	v_lshl_add_u64 v[6:7], v[0:1], 0, v[6:7]
	global_store_short v[6:7], v3, off
	v_mul_f32_e32 v3, v4, v85
	v_cvt_pk_bf16_f32 v3, v3, s0
	global_store_short v[6:7], v3, off offset:64
	v_or_b32_e32 v6, 0x41, v2
	v_ashrrev_i32_e32 v7, 31, v6
	v_mul_f32_e32 v3, v4, v101
	v_lshlrev_b64 v[6:7], 7, v[6:7]
	v_cvt_pk_bf16_f32 v3, v3, s0
	v_lshl_add_u64 v[6:7], v[0:1], 0, v[6:7]
	global_store_short v[6:7], v3, off
	v_mul_f32_e32 v3, v4, v84
	v_cvt_pk_bf16_f32 v3, v3, s0
	global_store_short v[6:7], v3, off offset:64
	v_or_b32_e32 v6, 0x42, v2
	v_ashrrev_i32_e32 v7, 31, v6
	v_mul_f32_e32 v3, v4, v100
	v_lshlrev_b64 v[6:7], 7, v[6:7]
	v_cvt_pk_bf16_f32 v3, v3, s0
	v_lshl_add_u64 v[6:7], v[0:1], 0, v[6:7]
	global_store_short v[6:7], v3, off
	v_mul_f32_e32 v3, v4, v83
	v_cvt_pk_bf16_f32 v3, v3, s0
	global_store_short v[6:7], v3, off offset:64
	v_or_b32_e32 v6, 0x43, v2
	v_ashrrev_i32_e32 v7, 31, v6
	v_mul_f32_e32 v3, v4, v98
	v_lshlrev_b64 v[6:7], 7, v[6:7]
	v_cvt_pk_bf16_f32 v3, v3, s0
	v_lshl_add_u64 v[6:7], v[0:1], 0, v[6:7]
	global_store_short v[6:7], v3, off
	v_mul_f32_e32 v3, v4, v82
	v_cvt_pk_bf16_f32 v3, v3, s0
	global_store_short v[6:7], v3, off offset:64
	v_or_b32_e32 v6, 0x48, v2
	v_ashrrev_i32_e32 v7, 31, v6
	v_mul_f32_e32 v3, v4, v97
	v_lshlrev_b64 v[6:7], 7, v[6:7]
	v_cvt_pk_bf16_f32 v3, v3, s0
	v_lshl_add_u64 v[6:7], v[0:1], 0, v[6:7]
	global_store_short v[6:7], v3, off
	v_mul_f32_e32 v3, v4, v81
	v_cvt_pk_bf16_f32 v3, v3, s0
	global_store_short v[6:7], v3, off offset:64
	v_or_b32_e32 v6, 0x49, v2
	v_ashrrev_i32_e32 v7, 31, v6
	v_mul_f32_e32 v3, v4, v96
	v_lshlrev_b64 v[6:7], 7, v[6:7]
	v_cvt_pk_bf16_f32 v3, v3, s0
	v_lshl_add_u64 v[6:7], v[0:1], 0, v[6:7]
	global_store_short v[6:7], v3, off
	v_mul_f32_e32 v3, v4, v80
	v_cvt_pk_bf16_f32 v3, v3, s0
	global_store_short v[6:7], v3, off offset:64
	v_or_b32_e32 v6, 0x4a, v2
	v_ashrrev_i32_e32 v7, 31, v6
	v_mul_f32_e32 v3, v4, v95
	v_lshlrev_b64 v[6:7], 7, v[6:7]
	v_cvt_pk_bf16_f32 v3, v3, s0
	v_lshl_add_u64 v[6:7], v[0:1], 0, v[6:7]
	global_store_short v[6:7], v3, off
	v_mul_f32_e32 v3, v4, v79
	v_cvt_pk_bf16_f32 v3, v3, s0
	global_store_short v[6:7], v3, off offset:64
	v_or_b32_e32 v6, 0x4b, v2
	v_ashrrev_i32_e32 v7, 31, v6
	v_mul_f32_e32 v3, v4, v94
	v_lshlrev_b64 v[6:7], 7, v[6:7]
	v_cvt_pk_bf16_f32 v3, v3, s0
	v_lshl_add_u64 v[6:7], v[0:1], 0, v[6:7]
	global_store_short v[6:7], v3, off
	v_mul_f32_e32 v3, v4, v78
	v_cvt_pk_bf16_f32 v3, v3, s0
	global_store_short v[6:7], v3, off offset:64
	v_or_b32_e32 v6, 0x50, v2
	v_ashrrev_i32_e32 v7, 31, v6
	v_mul_f32_e32 v3, v4, v93
	v_lshlrev_b64 v[6:7], 7, v[6:7]
	v_cvt_pk_bf16_f32 v3, v3, s0
	v_lshl_add_u64 v[6:7], v[0:1], 0, v[6:7]
	global_store_short v[6:7], v3, off
	v_mul_f32_e32 v3, v4, v77
	v_cvt_pk_bf16_f32 v3, v3, s0
	global_store_short v[6:7], v3, off offset:64
	v_or_b32_e32 v6, 0x51, v2
	v_ashrrev_i32_e32 v7, 31, v6
	v_mul_f32_e32 v3, v4, v92
	v_lshlrev_b64 v[6:7], 7, v[6:7]
	v_cvt_pk_bf16_f32 v3, v3, s0
	v_lshl_add_u64 v[6:7], v[0:1], 0, v[6:7]
	global_store_short v[6:7], v3, off
	v_mul_f32_e32 v3, v4, v76
	v_cvt_pk_bf16_f32 v3, v3, s0
	global_store_short v[6:7], v3, off offset:64
	v_or_b32_e32 v6, 0x52, v2
	v_ashrrev_i32_e32 v7, 31, v6
	v_mul_f32_e32 v3, v4, v91
	v_lshlrev_b64 v[6:7], 7, v[6:7]
	v_cvt_pk_bf16_f32 v3, v3, s0
	v_lshl_add_u64 v[6:7], v[0:1], 0, v[6:7]
	global_store_short v[6:7], v3, off
	v_mul_f32_e32 v3, v4, v75
	v_cvt_pk_bf16_f32 v3, v3, s0
	global_store_short v[6:7], v3, off offset:64
	v_or_b32_e32 v6, 0x53, v2
	v_ashrrev_i32_e32 v7, 31, v6
	v_mul_f32_e32 v3, v4, v90
	v_lshlrev_b64 v[6:7], 7, v[6:7]
	v_cvt_pk_bf16_f32 v3, v3, s0
	v_lshl_add_u64 v[6:7], v[0:1], 0, v[6:7]
	global_store_short v[6:7], v3, off
	v_mul_f32_e32 v3, v4, v74
	v_cvt_pk_bf16_f32 v3, v3, s0
	global_store_short v[6:7], v3, off offset:64
	v_or_b32_e32 v6, 0x58, v2
	v_ashrrev_i32_e32 v7, 31, v6
	v_mul_f32_e32 v3, v4, v89
	v_lshlrev_b64 v[6:7], 7, v[6:7]
	v_cvt_pk_bf16_f32 v3, v3, s0
	v_lshl_add_u64 v[6:7], v[0:1], 0, v[6:7]
	global_store_short v[6:7], v3, off
	v_mul_f32_e32 v3, v4, v73
	v_cvt_pk_bf16_f32 v3, v3, s0
	global_store_short v[6:7], v3, off offset:64
	v_or_b32_e32 v6, 0x59, v2
	v_ashrrev_i32_e32 v7, 31, v6
	v_mul_f32_e32 v3, v4, v88
	v_lshlrev_b64 v[6:7], 7, v[6:7]
	v_cvt_pk_bf16_f32 v3, v3, s0
	v_lshl_add_u64 v[6:7], v[0:1], 0, v[6:7]
	global_store_short v[6:7], v3, off
	v_mul_f32_e32 v3, v4, v72
	v_cvt_pk_bf16_f32 v3, v3, s0
	global_store_short v[6:7], v3, off offset:64
	v_or_b32_e32 v6, 0x5a, v2
	v_ashrrev_i32_e32 v7, 31, v6
	v_mul_f32_e32 v3, v4, v87
	v_lshlrev_b64 v[6:7], 7, v[6:7]
	v_cvt_pk_bf16_f32 v3, v3, s0
	v_lshl_add_u64 v[6:7], v[0:1], 0, v[6:7]
	global_store_short v[6:7], v3, off
	v_mul_f32_e32 v3, v4, v71
	v_cvt_pk_bf16_f32 v3, v3, s0
	global_store_short v[6:7], v3, off offset:64
	v_or_b32_e32 v6, 0x5b, v2
	v_ashrrev_i32_e32 v7, 31, v6
	v_mul_f32_e32 v3, v4, v86
	v_lshlrev_b64 v[6:7], 7, v[6:7]
	v_cvt_pk_bf16_f32 v3, v3, s0
	v_lshl_add_u64 v[6:7], v[0:1], 0, v[6:7]
	global_store_short v[6:7], v3, off
	v_mul_f32_e32 v3, v4, v70
	v_cvt_pk_bf16_f32 v3, v3, s0
	global_store_short v[6:7], v3, off offset:64
	v_or_b32_e32 v6, 0x60, v2
	v_ashrrev_i32_e32 v7, 31, v6
	v_mul_f32_e32 v3, v4, v69
	v_lshlrev_b64 v[6:7], 7, v[6:7]
	v_cvt_pk_bf16_f32 v3, v3, s0
	v_lshl_add_u64 v[6:7], v[0:1], 0, v[6:7]
	global_store_short v[6:7], v3, off
	v_mul_f32_e32 v3, v4, v53
	v_cvt_pk_bf16_f32 v3, v3, s0
; DI void phase_in(const Params& p, int L, char* smem) {
;     ...
;       float g0 = sc, g1 = sc;
;       if (g) { g0 = g[r] * sc; g1 = g[32 + r] * sc; }
; #pragma unroll
;       for (int mt = 0; mt < 4; ++mt)
; #pragma unroll
;         for (int i = 0; i < 16; ++i) {
;           float v0 = acc[mt][0][i], v1 = acc[mt][1][i];
;           float rs = 1.f;
;           if (g) {
;             float ss = v0 * v0 + v1 * v1;
;             ss += __shfl_xor(ss, 1); ss += __shfl_xor(ss, 2); ss += __shfl_xor(ss, 4); ss += __shfl_xor(ss, 8); ss += __shfl_xor(ss, 16);
;             rs = rsqrtf(ss * (1.f / 64.f) + EPS);
;           }
;           const int sq = sb + mt * 32 + (i & 3) + 8 * (i >> 2) + 4 * hh;
;           dst[(size_t)sq * 64 + r] = f2bf(v0 * rs * g0);
;           dst[(size_t)sq * 64 + 32 + r] = f2bf(v1 * rs * g1);
;         }
	global_store_short v[6:7], v3, off offset:64
	v_or_b32_e32 v6, 0x61, v2
	v_ashrrev_i32_e32 v7, 31, v6
	v_mul_f32_e32 v3, v4, v68
	v_lshlrev_b64 v[6:7], 7, v[6:7]
	v_cvt_pk_bf16_f32 v3, v3, s0
	v_lshl_add_u64 v[6:7], v[0:1], 0, v[6:7]
	global_store_short v[6:7], v3, off
	v_mul_f32_e32 v3, v4, v52
	v_cvt_pk_bf16_f32 v3, v3, s0
	global_store_short v[6:7], v3, off offset:64
	v_or_b32_e32 v6, 0x62, v2
	v_ashrrev_i32_e32 v7, 31, v6
	v_mul_f32_e32 v3, v4, v67
	v_lshlrev_b64 v[6:7], 7, v[6:7]
	v_cvt_pk_bf16_f32 v3, v3, s0
	v_lshl_add_u64 v[6:7], v[0:1], 0, v[6:7]
	global_store_short v[6:7], v3, off
	v_mul_f32_e32 v3, v4, v51
	v_cvt_pk_bf16_f32 v3, v3, s0
	global_store_short v[6:7], v3, off offset:64
	v_or_b32_e32 v6, 0x63, v2
	v_ashrrev_i32_e32 v7, 31, v6
	v_mul_f32_e32 v3, v4, v66
	v_lshlrev_b64 v[6:7], 7, v[6:7]
	v_cvt_pk_bf16_f32 v3, v3, s0
	v_lshl_add_u64 v[6:7], v[0:1], 0, v[6:7]
	global_store_short v[6:7], v3, off
	v_mul_f32_e32 v3, v4, v50
	v_cvt_pk_bf16_f32 v3, v3, s0
	global_store_short v[6:7], v3, off offset:64
	v_or_b32_e32 v6, 0x68, v2
	v_ashrrev_i32_e32 v7, 31, v6
	v_mul_f32_e32 v3, v4, v65
	v_lshlrev_b64 v[6:7], 7, v[6:7]
	v_cvt_pk_bf16_f32 v3, v3, s0
	v_lshl_add_u64 v[6:7], v[0:1], 0, v[6:7]
	global_store_short v[6:7], v3, off
	v_mul_f32_e32 v3, v4, v49
	v_cvt_pk_bf16_f32 v3, v3, s0
	global_store_short v[6:7], v3, off offset:64
	v_or_b32_e32 v6, 0x69, v2
	v_ashrrev_i32_e32 v7, 31, v6
	v_mul_f32_e32 v3, v4, v64
	v_lshlrev_b64 v[6:7], 7, v[6:7]
	v_cvt_pk_bf16_f32 v3, v3, s0
	v_lshl_add_u64 v[6:7], v[0:1], 0, v[6:7]
	global_store_short v[6:7], v3, off
	v_mul_f32_e32 v3, v4, v48
	v_cvt_pk_bf16_f32 v3, v3, s0
	global_store_short v[6:7], v3, off offset:64
	v_or_b32_e32 v6, 0x6a, v2
	v_ashrrev_i32_e32 v7, 31, v6
	v_mul_f32_e32 v3, v4, v63
	v_lshlrev_b64 v[6:7], 7, v[6:7]
	v_cvt_pk_bf16_f32 v3, v3, s0
	v_lshl_add_u64 v[6:7], v[0:1], 0, v[6:7]
	global_store_short v[6:7], v3, off
	v_mul_f32_e32 v3, v4, v47
	v_cvt_pk_bf16_f32 v3, v3, s0
	global_store_short v[6:7], v3, off offset:64
	v_or_b32_e32 v6, 0x6b, v2
	v_ashrrev_i32_e32 v7, 31, v6
	v_mul_f32_e32 v3, v4, v62
	v_lshlrev_b64 v[6:7], 7, v[6:7]
	v_cvt_pk_bf16_f32 v3, v3, s0
	v_lshl_add_u64 v[6:7], v[0:1], 0, v[6:7]
	global_store_short v[6:7], v3, off
	v_mul_f32_e32 v3, v4, v46
	v_cvt_pk_bf16_f32 v3, v3, s0
	global_store_short v[6:7], v3, off offset:64
	v_or_b32_e32 v6, 0x70, v2
	v_ashrrev_i32_e32 v7, 31, v6
	v_mul_f32_e32 v3, v4, v61
	v_lshlrev_b64 v[6:7], 7, v[6:7]
	v_cvt_pk_bf16_f32 v3, v3, s0
	v_lshl_add_u64 v[6:7], v[0:1], 0, v[6:7]
	global_store_short v[6:7], v3, off
	v_mul_f32_e32 v3, v4, v45
	v_cvt_pk_bf16_f32 v3, v3, s0
	global_store_short v[6:7], v3, off offset:64
	v_or_b32_e32 v6, 0x71, v2
	v_ashrrev_i32_e32 v7, 31, v6
	v_mul_f32_e32 v3, v4, v60
	v_lshlrev_b64 v[6:7], 7, v[6:7]
	v_cvt_pk_bf16_f32 v3, v3, s0
	v_lshl_add_u64 v[6:7], v[0:1], 0, v[6:7]
	global_store_short v[6:7], v3, off
	v_mul_f32_e32 v3, v4, v44
	v_cvt_pk_bf16_f32 v3, v3, s0
	global_store_short v[6:7], v3, off offset:64
	v_or_b32_e32 v6, 0x72, v2
	v_ashrrev_i32_e32 v7, 31, v6
	v_mul_f32_e32 v3, v4, v59
	v_lshlrev_b64 v[6:7], 7, v[6:7]
	v_cvt_pk_bf16_f32 v3, v3, s0
	v_lshl_add_u64 v[6:7], v[0:1], 0, v[6:7]
	global_store_short v[6:7], v3, off
	v_mul_f32_e32 v3, v4, v43
	v_cvt_pk_bf16_f32 v3, v3, s0
	global_store_short v[6:7], v3, off offset:64
	v_or_b32_e32 v6, 0x73, v2
	v_ashrrev_i32_e32 v7, 31, v6
	v_mul_f32_e32 v3, v4, v58
	v_lshlrev_b64 v[6:7], 7, v[6:7]
	v_cvt_pk_bf16_f32 v3, v3, s0
	v_lshl_add_u64 v[6:7], v[0:1], 0, v[6:7]
	global_store_short v[6:7], v3, off
	v_mul_f32_e32 v3, v4, v42
	v_cvt_pk_bf16_f32 v3, v3, s0
	global_store_short v[6:7], v3, off offset:64
	v_or_b32_e32 v6, 0x78, v2
	v_ashrrev_i32_e32 v7, 31, v6
	v_mul_f32_e32 v3, v4, v57
	v_lshlrev_b64 v[6:7], 7, v[6:7]
	v_cvt_pk_bf16_f32 v3, v3, s0
	v_lshl_add_u64 v[6:7], v[0:1], 0, v[6:7]
	global_store_short v[6:7], v3, off
	v_mul_f32_e32 v3, v4, v41
	v_cvt_pk_bf16_f32 v3, v3, s0
	global_store_short v[6:7], v3, off offset:64
	v_or_b32_e32 v6, 0x79, v2
	v_ashrrev_i32_e32 v7, 31, v6
	v_mul_f32_e32 v3, v4, v56
	v_lshlrev_b64 v[6:7], 7, v[6:7]
	v_cvt_pk_bf16_f32 v3, v3, s0
	v_lshl_add_u64 v[6:7], v[0:1], 0, v[6:7]
	global_store_short v[6:7], v3, off
	v_mul_f32_e32 v3, v4, v40
	v_cvt_pk_bf16_f32 v3, v3, s0
	global_store_short v[6:7], v3, off offset:64
	v_or_b32_e32 v6, 0x7a, v2
	v_ashrrev_i32_e32 v7, 31, v6
	v_mul_f32_e32 v3, v4, v55
	v_lshlrev_b64 v[6:7], 7, v[6:7]
	v_cvt_pk_bf16_f32 v3, v3, s0
	v_lshl_add_u64 v[6:7], v[0:1], 0, v[6:7]
	global_store_short v[6:7], v3, off
	v_mul_f32_e32 v3, v4, v39
	v_cvt_pk_bf16_f32 v3, v3, s0
	global_store_short v[6:7], v3, off offset:64
	v_or_b32_e32 v2, 0x7b, v2
	v_mul_f32_e32 v3, v4, v54
	v_cvt_pk_bf16_f32 v5, v3, s0
	v_ashrrev_i32_e32 v3, 31, v2
	v_lshlrev_b64 v[2:3], 7, v[2:3]
	v_lshl_add_u64 v[0:1], v[0:1], 0, v[2:3]
	v_mul_f32_e32 v2, v4, v38
	v_cvt_pk_bf16_f32 v2, v2, s0
	v_readlane_b32 s20, v254, 6
	v_readlane_b32 s21, v254, 7
	v_readlane_b32 s22, v254, 8
	v_readlane_b32 s23, v254, 9
	v_readlane_b32 s24, v254, 10
	v_readlane_b32 s25, v254, 11
	v_readlane_b32 s26, v254, 12
	v_readlane_b32 s27, v254, 13
	v_readlane_b32 s28, v254, 14
	v_readlane_b32 s29, v254, 15
	v_readlane_b32 s30, v254, 16
	v_readlane_b32 s31, v254, 17
	global_store_short v[0:1], v5, off
	global_store_short v[0:1], v2, off offset:64
; DI float sigmoidf_(float v) { return 1.f / (1.f + __expf(-v)); }
; DI void phase_in(const Params& p, int L, char* smem) {
;     ...
;     if (cb >= 43) {
;       if (cb < 107) {
;         EPI_BEGINM(acc, 4) p.gates[(size_t)row * 4096 + (col - 2752)] = f2bf(sigmoidf_(v)); EPI_END
;       }
.LBB0_1716:
	s_andn2_saveexec_b64 s[4:5], s[4:5]
	s_cbranch_execz .LBB0_779
	s_movk_i32 s6, 0x6b
	v_cmp_gt_u32_e32 vcc, s6, v167
	s_and_saveexec_b64 s[6:7], vcc
	s_cbranch_execz .LBB0_778
	v_mul_f32_e32 v0, 0xbfb8aa3b, v166
	v_exp_f32_e32 v0, v0
	v_add_u32_e32 v2, s34, v206
	s_movk_i32 s10, 0xf000
	v_mul_f32_e32 v150, 0xbfb8aa3b, v150
	v_add_f32_e32 v3, 1.0, v0
	v_div_scale_f32 v4, s[8:9], v3, v3, 1.0
	v_rcp_f32_e32 v5, v4
	v_or_b32_e32 v0, s33, v208
	v_ashrrev_i32_e32 v1, 31, v0
	v_lshl_add_u64 v[0:1], v[0:1], 1, s[70:71]
	v_fma_f32 v6, -v4, v5, 1.0
	v_fmac_f32_e32 v5, v6, v5
	v_div_scale_f32 v6, vcc, 1.0, v3, 1.0
	v_mul_f32_e32 v7, v6, v5
	v_fma_f32 v8, -v4, v7, v6
	v_fmac_f32_e32 v7, v8, v5
	v_fma_f32 v4, -v4, v7, v6
	v_div_fmas_f32 v4, v4, v5, v7
	v_div_fixup_f32 v3, v4, v3, 1.0
	v_cvt_pk_bf16_f32 v6, v3, s0
	v_mul_f32_e32 v3, 0xbfb8aa3b, v165
	v_exp_f32_e32 v7, v3
	v_ashrrev_i32_e32 v3, 31, v2
	v_lshlrev_b64 v[4:5], 13, v[2:3]
	v_lshl_add_u64 v[4:5], v[0:1], 0, v[4:5]
	v_add_f32_e32 v3, 1.0, v7
	v_div_scale_f32 v7, s[8:9], v3, v3, 1.0
	v_rcp_f32_e32 v8, v7
	v_add_co_u32_e32 v4, vcc, s10, v4
	v_exp_f32_e32 v150, v150
	s_nop 0
	v_addc_co_u32_e32 v5, vcc, -1, v5, vcc
	v_fma_f32 v9, -v7, v8, 1.0
	v_fmac_f32_e32 v8, v9, v8
	v_div_scale_f32 v9, vcc, 1.0, v3, 1.0
	v_mul_f32_e32 v10, v9, v8
	v_fma_f32 v11, -v7, v10, v9
	v_fmac_f32_e32 v10, v11, v8
	v_fma_f32 v7, -v7, v10, v9
	v_div_fmas_f32 v7, v7, v8, v10
	v_div_fixup_f32 v3, v7, v3, 1.0
	v_mul_f32_e32 v7, 0xbfb8aa3b, v164
	v_exp_f32_e32 v8, v7
	global_store_short v[4:5], v6, off offset:-1408
	v_or_b32_e32 v6, 1, v2
	v_ashrrev_i32_e32 v7, 31, v6
	v_add_f32_e32 v9, 1.0, v8
	v_div_scale_f32 v10, s[8:9], v9, v9, 1.0
	v_lshlrev_b64 v[6:7], 13, v[6:7]
	v_rcp_f32_e32 v11, v10
	v_lshl_add_u64 v[6:7], v[0:1], 0, v[6:7]
	v_add_co_u32_e32 v6, vcc, s10, v6
	v_cvt_pk_bf16_f32 v3, v3, s0
	s_nop 0
	v_addc_co_u32_e32 v7, vcc, -1, v7, vcc
	global_store_short v[6:7], v3, off offset:-1408
	v_fma_f32 v3, -v10, v11, 1.0
	v_fmac_f32_e32 v11, v3, v11
	v_div_scale_f32 v3, vcc, 1.0, v9, 1.0
	v_mul_f32_e32 v12, v3, v11
	v_fma_f32 v13, -v10, v12, v3
	v_fmac_f32_e32 v12, v13, v11
	v_fma_f32 v3, -v10, v12, v3
	v_div_fmas_f32 v3, v3, v11, v12
	v_div_fixup_f32 v3, v3, v9, 1.0
	v_mul_f32_e32 v9, 0xbfb8aa3b, v163
	v_exp_f32_e32 v10, v9
	v_or_b32_e32 v8, 2, v2
	v_ashrrev_i32_e32 v9, 31, v8
	v_lshlrev_b64 v[8:9], 13, v[8:9]
	v_add_f32_e32 v11, 1.0, v10
	v_div_scale_f32 v12, s[8:9], v11, v11, 1.0
	v_rcp_f32_e32 v13, v12
	v_lshl_add_u64 v[8:9], v[0:1], 0, v[8:9]
	v_add_co_u32_e32 v8, vcc, s10, v8
	v_cvt_pk_bf16_f32 v3, v3, s0
	s_nop 0
	v_addc_co_u32_e32 v9, vcc, -1, v9, vcc
	global_store_short v[8:9], v3, off offset:-1408
	v_fma_f32 v3, -v12, v13, 1.0
	v_fmac_f32_e32 v13, v3, v13
	v_div_scale_f32 v3, vcc, 1.0, v11, 1.0
	v_mul_f32_e32 v14, v3, v13
	v_fma_f32 v15, -v12, v14, v3
	v_fmac_f32_e32 v14, v15, v13
	v_fma_f32 v3, -v12, v14, v3
	v_div_fmas_f32 v3, v3, v13, v14
	v_div_fixup_f32 v3, v3, v11, 1.0
	v_mul_f32_e32 v11, 0xbfb8aa3b, v162
	v_exp_f32_e32 v12, v11
	v_or_b32_e32 v10, 3, v2
	v_ashrrev_i32_e32 v11, 31, v10
	v_lshlrev_b64 v[10:11], 13, v[10:11]
	v_add_f32_e32 v13, 1.0, v12
	v_div_scale_f32 v14, s[8:9], v13, v13, 1.0
	v_rcp_f32_e32 v15, v14
	v_lshl_add_u64 v[10:11], v[0:1], 0, v[10:11]
	v_add_co_u32_e32 v10, vcc, s10, v10
	v_cvt_pk_bf16_f32 v3, v3, s0
	s_nop 0
	v_addc_co_u32_e32 v11, vcc, -1, v11, vcc
	global_store_short v[10:11], v3, off offset:-1408
	v_fma_f32 v3, -v14, v15, 1.0
	v_fmac_f32_e32 v15, v3, v15
	v_div_scale_f32 v3, vcc, 1.0, v13, 1.0
	v_mul_f32_e32 v16, v3, v15
	v_fma_f32 v17, -v14, v16, v3
	v_fmac_f32_e32 v16, v17, v15
	v_fma_f32 v3, -v14, v16, v3
	v_div_fmas_f32 v3, v3, v15, v16
	v_div_fixup_f32 v3, v3, v13, 1.0
	v_mul_f32_e32 v13, 0xbfb8aa3b, v161
	v_exp_f32_e32 v14, v13
	v_or_b32_e32 v12, 8, v2
	v_ashrrev_i32_e32 v13, 31, v12
	v_lshlrev_b64 v[12:13], 13, v[12:13]
	v_add_f32_e32 v15, 1.0, v14
	v_div_scale_f32 v16, s[8:9], v15, v15, 1.0
	v_rcp_f32_e32 v17, v16
	v_lshl_add_u64 v[12:13], v[0:1], 0, v[12:13]
	v_add_co_u32_e32 v12, vcc, s10, v12
	v_cvt_pk_bf16_f32 v3, v3, s0
	s_nop 0
	v_addc_co_u32_e32 v13, vcc, -1, v13, vcc
	global_store_short v[12:13], v3, off offset:-1408
	v_fma_f32 v3, -v16, v17, 1.0
	v_fmac_f32_e32 v17, v3, v17
	v_div_scale_f32 v3, vcc, 1.0, v15, 1.0
	v_mul_f32_e32 v18, v3, v17
	v_fma_f32 v19, -v16, v18, v3
	v_fmac_f32_e32 v18, v19, v17
	v_fma_f32 v3, -v16, v18, v3
	v_div_fmas_f32 v3, v3, v17, v18
	v_div_fixup_f32 v3, v3, v15, 1.0
	v_mul_f32_e32 v15, 0xbfb8aa3b, v160
	v_exp_f32_e32 v16, v15
	v_or_b32_e32 v14, 9, v2
	v_ashrrev_i32_e32 v15, 31, v14
	v_lshlrev_b64 v[14:15], 13, v[14:15]
	v_add_f32_e32 v17, 1.0, v16
	v_div_scale_f32 v18, s[8:9], v17, v17, 1.0
	v_rcp_f32_e32 v19, v18
	v_lshl_add_u64 v[14:15], v[0:1], 0, v[14:15]
	v_add_co_u32_e32 v14, vcc, s10, v14
	v_cvt_pk_bf16_f32 v3, v3, s0
	s_nop 0
	v_addc_co_u32_e32 v15, vcc, -1, v15, vcc
	global_store_short v[14:15], v3, off offset:-1408
	v_fma_f32 v3, -v18, v19, 1.0
	v_fmac_f32_e32 v19, v3, v19
	v_div_scale_f32 v3, vcc, 1.0, v17, 1.0
	v_mul_f32_e32 v20, v3, v19
	v_fma_f32 v21, -v18, v20, v3
	v_fmac_f32_e32 v20, v21, v19
	v_fma_f32 v3, -v18, v20, v3
	v_div_fmas_f32 v3, v3, v19, v20
	v_div_fixup_f32 v3, v3, v17, 1.0
	v_mul_f32_e32 v17, 0xbfb8aa3b, v159
	v_exp_f32_e32 v18, v17
	v_or_b32_e32 v16, 10, v2
	v_ashrrev_i32_e32 v17, 31, v16
	v_lshlrev_b64 v[16:17], 13, v[16:17]
	v_add_f32_e32 v19, 1.0, v18
	v_div_scale_f32 v20, s[8:9], v19, v19, 1.0
	v_rcp_f32_e32 v21, v20
	v_lshl_add_u64 v[16:17], v[0:1], 0, v[16:17]
	v_add_co_u32_e32 v16, vcc, s10, v16
	v_cvt_pk_bf16_f32 v3, v3, s0
	s_nop 0
	v_addc_co_u32_e32 v17, vcc, -1, v17, vcc
; DI float sigmoidf_(float v) { return 1.f / (1.f + __expf(-v)); }
; DI void phase_in(const Params& p, int L, char* smem) {
;     ...
;     if (cb >= 43) {
;       if (cb < 107) {
;         EPI_BEGINM(acc, 4) p.gates[(size_t)row * 4096 + (col - 2752)] = f2bf(sigmoidf_(v)); EPI_END
	global_store_short v[16:17], v3, off offset:-1408
	v_fma_f32 v3, -v20, v21, 1.0
	v_fmac_f32_e32 v21, v3, v21
	v_div_scale_f32 v3, vcc, 1.0, v19, 1.0
	v_mul_f32_e32 v22, v3, v21
	v_fma_f32 v23, -v20, v22, v3
	v_fmac_f32_e32 v22, v23, v21
	v_fma_f32 v3, -v20, v22, v3
	v_div_fmas_f32 v3, v3, v21, v22
	v_div_fixup_f32 v3, v3, v19, 1.0
	v_mul_f32_e32 v19, 0xbfb8aa3b, v158
	v_exp_f32_e32 v20, v19
	v_or_b32_e32 v18, 11, v2
	v_ashrrev_i32_e32 v19, 31, v18
	v_lshlrev_b64 v[18:19], 13, v[18:19]
	v_add_f32_e32 v21, 1.0, v20
	v_div_scale_f32 v22, s[8:9], v21, v21, 1.0
	v_rcp_f32_e32 v23, v22
	v_lshl_add_u64 v[18:19], v[0:1], 0, v[18:19]
	v_add_co_u32_e32 v18, vcc, s10, v18
	v_cvt_pk_bf16_f32 v3, v3, s0
	s_nop 0
	v_addc_co_u32_e32 v19, vcc, -1, v19, vcc
	global_store_short v[18:19], v3, off offset:-1408
	v_fma_f32 v3, -v22, v23, 1.0
	v_fmac_f32_e32 v23, v3, v23
	v_div_scale_f32 v3, vcc, 1.0, v21, 1.0
	v_mul_f32_e32 v24, v3, v23
	v_fma_f32 v25, -v22, v24, v3
	v_fmac_f32_e32 v24, v25, v23
	v_fma_f32 v3, -v22, v24, v3
	v_div_fmas_f32 v3, v3, v23, v24
	v_div_fixup_f32 v3, v3, v21, 1.0
	v_mul_f32_e32 v21, 0xbfb8aa3b, v157
	v_exp_f32_e32 v22, v21
	v_or_b32_e32 v20, 16, v2
	v_ashrrev_i32_e32 v21, 31, v20
	v_lshlrev_b64 v[20:21], 13, v[20:21]
	v_add_f32_e32 v23, 1.0, v22
	v_div_scale_f32 v24, s[8:9], v23, v23, 1.0
	v_rcp_f32_e32 v25, v24
	v_lshl_add_u64 v[20:21], v[0:1], 0, v[20:21]
	v_add_co_u32_e32 v20, vcc, s10, v20
	v_cvt_pk_bf16_f32 v3, v3, s0
	s_nop 0
	v_addc_co_u32_e32 v21, vcc, -1, v21, vcc
	global_store_short v[20:21], v3, off offset:-1408
	v_fma_f32 v3, -v24, v25, 1.0
	v_fmac_f32_e32 v25, v3, v25
	v_div_scale_f32 v3, vcc, 1.0, v23, 1.0
	v_mul_f32_e32 v26, v3, v25
	v_fma_f32 v27, -v24, v26, v3
	v_fmac_f32_e32 v26, v27, v25
	v_fma_f32 v3, -v24, v26, v3
	v_div_fmas_f32 v3, v3, v25, v26
	v_div_fixup_f32 v3, v3, v23, 1.0
	v_mul_f32_e32 v23, 0xbfb8aa3b, v156
	v_exp_f32_e32 v24, v23
	v_or_b32_e32 v22, 17, v2
	v_ashrrev_i32_e32 v23, 31, v22
	v_lshlrev_b64 v[22:23], 13, v[22:23]
	v_add_f32_e32 v25, 1.0, v24
	v_div_scale_f32 v26, s[8:9], v25, v25, 1.0
	v_rcp_f32_e32 v27, v26
	v_lshl_add_u64 v[22:23], v[0:1], 0, v[22:23]
	v_add_co_u32_e32 v22, vcc, s10, v22
	v_cvt_pk_bf16_f32 v3, v3, s0
	s_nop 0
	v_addc_co_u32_e32 v23, vcc, -1, v23, vcc
	global_store_short v[22:23], v3, off offset:-1408
	v_fma_f32 v3, -v26, v27, 1.0
	v_fmac_f32_e32 v27, v3, v27
	v_div_scale_f32 v3, vcc, 1.0, v25, 1.0
	v_mul_f32_e32 v28, v3, v27
	v_fma_f32 v29, -v26, v28, v3
	v_fmac_f32_e32 v28, v29, v27
	v_fma_f32 v3, -v26, v28, v3
	v_div_fmas_f32 v3, v3, v27, v28
	v_div_fixup_f32 v3, v3, v25, 1.0
	v_mul_f32_e32 v25, 0xbfb8aa3b, v155
	v_exp_f32_e32 v26, v25
	v_or_b32_e32 v24, 18, v2
	v_ashrrev_i32_e32 v25, 31, v24
	v_lshlrev_b64 v[24:25], 13, v[24:25]
	v_add_f32_e32 v27, 1.0, v26
	v_div_scale_f32 v28, s[8:9], v27, v27, 1.0
	v_rcp_f32_e32 v29, v28
	v_lshl_add_u64 v[24:25], v[0:1], 0, v[24:25]
	v_add_co_u32_e32 v24, vcc, s10, v24
	v_cvt_pk_bf16_f32 v3, v3, s0
	s_nop 0
	v_addc_co_u32_e32 v25, vcc, -1, v25, vcc
	global_store_short v[24:25], v3, off offset:-1408
	v_fma_f32 v3, -v28, v29, 1.0
	v_fmac_f32_e32 v29, v3, v29
	v_div_scale_f32 v3, vcc, 1.0, v27, 1.0
	v_mul_f32_e32 v30, v3, v29
	v_fma_f32 v31, -v28, v30, v3
	v_fmac_f32_e32 v30, v31, v29
	v_fma_f32 v3, -v28, v30, v3
	v_div_fmas_f32 v3, v3, v29, v30
	v_div_fixup_f32 v3, v3, v27, 1.0
	v_mul_f32_e32 v27, 0xbfb8aa3b, v154
	v_exp_f32_e32 v28, v27
	v_or_b32_e32 v26, 19, v2
	v_ashrrev_i32_e32 v27, 31, v26
	v_lshlrev_b64 v[26:27], 13, v[26:27]
	v_add_f32_e32 v29, 1.0, v28
	v_div_scale_f32 v30, s[8:9], v29, v29, 1.0
	v_rcp_f32_e32 v31, v30
	v_lshl_add_u64 v[26:27], v[0:1], 0, v[26:27]
	v_add_co_u32_e32 v26, vcc, s10, v26
	v_cvt_pk_bf16_f32 v3, v3, s0
	s_nop 0
	v_addc_co_u32_e32 v27, vcc, -1, v27, vcc
	global_store_short v[26:27], v3, off offset:-1408
	v_fma_f32 v3, -v30, v31, 1.0
	v_fmac_f32_e32 v31, v3, v31
	v_div_scale_f32 v3, vcc, 1.0, v29, 1.0
	v_mul_f32_e32 v32, v3, v31
	v_fma_f32 v33, -v30, v32, v3
	v_fmac_f32_e32 v32, v33, v31
	v_fma_f32 v3, -v30, v32, v3
	v_div_fmas_f32 v3, v3, v31, v32
	v_div_fixup_f32 v3, v3, v29, 1.0
	v_mul_f32_e32 v29, 0xbfb8aa3b, v153
	v_exp_f32_e32 v30, v29
	v_or_b32_e32 v28, 24, v2
	v_ashrrev_i32_e32 v29, 31, v28
	v_lshlrev_b64 v[28:29], 13, v[28:29]
	v_add_f32_e32 v31, 1.0, v30
	v_div_scale_f32 v32, s[8:9], v31, v31, 1.0
	v_rcp_f32_e32 v33, v32
	v_lshl_add_u64 v[28:29], v[0:1], 0, v[28:29]
	v_add_co_u32_e32 v28, vcc, s10, v28
	v_cvt_pk_bf16_f32 v3, v3, s0
	s_nop 0
	v_addc_co_u32_e32 v29, vcc, -1, v29, vcc
	global_store_short v[28:29], v3, off offset:-1408
	v_fma_f32 v3, -v32, v33, 1.0
	v_fmac_f32_e32 v33, v3, v33
	v_div_scale_f32 v3, vcc, 1.0, v31, 1.0
	v_mul_f32_e32 v34, v3, v33
	v_fma_f32 v35, -v32, v34, v3
	v_fmac_f32_e32 v34, v35, v33
	v_fma_f32 v3, -v32, v34, v3
	v_div_fmas_f32 v3, v3, v33, v34
	v_div_fixup_f32 v3, v3, v31, 1.0
	v_mul_f32_e32 v31, 0xbfb8aa3b, v152
	v_exp_f32_e32 v32, v31
	v_or_b32_e32 v30, 25, v2
	v_ashrrev_i32_e32 v31, 31, v30
	v_lshlrev_b64 v[30:31], 13, v[30:31]
	v_add_f32_e32 v33, 1.0, v32
	v_div_scale_f32 v34, s[8:9], v33, v33, 1.0
	v_rcp_f32_e32 v35, v34
	v_lshl_add_u64 v[30:31], v[0:1], 0, v[30:31]
	v_add_co_u32_e32 v30, vcc, s10, v30
	v_cvt_pk_bf16_f32 v3, v3, s0
	s_nop 0
	v_addc_co_u32_e32 v31, vcc, -1, v31, vcc
	global_store_short v[30:31], v3, off offset:-1408
	v_fma_f32 v3, -v34, v35, 1.0
	v_fmac_f32_e32 v35, v3, v35
	v_div_scale_f32 v3, vcc, 1.0, v33, 1.0
	v_mul_f32_e32 v36, v3, v35
	v_fma_f32 v37, -v34, v36, v3
	v_fmac_f32_e32 v36, v37, v35
	v_fma_f32 v3, -v34, v36, v3
	v_div_fmas_f32 v3, v3, v35, v36
	v_div_fixup_f32 v3, v3, v33, 1.0
	v_mul_f32_e32 v33, 0xbfb8aa3b, v103
; DI float sigmoidf_(float v) { return 1.f / (1.f + __expf(-v)); }
; DI void phase_in(const Params& p, int L, char* smem) {
;     ...
;     if (cb >= 43) {
;       if (cb < 107) {
;         EPI_BEGINM(acc, 4) p.gates[(size_t)row * 4096 + (col - 2752)] = f2bf(sigmoidf_(v)); EPI_END
	v_exp_f32_e32 v34, v33
	v_or_b32_e32 v32, 26, v2
	v_ashrrev_i32_e32 v33, 31, v32
	v_lshlrev_b64 v[32:33], 13, v[32:33]
	v_add_f32_e32 v35, 1.0, v34
	v_div_scale_f32 v36, s[8:9], v35, v35, 1.0
	v_rcp_f32_e32 v37, v36
	v_lshl_add_u64 v[32:33], v[0:1], 0, v[32:33]
	v_add_co_u32_e32 v32, vcc, s10, v32
	v_cvt_pk_bf16_f32 v3, v3, s0
	s_nop 0
	v_addc_co_u32_e32 v33, vcc, -1, v33, vcc
	global_store_short v[32:33], v3, off offset:-1408
	v_fma_f32 v3, -v36, v37, 1.0
	v_fmac_f32_e32 v37, v3, v37
	v_div_scale_f32 v3, vcc, 1.0, v35, 1.0
	v_mul_f32_e32 v99, v3, v37
	v_fma_f32 v103, -v36, v99, v3
	v_fmac_f32_e32 v99, v103, v37
	v_fma_f32 v3, -v36, v99, v3
	v_div_fmas_f32 v3, v3, v37, v99
	v_div_fixup_f32 v3, v3, v35, 1.0
	v_mul_f32_e32 v35, 0xbfb8aa3b, v151
	v_exp_f32_e32 v36, v35
	v_or_b32_e32 v34, 27, v2
	v_ashrrev_i32_e32 v35, 31, v34
	v_lshlrev_b64 v[34:35], 13, v[34:35]
	v_add_f32_e32 v36, 1.0, v36
	v_div_scale_f32 v37, s[8:9], v36, v36, 1.0
	v_rcp_f32_e32 v99, v37
	v_lshl_add_u64 v[34:35], v[0:1], 0, v[34:35]
	v_add_co_u32_e32 v34, vcc, s10, v34
	v_cvt_pk_bf16_f32 v3, v3, s0
	s_nop 0
	v_addc_co_u32_e32 v35, vcc, -1, v35, vcc
	global_store_short v[34:35], v3, off offset:-1408
	v_fma_f32 v3, -v37, v99, 1.0
	v_fmac_f32_e32 v99, v3, v99
	v_div_scale_f32 v3, vcc, 1.0, v36, 1.0
	v_mul_f32_e32 v103, v3, v99
	v_fma_f32 v151, -v37, v103, v3
	v_fmac_f32_e32 v103, v151, v99
	v_fma_f32 v3, -v37, v103, v3
	v_add_f32_e32 v37, 1.0, v150
	v_div_fmas_f32 v3, v3, v99, v103
	v_div_scale_f32 v99, s[8:9], v37, v37, 1.0
	v_rcp_f32_e32 v103, v99
	v_div_fixup_f32 v3, v3, v36, 1.0
	v_cvt_pk_bf16_f32 v3, v3, s0
	global_store_short v[4:5], v3, off offset:-1344
	v_fma_f32 v3, -v99, v103, 1.0
	v_fmac_f32_e32 v103, v3, v103
	v_div_scale_f32 v3, vcc, 1.0, v37, 1.0
	v_mul_f32_e32 v4, v3, v103
	v_fma_f32 v5, -v99, v4, v3
	v_fmac_f32_e32 v4, v5, v103
	v_mul_f32_e32 v5, 0xbfb8aa3b, v149
	v_exp_f32_e32 v5, v5
	v_fma_f32 v3, -v99, v4, v3
	v_div_fmas_f32 v3, v3, v103, v4
	v_div_fixup_f32 v3, v3, v37, 1.0
	v_add_f32_e32 v4, 1.0, v5
	v_div_scale_f32 v5, s[8:9], v4, v4, 1.0
	v_rcp_f32_e32 v36, v5
	v_cvt_pk_bf16_f32 v3, v3, s0
	global_store_short v[6:7], v3, off offset:-1344
	v_mul_f32_e32 v118, 0xbfb8aa3b, v118
	v_fma_f32 v3, -v5, v36, 1.0
	v_fmac_f32_e32 v36, v3, v36
	v_div_scale_f32 v3, vcc, 1.0, v4, 1.0
	v_mul_f32_e32 v6, v3, v36
	v_fma_f32 v7, -v5, v6, v3
	v_fmac_f32_e32 v6, v7, v36
	v_mul_f32_e32 v7, 0xbfb8aa3b, v148
	v_exp_f32_e32 v7, v7
	v_fma_f32 v3, -v5, v6, v3
	v_div_fmas_f32 v3, v3, v36, v6
	v_div_fixup_f32 v3, v3, v4, 1.0
	v_add_f32_e32 v5, 1.0, v7
	v_div_scale_f32 v6, s[8:9], v5, v5, 1.0
	v_rcp_f32_e32 v7, v6
	v_cvt_pk_bf16_f32 v3, v3, s0
	global_store_short v[8:9], v3, off offset:-1344
	v_exp_f32_e32 v118, v118
	v_fma_f32 v3, -v6, v7, 1.0
	v_fmac_f32_e32 v7, v3, v7
	v_div_scale_f32 v3, vcc, 1.0, v5, 1.0
	v_mul_f32_e32 v4, v3, v7
	v_fma_f32 v8, -v6, v4, v3
	v_fmac_f32_e32 v4, v8, v7
	v_mul_f32_e32 v8, 0xbfb8aa3b, v147
	v_exp_f32_e32 v8, v8
	v_fma_f32 v3, -v6, v4, v3
	v_div_fmas_f32 v3, v3, v7, v4
	v_div_fixup_f32 v3, v3, v5, 1.0
	v_add_f32_e32 v4, 1.0, v8
	v_div_scale_f32 v6, s[8:9], v4, v4, 1.0
	v_rcp_f32_e32 v7, v6
	v_cvt_pk_bf16_f32 v3, v3, s0
	global_store_short v[10:11], v3, off offset:-1344
	v_mul_f32_e32 v84, 0xbfb8aa3b, v84
	v_fma_f32 v3, -v6, v7, 1.0
	v_fmac_f32_e32 v7, v3, v7
	v_div_scale_f32 v3, vcc, 1.0, v4, 1.0
	v_mul_f32_e32 v5, v3, v7
	v_fma_f32 v8, -v6, v5, v3
	v_fmac_f32_e32 v5, v8, v7
	v_mul_f32_e32 v8, 0xbfb8aa3b, v146
	v_exp_f32_e32 v8, v8
	v_fma_f32 v3, -v6, v5, v3
	v_div_fmas_f32 v3, v3, v7, v5
	v_div_fixup_f32 v3, v3, v4, 1.0
	v_add_f32_e32 v5, 1.0, v8
	v_div_scale_f32 v6, s[8:9], v5, v5, 1.0
	v_rcp_f32_e32 v7, v6
	v_cvt_pk_bf16_f32 v3, v3, s0
	global_store_short v[12:13], v3, off offset:-1344
	v_exp_f32_e32 v84, v84
	v_fma_f32 v3, -v6, v7, 1.0
	v_fmac_f32_e32 v7, v3, v7
	v_div_scale_f32 v3, vcc, 1.0, v5, 1.0
	v_mul_f32_e32 v4, v3, v7
	v_fma_f32 v8, -v6, v4, v3
	v_fmac_f32_e32 v4, v8, v7
	v_mul_f32_e32 v8, 0xbfb8aa3b, v145
	v_exp_f32_e32 v8, v8
	v_fma_f32 v3, -v6, v4, v3
	v_div_fmas_f32 v3, v3, v7, v4
	v_div_fixup_f32 v3, v3, v5, 1.0
	v_add_f32_e32 v4, 1.0, v8
	v_div_scale_f32 v6, s[8:9], v4, v4, 1.0
	v_rcp_f32_e32 v7, v6
	v_cvt_pk_bf16_f32 v3, v3, s0
	global_store_short v[14:15], v3, off offset:-1344
	v_fma_f32 v3, -v6, v7, 1.0
	v_fmac_f32_e32 v7, v3, v7
	v_div_scale_f32 v3, vcc, 1.0, v4, 1.0
	v_mul_f32_e32 v5, v3, v7
	v_fma_f32 v8, -v6, v5, v3
	v_fmac_f32_e32 v5, v8, v7
	v_mul_f32_e32 v8, 0xbfb8aa3b, v144
	v_exp_f32_e32 v8, v8
	v_fma_f32 v3, -v6, v5, v3
	v_div_fmas_f32 v3, v3, v7, v5
	v_div_fixup_f32 v3, v3, v4, 1.0
	v_add_f32_e32 v5, 1.0, v8
	v_div_scale_f32 v6, s[8:9], v5, v5, 1.0
	v_rcp_f32_e32 v7, v6
	v_cvt_pk_bf16_f32 v3, v3, s0
	global_store_short v[16:17], v3, off offset:-1344
	v_fma_f32 v3, -v6, v7, 1.0
	v_fmac_f32_e32 v7, v3, v7
	v_div_scale_f32 v3, vcc, 1.0, v5, 1.0
	v_mul_f32_e32 v4, v3, v7
	v_fma_f32 v8, -v6, v4, v3
	v_fmac_f32_e32 v4, v8, v7
	v_mul_f32_e32 v8, 0xbfb8aa3b, v143
	v_exp_f32_e32 v8, v8
	v_fma_f32 v3, -v6, v4, v3
	v_div_fmas_f32 v3, v3, v7, v4
	v_div_fixup_f32 v3, v3, v5, 1.0
	v_add_f32_e32 v4, 1.0, v8
	v_div_scale_f32 v6, s[8:9], v4, v4, 1.0
	v_rcp_f32_e32 v7, v6
	v_cvt_pk_bf16_f32 v3, v3, s0
	global_store_short v[18:19], v3, off offset:-1344
	v_fma_f32 v3, -v6, v7, 1.0
	v_fmac_f32_e32 v7, v3, v7
	v_div_scale_f32 v3, vcc, 1.0, v4, 1.0
	v_mul_f32_e32 v5, v3, v7
	v_fma_f32 v8, -v6, v5, v3
	v_fmac_f32_e32 v5, v8, v7
	v_mul_f32_e32 v8, 0xbfb8aa3b, v142
	v_exp_f32_e32 v8, v8
	v_fma_f32 v3, -v6, v5, v3
	v_div_fmas_f32 v3, v3, v7, v5
	v_div_fixup_f32 v3, v3, v4, 1.0
	v_add_f32_e32 v5, 1.0, v8
	v_div_scale_f32 v6, s[8:9], v5, v5, 1.0
; DI float sigmoidf_(float v) { return 1.f / (1.f + __expf(-v)); }
; DI void phase_in(const Params& p, int L, char* smem) {
;     ...
;     if (cb >= 43) {
;       if (cb < 107) {
;         EPI_BEGINM(acc, 4) p.gates[(size_t)row * 4096 + (col - 2752)] = f2bf(sigmoidf_(v)); EPI_END
	v_rcp_f32_e32 v7, v6
	v_cvt_pk_bf16_f32 v3, v3, s0
	global_store_short v[20:21], v3, off offset:-1344
	v_fma_f32 v3, -v6, v7, 1.0
	v_fmac_f32_e32 v7, v3, v7
	v_div_scale_f32 v3, vcc, 1.0, v5, 1.0
	v_mul_f32_e32 v4, v3, v7
	v_fma_f32 v8, -v6, v4, v3
	v_fmac_f32_e32 v4, v8, v7
	v_mul_f32_e32 v8, 0xbfb8aa3b, v141
	v_exp_f32_e32 v8, v8
	v_fma_f32 v3, -v6, v4, v3
	v_div_fmas_f32 v3, v3, v7, v4
	v_div_fixup_f32 v3, v3, v5, 1.0
	v_add_f32_e32 v4, 1.0, v8
	v_div_scale_f32 v6, s[8:9], v4, v4, 1.0
	v_rcp_f32_e32 v7, v6
	v_cvt_pk_bf16_f32 v3, v3, s0
	global_store_short v[22:23], v3, off offset:-1344
	v_fma_f32 v3, -v6, v7, 1.0
	v_fmac_f32_e32 v7, v3, v7
	v_div_scale_f32 v3, vcc, 1.0, v4, 1.0
	v_mul_f32_e32 v5, v3, v7
	v_fma_f32 v8, -v6, v5, v3
	v_fmac_f32_e32 v5, v8, v7
	v_mul_f32_e32 v8, 0xbfb8aa3b, v140
	v_exp_f32_e32 v8, v8
	v_fma_f32 v3, -v6, v5, v3
	v_div_fmas_f32 v3, v3, v7, v5
	v_div_fixup_f32 v3, v3, v4, 1.0
	v_add_f32_e32 v5, 1.0, v8
	v_div_scale_f32 v6, s[8:9], v5, v5, 1.0
	v_rcp_f32_e32 v7, v6
	v_cvt_pk_bf16_f32 v3, v3, s0
	global_store_short v[24:25], v3, off offset:-1344
	v_fma_f32 v3, -v6, v7, 1.0
	v_fmac_f32_e32 v7, v3, v7
	v_div_scale_f32 v3, vcc, 1.0, v5, 1.0
	v_mul_f32_e32 v4, v3, v7
	v_fma_f32 v8, -v6, v4, v3
	v_fmac_f32_e32 v4, v8, v7
	v_mul_f32_e32 v8, 0xbfb8aa3b, v139
	v_exp_f32_e32 v8, v8
	v_fma_f32 v3, -v6, v4, v3
	v_div_fmas_f32 v3, v3, v7, v4
	v_div_fixup_f32 v3, v3, v5, 1.0
	v_add_f32_e32 v4, 1.0, v8
	v_div_scale_f32 v6, s[8:9], v4, v4, 1.0
	v_rcp_f32_e32 v7, v6
	v_cvt_pk_bf16_f32 v3, v3, s0
	global_store_short v[26:27], v3, off offset:-1344
	v_fma_f32 v3, -v6, v7, 1.0
	v_fmac_f32_e32 v7, v3, v7
	v_div_scale_f32 v3, vcc, 1.0, v4, 1.0
	v_mul_f32_e32 v5, v3, v7
	v_fma_f32 v8, -v6, v5, v3
	v_fmac_f32_e32 v5, v8, v7
	v_mul_f32_e32 v8, 0xbfb8aa3b, v138
	v_exp_f32_e32 v8, v8
	v_fma_f32 v3, -v6, v5, v3
	v_div_fmas_f32 v3, v3, v7, v5
	v_div_fixup_f32 v3, v3, v4, 1.0
	v_add_f32_e32 v5, 1.0, v8
	v_div_scale_f32 v6, s[8:9], v5, v5, 1.0
	v_rcp_f32_e32 v7, v6
	v_cvt_pk_bf16_f32 v3, v3, s0
	global_store_short v[28:29], v3, off offset:-1344
	v_fma_f32 v3, -v6, v7, 1.0
	v_fmac_f32_e32 v7, v3, v7
	v_div_scale_f32 v3, vcc, 1.0, v5, 1.0
	v_mul_f32_e32 v4, v3, v7
	v_fma_f32 v8, -v6, v4, v3
	v_fmac_f32_e32 v4, v8, v7
	v_mul_f32_e32 v8, 0xbfb8aa3b, v137
	v_exp_f32_e32 v8, v8
	v_fma_f32 v3, -v6, v4, v3
	v_div_fmas_f32 v3, v3, v7, v4
	v_div_fixup_f32 v3, v3, v5, 1.0
	v_add_f32_e32 v4, 1.0, v8
	v_div_scale_f32 v6, s[8:9], v4, v4, 1.0
	v_rcp_f32_e32 v7, v6
	v_cvt_pk_bf16_f32 v3, v3, s0
	global_store_short v[30:31], v3, off offset:-1344
	v_fma_f32 v3, -v6, v7, 1.0
	v_fmac_f32_e32 v7, v3, v7
	v_div_scale_f32 v3, vcc, 1.0, v4, 1.0
	v_mul_f32_e32 v5, v3, v7
	v_fma_f32 v8, -v6, v5, v3
	v_fmac_f32_e32 v5, v8, v7
	v_mul_f32_e32 v8, 0xbfb8aa3b, v136
	v_exp_f32_e32 v8, v8
	v_fma_f32 v3, -v6, v5, v3
	v_div_fmas_f32 v3, v3, v7, v5
	v_div_fixup_f32 v3, v3, v4, 1.0
	v_add_f32_e32 v5, 1.0, v8
	v_div_scale_f32 v6, s[8:9], v5, v5, 1.0
	v_rcp_f32_e32 v7, v6
	v_cvt_pk_bf16_f32 v3, v3, s0
	global_store_short v[32:33], v3, off offset:-1344
	v_fma_f32 v3, -v6, v7, 1.0
	v_fmac_f32_e32 v7, v3, v7
	v_div_scale_f32 v3, vcc, 1.0, v5, 1.0
	v_mul_f32_e32 v4, v3, v7
	v_fma_f32 v8, -v6, v4, v3
	v_fmac_f32_e32 v4, v8, v7
	v_fma_f32 v3, -v6, v4, v3
	v_mul_f32_e32 v6, 0xbfb8aa3b, v135
	v_exp_f32_e32 v6, v6
	v_div_fmas_f32 v3, v3, v7, v4
	v_div_fixup_f32 v3, v3, v5, 1.0
	v_cvt_pk_bf16_f32 v3, v3, s0
	v_add_f32_e32 v5, 1.0, v6
	v_div_scale_f32 v6, s[8:9], v5, v5, 1.0
	v_rcp_f32_e32 v7, v6
	global_store_short v[34:35], v3, off offset:-1344
	v_or_b32_e32 v4, 32, v2
	v_fma_f32 v3, -v6, v7, 1.0
	v_fmac_f32_e32 v7, v3, v7
	v_div_scale_f32 v3, vcc, 1.0, v5, 1.0
	v_mul_f32_e32 v8, v3, v7
	v_fma_f32 v9, -v6, v8, v3
	v_fmac_f32_e32 v8, v9, v7
	v_fma_f32 v3, -v6, v8, v3
	v_div_fmas_f32 v3, v3, v7, v8
	v_div_fixup_f32 v3, v3, v5, 1.0
	v_mul_f32_e32 v5, 0xbfb8aa3b, v134
	v_exp_f32_e32 v6, v5
	v_ashrrev_i32_e32 v5, 31, v4
	v_lshlrev_b64 v[4:5], 13, v[4:5]
	v_lshl_add_u64 v[4:5], v[0:1], 0, v[4:5]
	v_add_f32_e32 v7, 1.0, v6
	v_div_scale_f32 v8, s[8:9], v7, v7, 1.0
	v_rcp_f32_e32 v9, v8
	v_add_co_u32_e32 v4, vcc, s10, v4
	v_cvt_pk_bf16_f32 v3, v3, s0
	s_nop 0
	v_addc_co_u32_e32 v5, vcc, -1, v5, vcc
	global_store_short v[4:5], v3, off offset:-1408
	v_fma_f32 v3, -v8, v9, 1.0
	v_fmac_f32_e32 v9, v3, v9
	v_div_scale_f32 v3, vcc, 1.0, v7, 1.0
	v_mul_f32_e32 v10, v3, v9
	v_fma_f32 v11, -v8, v10, v3
	v_fmac_f32_e32 v10, v11, v9
	v_fma_f32 v3, -v8, v10, v3
	v_div_fmas_f32 v3, v3, v9, v10
	v_div_fixup_f32 v3, v3, v7, 1.0
	v_mul_f32_e32 v7, 0xbfb8aa3b, v133
	v_exp_f32_e32 v8, v7
	v_or_b32_e32 v6, 33, v2
	v_ashrrev_i32_e32 v7, 31, v6
	v_lshlrev_b64 v[6:7], 13, v[6:7]
	v_add_f32_e32 v9, 1.0, v8
	v_div_scale_f32 v10, s[8:9], v9, v9, 1.0
	v_rcp_f32_e32 v11, v10
	v_lshl_add_u64 v[6:7], v[0:1], 0, v[6:7]
	v_add_co_u32_e32 v6, vcc, s10, v6
	v_cvt_pk_bf16_f32 v3, v3, s0
	s_nop 0
	v_addc_co_u32_e32 v7, vcc, -1, v7, vcc
	global_store_short v[6:7], v3, off offset:-1408
	v_fma_f32 v3, -v10, v11, 1.0
	v_fmac_f32_e32 v11, v3, v11
	v_div_scale_f32 v3, vcc, 1.0, v9, 1.0
	v_mul_f32_e32 v12, v3, v11
	v_fma_f32 v13, -v10, v12, v3
	v_fmac_f32_e32 v12, v13, v11
	v_fma_f32 v3, -v10, v12, v3
	v_div_fmas_f32 v3, v3, v11, v12
	v_div_fixup_f32 v3, v3, v9, 1.0
	v_mul_f32_e32 v9, 0xbfb8aa3b, v132
	v_exp_f32_e32 v10, v9
	v_or_b32_e32 v8, 34, v2
	v_ashrrev_i32_e32 v9, 31, v8
	v_lshlrev_b64 v[8:9], 13, v[8:9]
	v_add_f32_e32 v11, 1.0, v10
	v_div_scale_f32 v12, s[8:9], v11, v11, 1.0
	v_rcp_f32_e32 v13, v12
	v_lshl_add_u64 v[8:9], v[0:1], 0, v[8:9]
	v_add_co_u32_e32 v8, vcc, s10, v8
	v_cvt_pk_bf16_f32 v3, v3, s0
	s_nop 0
; DI float sigmoidf_(float v) { return 1.f / (1.f + __expf(-v)); }
; DI void phase_in(const Params& p, int L, char* smem) {
;     ...
;     if (cb >= 43) {
;       if (cb < 107) {
;         EPI_BEGINM(acc, 4) p.gates[(size_t)row * 4096 + (col - 2752)] = f2bf(sigmoidf_(v)); EPI_END
	v_addc_co_u32_e32 v9, vcc, -1, v9, vcc
	global_store_short v[8:9], v3, off offset:-1408
	v_fma_f32 v3, -v12, v13, 1.0
	v_fmac_f32_e32 v13, v3, v13
	v_div_scale_f32 v3, vcc, 1.0, v11, 1.0
	v_mul_f32_e32 v14, v3, v13
	v_fma_f32 v15, -v12, v14, v3
	v_fmac_f32_e32 v14, v15, v13
	v_fma_f32 v3, -v12, v14, v3
	v_div_fmas_f32 v3, v3, v13, v14
	v_div_fixup_f32 v3, v3, v11, 1.0
	v_mul_f32_e32 v11, 0xbfb8aa3b, v131
	v_exp_f32_e32 v12, v11
	v_or_b32_e32 v10, 35, v2
	v_ashrrev_i32_e32 v11, 31, v10
	v_lshlrev_b64 v[10:11], 13, v[10:11]
	v_add_f32_e32 v13, 1.0, v12
	v_div_scale_f32 v14, s[8:9], v13, v13, 1.0
	v_rcp_f32_e32 v15, v14
	v_lshl_add_u64 v[10:11], v[0:1], 0, v[10:11]
	v_add_co_u32_e32 v10, vcc, s10, v10
	v_cvt_pk_bf16_f32 v3, v3, s0
	s_nop 0
	v_addc_co_u32_e32 v11, vcc, -1, v11, vcc
	global_store_short v[10:11], v3, off offset:-1408
	v_fma_f32 v3, -v14, v15, 1.0
	v_fmac_f32_e32 v15, v3, v15
	v_div_scale_f32 v3, vcc, 1.0, v13, 1.0
	v_mul_f32_e32 v16, v3, v15
	v_fma_f32 v17, -v14, v16, v3
	v_fmac_f32_e32 v16, v17, v15
	v_fma_f32 v3, -v14, v16, v3
	v_div_fmas_f32 v3, v3, v15, v16
	v_div_fixup_f32 v3, v3, v13, 1.0
	v_mul_f32_e32 v13, 0xbfb8aa3b, v130
	v_exp_f32_e32 v14, v13
	v_or_b32_e32 v12, 40, v2
	v_ashrrev_i32_e32 v13, 31, v12
	v_lshlrev_b64 v[12:13], 13, v[12:13]
	v_add_f32_e32 v15, 1.0, v14
	v_div_scale_f32 v16, s[8:9], v15, v15, 1.0
	v_rcp_f32_e32 v17, v16
	v_lshl_add_u64 v[12:13], v[0:1], 0, v[12:13]
	v_add_co_u32_e32 v12, vcc, s10, v12
	v_cvt_pk_bf16_f32 v3, v3, s0
	s_nop 0
	v_addc_co_u32_e32 v13, vcc, -1, v13, vcc
	global_store_short v[12:13], v3, off offset:-1408
	v_fma_f32 v3, -v16, v17, 1.0
	v_fmac_f32_e32 v17, v3, v17
	v_div_scale_f32 v3, vcc, 1.0, v15, 1.0
	v_mul_f32_e32 v18, v3, v17
	v_fma_f32 v19, -v16, v18, v3
	v_fmac_f32_e32 v18, v19, v17
	v_fma_f32 v3, -v16, v18, v3
	v_div_fmas_f32 v3, v3, v17, v18
	v_div_fixup_f32 v3, v3, v15, 1.0
	v_mul_f32_e32 v15, 0xbfb8aa3b, v129
	v_exp_f32_e32 v16, v15
	v_or_b32_e32 v14, 41, v2
	v_ashrrev_i32_e32 v15, 31, v14
	v_lshlrev_b64 v[14:15], 13, v[14:15]
	v_add_f32_e32 v17, 1.0, v16
	v_div_scale_f32 v18, s[8:9], v17, v17, 1.0
	v_rcp_f32_e32 v19, v18
	v_lshl_add_u64 v[14:15], v[0:1], 0, v[14:15]
	v_add_co_u32_e32 v14, vcc, s10, v14
	v_cvt_pk_bf16_f32 v3, v3, s0
	s_nop 0
	v_addc_co_u32_e32 v15, vcc, -1, v15, vcc
	global_store_short v[14:15], v3, off offset:-1408
	v_fma_f32 v3, -v18, v19, 1.0
	v_fmac_f32_e32 v19, v3, v19
	v_div_scale_f32 v3, vcc, 1.0, v17, 1.0
	v_mul_f32_e32 v20, v3, v19
	v_fma_f32 v21, -v18, v20, v3
	v_fmac_f32_e32 v20, v21, v19
	v_fma_f32 v3, -v18, v20, v3
	v_div_fmas_f32 v3, v3, v19, v20
	v_div_fixup_f32 v3, v3, v17, 1.0
	v_mul_f32_e32 v17, 0xbfb8aa3b, v128
	v_exp_f32_e32 v18, v17
	v_or_b32_e32 v16, 42, v2
	v_ashrrev_i32_e32 v17, 31, v16
	v_lshlrev_b64 v[16:17], 13, v[16:17]
	v_add_f32_e32 v19, 1.0, v18
	v_div_scale_f32 v20, s[8:9], v19, v19, 1.0
	v_rcp_f32_e32 v21, v20
	v_lshl_add_u64 v[16:17], v[0:1], 0, v[16:17]
	v_add_co_u32_e32 v16, vcc, s10, v16
	v_cvt_pk_bf16_f32 v3, v3, s0
	s_nop 0
	v_addc_co_u32_e32 v17, vcc, -1, v17, vcc
	global_store_short v[16:17], v3, off offset:-1408
	v_fma_f32 v3, -v20, v21, 1.0
	v_fmac_f32_e32 v21, v3, v21
	v_div_scale_f32 v3, vcc, 1.0, v19, 1.0
	v_mul_f32_e32 v22, v3, v21
	v_fma_f32 v23, -v20, v22, v3
	v_fmac_f32_e32 v22, v23, v21
	v_fma_f32 v3, -v20, v22, v3
	v_div_fmas_f32 v3, v3, v21, v22
	v_div_fixup_f32 v3, v3, v19, 1.0
	v_mul_f32_e32 v19, 0xbfb8aa3b, v127
	v_exp_f32_e32 v20, v19
	v_or_b32_e32 v18, 43, v2
	v_ashrrev_i32_e32 v19, 31, v18
	v_lshlrev_b64 v[18:19], 13, v[18:19]
	v_add_f32_e32 v21, 1.0, v20
	v_div_scale_f32 v22, s[8:9], v21, v21, 1.0
	v_rcp_f32_e32 v23, v22
	v_lshl_add_u64 v[18:19], v[0:1], 0, v[18:19]
	v_add_co_u32_e32 v18, vcc, s10, v18
	v_cvt_pk_bf16_f32 v3, v3, s0
	s_nop 0
	v_addc_co_u32_e32 v19, vcc, -1, v19, vcc
	global_store_short v[18:19], v3, off offset:-1408
	v_fma_f32 v3, -v22, v23, 1.0
	v_fmac_f32_e32 v23, v3, v23
	v_div_scale_f32 v3, vcc, 1.0, v21, 1.0
	v_mul_f32_e32 v24, v3, v23
	v_fma_f32 v25, -v22, v24, v3
	v_fmac_f32_e32 v24, v25, v23
	v_fma_f32 v3, -v22, v24, v3
	v_div_fmas_f32 v3, v3, v23, v24
	v_div_fixup_f32 v3, v3, v21, 1.0
	v_mul_f32_e32 v21, 0xbfb8aa3b, v126
	v_exp_f32_e32 v22, v21
	v_or_b32_e32 v20, 48, v2
	v_ashrrev_i32_e32 v21, 31, v20
	v_lshlrev_b64 v[20:21], 13, v[20:21]
	v_add_f32_e32 v23, 1.0, v22
	v_div_scale_f32 v24, s[8:9], v23, v23, 1.0
	v_rcp_f32_e32 v25, v24
	v_lshl_add_u64 v[20:21], v[0:1], 0, v[20:21]
	v_add_co_u32_e32 v20, vcc, s10, v20
	v_cvt_pk_bf16_f32 v3, v3, s0
	s_nop 0
	v_addc_co_u32_e32 v21, vcc, -1, v21, vcc
	global_store_short v[20:21], v3, off offset:-1408
	v_fma_f32 v3, -v24, v25, 1.0
	v_fmac_f32_e32 v25, v3, v25
	v_div_scale_f32 v3, vcc, 1.0, v23, 1.0
	v_mul_f32_e32 v26, v3, v25
	v_fma_f32 v27, -v24, v26, v3
	v_fmac_f32_e32 v26, v27, v25
	v_fma_f32 v3, -v24, v26, v3
	v_div_fmas_f32 v3, v3, v25, v26
	v_div_fixup_f32 v3, v3, v23, 1.0
	v_mul_f32_e32 v23, 0xbfb8aa3b, v125
	v_exp_f32_e32 v24, v23
	v_or_b32_e32 v22, 49, v2
	v_ashrrev_i32_e32 v23, 31, v22
	v_lshlrev_b64 v[22:23], 13, v[22:23]
	v_add_f32_e32 v25, 1.0, v24
	v_div_scale_f32 v26, s[8:9], v25, v25, 1.0
	v_rcp_f32_e32 v27, v26
	v_lshl_add_u64 v[22:23], v[0:1], 0, v[22:23]
	v_add_co_u32_e32 v22, vcc, s10, v22
	v_cvt_pk_bf16_f32 v3, v3, s0
	s_nop 0
	v_addc_co_u32_e32 v23, vcc, -1, v23, vcc
	global_store_short v[22:23], v3, off offset:-1408
	v_fma_f32 v3, -v26, v27, 1.0
	v_fmac_f32_e32 v27, v3, v27
	v_div_scale_f32 v3, vcc, 1.0, v25, 1.0
	v_mul_f32_e32 v28, v3, v27
	v_fma_f32 v29, -v26, v28, v3
	v_fmac_f32_e32 v28, v29, v27
	v_fma_f32 v3, -v26, v28, v3
	v_div_fmas_f32 v3, v3, v27, v28
	v_div_fixup_f32 v3, v3, v25, 1.0
; DI float sigmoidf_(float v) { return 1.f / (1.f + __expf(-v)); }
; DI void phase_in(const Params& p, int L, char* smem) {
;     ...
;     if (cb >= 43) {
;       if (cb < 107) {
;         EPI_BEGINM(acc, 4) p.gates[(size_t)row * 4096 + (col - 2752)] = f2bf(sigmoidf_(v)); EPI_END
	v_mul_f32_e32 v25, 0xbfb8aa3b, v124
	v_exp_f32_e32 v26, v25
	v_or_b32_e32 v24, 50, v2
	v_ashrrev_i32_e32 v25, 31, v24
	v_lshlrev_b64 v[24:25], 13, v[24:25]
	v_add_f32_e32 v27, 1.0, v26
	v_div_scale_f32 v28, s[8:9], v27, v27, 1.0
	v_rcp_f32_e32 v29, v28
	v_lshl_add_u64 v[24:25], v[0:1], 0, v[24:25]
	v_add_co_u32_e32 v24, vcc, s10, v24
	v_cvt_pk_bf16_f32 v3, v3, s0
	s_nop 0
	v_addc_co_u32_e32 v25, vcc, -1, v25, vcc
	global_store_short v[24:25], v3, off offset:-1408
	v_fma_f32 v3, -v28, v29, 1.0
	v_fmac_f32_e32 v29, v3, v29
	v_div_scale_f32 v3, vcc, 1.0, v27, 1.0
	v_mul_f32_e32 v30, v3, v29
	v_fma_f32 v31, -v28, v30, v3
	v_fmac_f32_e32 v30, v31, v29
	v_fma_f32 v3, -v28, v30, v3
	v_div_fmas_f32 v3, v3, v29, v30
	v_div_fixup_f32 v3, v3, v27, 1.0
	v_mul_f32_e32 v27, 0xbfb8aa3b, v123
	v_exp_f32_e32 v28, v27
	v_or_b32_e32 v26, 51, v2
	v_ashrrev_i32_e32 v27, 31, v26
	v_lshlrev_b64 v[26:27], 13, v[26:27]
	v_add_f32_e32 v29, 1.0, v28
	v_div_scale_f32 v30, s[8:9], v29, v29, 1.0
	v_rcp_f32_e32 v31, v30
	v_lshl_add_u64 v[26:27], v[0:1], 0, v[26:27]
	v_add_co_u32_e32 v26, vcc, s10, v26
	v_cvt_pk_bf16_f32 v3, v3, s0
	s_nop 0
	v_addc_co_u32_e32 v27, vcc, -1, v27, vcc
	global_store_short v[26:27], v3, off offset:-1408
	v_fma_f32 v3, -v30, v31, 1.0
	v_fmac_f32_e32 v31, v3, v31
	v_div_scale_f32 v3, vcc, 1.0, v29, 1.0
	v_mul_f32_e32 v32, v3, v31
	v_fma_f32 v33, -v30, v32, v3
	v_fmac_f32_e32 v32, v33, v31
	v_fma_f32 v3, -v30, v32, v3
	v_div_fmas_f32 v3, v3, v31, v32
	v_div_fixup_f32 v3, v3, v29, 1.0
	v_mul_f32_e32 v29, 0xbfb8aa3b, v122
	v_exp_f32_e32 v30, v29
	v_or_b32_e32 v28, 56, v2
	v_ashrrev_i32_e32 v29, 31, v28
	v_lshlrev_b64 v[28:29], 13, v[28:29]
	v_add_f32_e32 v31, 1.0, v30
	v_div_scale_f32 v32, s[8:9], v31, v31, 1.0
	v_rcp_f32_e32 v33, v32
	v_lshl_add_u64 v[28:29], v[0:1], 0, v[28:29]
	v_add_co_u32_e32 v28, vcc, s10, v28
	v_cvt_pk_bf16_f32 v3, v3, s0
	s_nop 0
	v_addc_co_u32_e32 v29, vcc, -1, v29, vcc
	global_store_short v[28:29], v3, off offset:-1408
	v_fma_f32 v3, -v32, v33, 1.0
	v_fmac_f32_e32 v33, v3, v33
	v_div_scale_f32 v3, vcc, 1.0, v31, 1.0
	v_mul_f32_e32 v34, v3, v33
	v_fma_f32 v35, -v32, v34, v3
	v_fmac_f32_e32 v34, v35, v33
	v_fma_f32 v3, -v32, v34, v3
	v_div_fmas_f32 v3, v3, v33, v34
	v_div_fixup_f32 v3, v3, v31, 1.0
	v_mul_f32_e32 v31, 0xbfb8aa3b, v121
	v_exp_f32_e32 v32, v31
	v_or_b32_e32 v30, 57, v2
	v_ashrrev_i32_e32 v31, 31, v30
	v_lshlrev_b64 v[30:31], 13, v[30:31]
	v_add_f32_e32 v33, 1.0, v32
	v_div_scale_f32 v34, s[8:9], v33, v33, 1.0
	v_rcp_f32_e32 v35, v34
	v_lshl_add_u64 v[30:31], v[0:1], 0, v[30:31]
	v_add_co_u32_e32 v30, vcc, s10, v30
	v_cvt_pk_bf16_f32 v3, v3, s0
	s_nop 0
	v_addc_co_u32_e32 v31, vcc, -1, v31, vcc
	global_store_short v[30:31], v3, off offset:-1408
	v_fma_f32 v3, -v34, v35, 1.0
	v_fmac_f32_e32 v35, v3, v35
	v_div_scale_f32 v3, vcc, 1.0, v33, 1.0
	v_mul_f32_e32 v36, v3, v35
	v_fma_f32 v37, -v34, v36, v3
	v_fmac_f32_e32 v36, v37, v35
	v_fma_f32 v3, -v34, v36, v3
	v_div_fmas_f32 v3, v3, v35, v36
	v_div_fixup_f32 v3, v3, v33, 1.0
	v_mul_f32_e32 v33, 0xbfb8aa3b, v120
	v_exp_f32_e32 v34, v33
	v_or_b32_e32 v32, 58, v2
	v_ashrrev_i32_e32 v33, 31, v32
	v_lshlrev_b64 v[32:33], 13, v[32:33]
	v_add_f32_e32 v35, 1.0, v34
	v_div_scale_f32 v36, s[8:9], v35, v35, 1.0
	v_rcp_f32_e32 v37, v36
	v_lshl_add_u64 v[32:33], v[0:1], 0, v[32:33]
	v_add_co_u32_e32 v32, vcc, s10, v32
	v_cvt_pk_bf16_f32 v3, v3, s0
	s_nop 0
	v_addc_co_u32_e32 v33, vcc, -1, v33, vcc
	global_store_short v[32:33], v3, off offset:-1408
	v_fma_f32 v3, -v36, v37, 1.0
	v_fmac_f32_e32 v37, v3, v37
	v_div_scale_f32 v3, vcc, 1.0, v35, 1.0
	v_mul_f32_e32 v99, v3, v37
	v_fma_f32 v103, -v36, v99, v3
	v_fmac_f32_e32 v99, v103, v37
	v_fma_f32 v3, -v36, v99, v3
	v_div_fmas_f32 v3, v3, v37, v99
	v_div_fixup_f32 v3, v3, v35, 1.0
	v_mul_f32_e32 v35, 0xbfb8aa3b, v119
	v_exp_f32_e32 v36, v35
	v_or_b32_e32 v34, 59, v2
	v_ashrrev_i32_e32 v35, 31, v34
	v_lshlrev_b64 v[34:35], 13, v[34:35]
	v_add_f32_e32 v36, 1.0, v36
	v_div_scale_f32 v37, s[8:9], v36, v36, 1.0
	v_rcp_f32_e32 v99, v37
	v_lshl_add_u64 v[34:35], v[0:1], 0, v[34:35]
	v_add_co_u32_e32 v34, vcc, s10, v34
	v_cvt_pk_bf16_f32 v3, v3, s0
	s_nop 0
	v_addc_co_u32_e32 v35, vcc, -1, v35, vcc
	global_store_short v[34:35], v3, off offset:-1408
	v_fma_f32 v3, -v37, v99, 1.0
	v_fmac_f32_e32 v99, v3, v99
	v_div_scale_f32 v3, vcc, 1.0, v36, 1.0
	v_mul_f32_e32 v103, v3, v99
	v_fma_f32 v119, -v37, v103, v3
	v_fmac_f32_e32 v103, v119, v99
	v_fma_f32 v3, -v37, v103, v3
	v_add_f32_e32 v37, 1.0, v118
	v_div_fmas_f32 v3, v3, v99, v103
	v_div_scale_f32 v99, s[8:9], v37, v37, 1.0
	v_rcp_f32_e32 v103, v99
	v_div_fixup_f32 v3, v3, v36, 1.0
	v_cvt_pk_bf16_f32 v3, v3, s0
	global_store_short v[4:5], v3, off offset:-1344
	v_fma_f32 v3, -v99, v103, 1.0
	v_fmac_f32_e32 v103, v3, v103
	v_div_scale_f32 v3, vcc, 1.0, v37, 1.0
	v_mul_f32_e32 v4, v3, v103
	v_fma_f32 v5, -v99, v4, v3
	v_fmac_f32_e32 v4, v5, v103
	v_mul_f32_e32 v5, 0xbfb8aa3b, v117
	v_exp_f32_e32 v5, v5
	v_fma_f32 v3, -v99, v4, v3
	v_div_fmas_f32 v3, v3, v103, v4
	v_div_fixup_f32 v3, v3, v37, 1.0
	v_add_f32_e32 v4, 1.0, v5
	v_div_scale_f32 v5, s[8:9], v4, v4, 1.0
	v_rcp_f32_e32 v36, v5
	v_cvt_pk_bf16_f32 v3, v3, s0
	global_store_short v[6:7], v3, off offset:-1344
	v_fma_f32 v3, -v5, v36, 1.0
	v_fmac_f32_e32 v36, v3, v36
	v_div_scale_f32 v3, vcc, 1.0, v4, 1.0
	v_mul_f32_e32 v6, v3, v36
	v_fma_f32 v7, -v5, v6, v3
	v_fmac_f32_e32 v6, v7, v36
	v_mul_f32_e32 v7, 0xbfb8aa3b, v116
	v_exp_f32_e32 v7, v7
	v_fma_f32 v3, -v5, v6, v3
	v_div_fmas_f32 v3, v3, v36, v6
	v_div_fixup_f32 v3, v3, v4, 1.0
	v_add_f32_e32 v5, 1.0, v7
	v_div_scale_f32 v6, s[8:9], v5, v5, 1.0
	v_rcp_f32_e32 v7, v6
; DI float sigmoidf_(float v) { return 1.f / (1.f + __expf(-v)); }
; DI void phase_in(const Params& p, int L, char* smem) {
;     ...
;     if (cb >= 43) {
;       if (cb < 107) {
;         EPI_BEGINM(acc, 4) p.gates[(size_t)row * 4096 + (col - 2752)] = f2bf(sigmoidf_(v)); EPI_END
	v_cvt_pk_bf16_f32 v3, v3, s0
	global_store_short v[8:9], v3, off offset:-1344
	v_fma_f32 v3, -v6, v7, 1.0
	v_fmac_f32_e32 v7, v3, v7
	v_div_scale_f32 v3, vcc, 1.0, v5, 1.0
	v_mul_f32_e32 v4, v3, v7
	v_fma_f32 v8, -v6, v4, v3
	v_fmac_f32_e32 v4, v8, v7
	v_mul_f32_e32 v8, 0xbfb8aa3b, v115
	v_exp_f32_e32 v8, v8
	v_fma_f32 v3, -v6, v4, v3
	v_div_fmas_f32 v3, v3, v7, v4
	v_div_fixup_f32 v3, v3, v5, 1.0
	v_add_f32_e32 v4, 1.0, v8
	v_div_scale_f32 v6, s[8:9], v4, v4, 1.0
	v_rcp_f32_e32 v7, v6
	v_cvt_pk_bf16_f32 v3, v3, s0
	global_store_short v[10:11], v3, off offset:-1344
	v_fma_f32 v3, -v6, v7, 1.0
	v_fmac_f32_e32 v7, v3, v7
	v_div_scale_f32 v3, vcc, 1.0, v4, 1.0
	v_mul_f32_e32 v5, v3, v7
	v_fma_f32 v8, -v6, v5, v3
	v_fmac_f32_e32 v5, v8, v7
	v_mul_f32_e32 v8, 0xbfb8aa3b, v114
	v_exp_f32_e32 v8, v8
	v_fma_f32 v3, -v6, v5, v3
	v_div_fmas_f32 v3, v3, v7, v5
	v_div_fixup_f32 v3, v3, v4, 1.0
	v_add_f32_e32 v5, 1.0, v8
	v_div_scale_f32 v6, s[8:9], v5, v5, 1.0
	v_rcp_f32_e32 v7, v6
	v_cvt_pk_bf16_f32 v3, v3, s0
	global_store_short v[12:13], v3, off offset:-1344
	v_fma_f32 v3, -v6, v7, 1.0
	v_fmac_f32_e32 v7, v3, v7
	v_div_scale_f32 v3, vcc, 1.0, v5, 1.0
	v_mul_f32_e32 v4, v3, v7
	v_fma_f32 v8, -v6, v4, v3
	v_fmac_f32_e32 v4, v8, v7
	v_mul_f32_e32 v8, 0xbfb8aa3b, v113
	v_exp_f32_e32 v8, v8
	v_fma_f32 v3, -v6, v4, v3
	v_div_fmas_f32 v3, v3, v7, v4
	v_div_fixup_f32 v3, v3, v5, 1.0
	v_add_f32_e32 v4, 1.0, v8
	v_div_scale_f32 v6, s[8:9], v4, v4, 1.0
	v_rcp_f32_e32 v7, v6
	v_cvt_pk_bf16_f32 v3, v3, s0
	global_store_short v[14:15], v3, off offset:-1344
	v_fma_f32 v3, -v6, v7, 1.0
	v_fmac_f32_e32 v7, v3, v7
	v_div_scale_f32 v3, vcc, 1.0, v4, 1.0
	v_mul_f32_e32 v5, v3, v7
	v_fma_f32 v8, -v6, v5, v3
	v_fmac_f32_e32 v5, v8, v7
	v_mul_f32_e32 v8, 0xbfb8aa3b, v112
	v_exp_f32_e32 v8, v8
	v_fma_f32 v3, -v6, v5, v3
	v_div_fmas_f32 v3, v3, v7, v5
	v_div_fixup_f32 v3, v3, v4, 1.0
	v_add_f32_e32 v5, 1.0, v8
	v_div_scale_f32 v6, s[8:9], v5, v5, 1.0
	v_rcp_f32_e32 v7, v6
	v_cvt_pk_bf16_f32 v3, v3, s0
	global_store_short v[16:17], v3, off offset:-1344
	v_fma_f32 v3, -v6, v7, 1.0
	v_fmac_f32_e32 v7, v3, v7
	v_div_scale_f32 v3, vcc, 1.0, v5, 1.0
	v_mul_f32_e32 v4, v3, v7
	v_fma_f32 v8, -v6, v4, v3
	v_fmac_f32_e32 v4, v8, v7
	v_mul_f32_e32 v8, 0xbfb8aa3b, v111
	v_exp_f32_e32 v8, v8
	v_fma_f32 v3, -v6, v4, v3
	v_div_fmas_f32 v3, v3, v7, v4
	v_div_fixup_f32 v3, v3, v5, 1.0
	v_add_f32_e32 v4, 1.0, v8
	v_div_scale_f32 v6, s[8:9], v4, v4, 1.0
	v_rcp_f32_e32 v7, v6
	v_cvt_pk_bf16_f32 v3, v3, s0
	global_store_short v[18:19], v3, off offset:-1344
	v_fma_f32 v3, -v6, v7, 1.0
	v_fmac_f32_e32 v7, v3, v7
	v_div_scale_f32 v3, vcc, 1.0, v4, 1.0
	v_mul_f32_e32 v5, v3, v7
	v_fma_f32 v8, -v6, v5, v3
	v_fmac_f32_e32 v5, v8, v7
	v_mul_f32_e32 v8, 0xbfb8aa3b, v110
	v_exp_f32_e32 v8, v8
	v_fma_f32 v3, -v6, v5, v3
	v_div_fmas_f32 v3, v3, v7, v5
	v_div_fixup_f32 v3, v3, v4, 1.0
	v_add_f32_e32 v5, 1.0, v8
	v_div_scale_f32 v6, s[8:9], v5, v5, 1.0
	v_rcp_f32_e32 v7, v6
	v_cvt_pk_bf16_f32 v3, v3, s0
	global_store_short v[20:21], v3, off offset:-1344
	v_fma_f32 v3, -v6, v7, 1.0
	v_fmac_f32_e32 v7, v3, v7
	v_div_scale_f32 v3, vcc, 1.0, v5, 1.0
	v_mul_f32_e32 v4, v3, v7
	v_fma_f32 v8, -v6, v4, v3
	v_fmac_f32_e32 v4, v8, v7
	v_mul_f32_e32 v8, 0xbfb8aa3b, v109
	v_exp_f32_e32 v8, v8
	v_fma_f32 v3, -v6, v4, v3
	v_div_fmas_f32 v3, v3, v7, v4
	v_div_fixup_f32 v3, v3, v5, 1.0
	v_add_f32_e32 v4, 1.0, v8
	v_div_scale_f32 v6, s[8:9], v4, v4, 1.0
	v_rcp_f32_e32 v7, v6
	v_cvt_pk_bf16_f32 v3, v3, s0
	global_store_short v[22:23], v3, off offset:-1344
	v_fma_f32 v3, -v6, v7, 1.0
	v_fmac_f32_e32 v7, v3, v7
	v_div_scale_f32 v3, vcc, 1.0, v4, 1.0
	v_mul_f32_e32 v5, v3, v7
	v_fma_f32 v8, -v6, v5, v3
	v_fmac_f32_e32 v5, v8, v7
	v_mul_f32_e32 v8, 0xbfb8aa3b, v108
	v_exp_f32_e32 v8, v8
	v_fma_f32 v3, -v6, v5, v3
	v_div_fmas_f32 v3, v3, v7, v5
	v_div_fixup_f32 v3, v3, v4, 1.0
	v_add_f32_e32 v5, 1.0, v8
	v_div_scale_f32 v6, s[8:9], v5, v5, 1.0
	v_rcp_f32_e32 v7, v6
	v_cvt_pk_bf16_f32 v3, v3, s0
	global_store_short v[24:25], v3, off offset:-1344
	v_fma_f32 v3, -v6, v7, 1.0
	v_fmac_f32_e32 v7, v3, v7
	v_div_scale_f32 v3, vcc, 1.0, v5, 1.0
	v_mul_f32_e32 v4, v3, v7
	v_fma_f32 v8, -v6, v4, v3
	v_fmac_f32_e32 v4, v8, v7
	v_mul_f32_e32 v8, 0xbfb8aa3b, v107
	v_exp_f32_e32 v8, v8
	v_fma_f32 v3, -v6, v4, v3
	v_div_fmas_f32 v3, v3, v7, v4
	v_div_fixup_f32 v3, v3, v5, 1.0
	v_add_f32_e32 v4, 1.0, v8
	v_div_scale_f32 v6, s[8:9], v4, v4, 1.0
	v_rcp_f32_e32 v7, v6
	v_cvt_pk_bf16_f32 v3, v3, s0
	global_store_short v[26:27], v3, off offset:-1344
	v_fma_f32 v3, -v6, v7, 1.0
	v_fmac_f32_e32 v7, v3, v7
	v_div_scale_f32 v3, vcc, 1.0, v4, 1.0
	v_mul_f32_e32 v5, v3, v7
	v_fma_f32 v8, -v6, v5, v3
	v_fmac_f32_e32 v5, v8, v7
	v_mul_f32_e32 v8, 0xbfb8aa3b, v106
	v_exp_f32_e32 v8, v8
	v_fma_f32 v3, -v6, v5, v3
	v_div_fmas_f32 v3, v3, v7, v5
	v_div_fixup_f32 v3, v3, v4, 1.0
	v_add_f32_e32 v5, 1.0, v8
	v_div_scale_f32 v6, s[8:9], v5, v5, 1.0
	v_rcp_f32_e32 v7, v6
	v_cvt_pk_bf16_f32 v3, v3, s0
	global_store_short v[28:29], v3, off offset:-1344
	v_fma_f32 v3, -v6, v7, 1.0
	v_fmac_f32_e32 v7, v3, v7
	v_div_scale_f32 v3, vcc, 1.0, v5, 1.0
	v_mul_f32_e32 v4, v3, v7
	v_fma_f32 v8, -v6, v4, v3
	v_fmac_f32_e32 v4, v8, v7
	v_mul_f32_e32 v8, 0xbfb8aa3b, v105
	v_exp_f32_e32 v8, v8
	v_fma_f32 v3, -v6, v4, v3
	v_div_fmas_f32 v3, v3, v7, v4
	v_div_fixup_f32 v3, v3, v5, 1.0
	v_add_f32_e32 v4, 1.0, v8
	v_div_scale_f32 v6, s[8:9], v4, v4, 1.0
	v_rcp_f32_e32 v7, v6
	v_cvt_pk_bf16_f32 v3, v3, s0
	global_store_short v[30:31], v3, off offset:-1344
	v_fma_f32 v3, -v6, v7, 1.0
	v_fmac_f32_e32 v7, v3, v7
	v_div_scale_f32 v3, vcc, 1.0, v4, 1.0
	v_mul_f32_e32 v5, v3, v7
; DI float sigmoidf_(float v) { return 1.f / (1.f + __expf(-v)); }
; DI void phase_in(const Params& p, int L, char* smem) {
;     ...
;     if (cb >= 43) {
;       if (cb < 107) {
;         EPI_BEGINM(acc, 4) p.gates[(size_t)row * 4096 + (col - 2752)] = f2bf(sigmoidf_(v)); EPI_END
	v_fma_f32 v8, -v6, v5, v3
	v_fmac_f32_e32 v5, v8, v7
	v_mul_f32_e32 v8, 0xbfb8aa3b, v104
	v_exp_f32_e32 v8, v8
	v_fma_f32 v3, -v6, v5, v3
	v_div_fmas_f32 v3, v3, v7, v5
	v_div_fixup_f32 v3, v3, v4, 1.0
	v_add_f32_e32 v5, 1.0, v8
	v_div_scale_f32 v6, s[8:9], v5, v5, 1.0
	v_rcp_f32_e32 v7, v6
	v_cvt_pk_bf16_f32 v3, v3, s0
	global_store_short v[32:33], v3, off offset:-1344
	v_fma_f32 v3, -v6, v7, 1.0
	v_fmac_f32_e32 v7, v3, v7
	v_div_scale_f32 v3, vcc, 1.0, v5, 1.0
	v_mul_f32_e32 v4, v3, v7
	v_fma_f32 v8, -v6, v4, v3
	v_fmac_f32_e32 v4, v8, v7
	v_fma_f32 v3, -v6, v4, v3
	v_mul_f32_e32 v6, 0xbfb8aa3b, v102
	v_exp_f32_e32 v6, v6
	v_div_fmas_f32 v3, v3, v7, v4
	v_div_fixup_f32 v3, v3, v5, 1.0
	v_cvt_pk_bf16_f32 v3, v3, s0
	v_add_f32_e32 v5, 1.0, v6
	v_div_scale_f32 v6, s[8:9], v5, v5, 1.0
	v_rcp_f32_e32 v7, v6
	global_store_short v[34:35], v3, off offset:-1344
	v_or_b32_e32 v4, 64, v2
	v_fma_f32 v3, -v6, v7, 1.0
	v_fmac_f32_e32 v7, v3, v7
	v_div_scale_f32 v3, vcc, 1.0, v5, 1.0
	v_mul_f32_e32 v8, v3, v7
	v_fma_f32 v9, -v6, v8, v3
	v_fmac_f32_e32 v8, v9, v7
	v_fma_f32 v3, -v6, v8, v3
	v_div_fmas_f32 v3, v3, v7, v8
	v_div_fixup_f32 v3, v3, v5, 1.0
	v_mul_f32_e32 v5, 0xbfb8aa3b, v101
	v_exp_f32_e32 v6, v5
	v_ashrrev_i32_e32 v5, 31, v4
	v_lshlrev_b64 v[4:5], 13, v[4:5]
	v_lshl_add_u64 v[4:5], v[0:1], 0, v[4:5]
	v_add_f32_e32 v7, 1.0, v6
	v_div_scale_f32 v8, s[8:9], v7, v7, 1.0
	v_rcp_f32_e32 v9, v8
	v_add_co_u32_e32 v4, vcc, s10, v4
	v_cvt_pk_bf16_f32 v3, v3, s0
	s_nop 0
	v_addc_co_u32_e32 v5, vcc, -1, v5, vcc
	global_store_short v[4:5], v3, off offset:-1408
	v_fma_f32 v3, -v8, v9, 1.0
	v_fmac_f32_e32 v9, v3, v9
	v_div_scale_f32 v3, vcc, 1.0, v7, 1.0
	v_mul_f32_e32 v10, v3, v9
	v_fma_f32 v11, -v8, v10, v3
	v_fmac_f32_e32 v10, v11, v9
	v_fma_f32 v3, -v8, v10, v3
	v_div_fmas_f32 v3, v3, v9, v10
	v_div_fixup_f32 v3, v3, v7, 1.0
	v_mul_f32_e32 v7, 0xbfb8aa3b, v100
	v_exp_f32_e32 v8, v7
	v_or_b32_e32 v6, 0x41, v2
	v_ashrrev_i32_e32 v7, 31, v6
	v_lshlrev_b64 v[6:7], 13, v[6:7]
	v_add_f32_e32 v9, 1.0, v8
	v_div_scale_f32 v10, s[8:9], v9, v9, 1.0
	v_rcp_f32_e32 v11, v10
	v_lshl_add_u64 v[6:7], v[0:1], 0, v[6:7]
	v_add_co_u32_e32 v6, vcc, s10, v6
	v_cvt_pk_bf16_f32 v3, v3, s0
	s_nop 0
	v_addc_co_u32_e32 v7, vcc, -1, v7, vcc
	global_store_short v[6:7], v3, off offset:-1408
	v_fma_f32 v3, -v10, v11, 1.0
	v_fmac_f32_e32 v11, v3, v11
	v_div_scale_f32 v3, vcc, 1.0, v9, 1.0
	v_mul_f32_e32 v12, v3, v11
	v_fma_f32 v13, -v10, v12, v3
	v_fmac_f32_e32 v12, v13, v11
	v_fma_f32 v3, -v10, v12, v3
	v_div_fmas_f32 v3, v3, v11, v12
	v_div_fixup_f32 v3, v3, v9, 1.0
	v_mul_f32_e32 v9, 0xbfb8aa3b, v98
	v_exp_f32_e32 v10, v9
	v_or_b32_e32 v8, 0x42, v2
	v_ashrrev_i32_e32 v9, 31, v8
	v_lshlrev_b64 v[8:9], 13, v[8:9]
	v_add_f32_e32 v11, 1.0, v10
	v_div_scale_f32 v12, s[8:9], v11, v11, 1.0
	v_rcp_f32_e32 v13, v12
	v_lshl_add_u64 v[8:9], v[0:1], 0, v[8:9]
	v_add_co_u32_e32 v8, vcc, s10, v8
	v_cvt_pk_bf16_f32 v3, v3, s0
	s_nop 0
	v_addc_co_u32_e32 v9, vcc, -1, v9, vcc
	global_store_short v[8:9], v3, off offset:-1408
	v_fma_f32 v3, -v12, v13, 1.0
	v_fmac_f32_e32 v13, v3, v13
	v_div_scale_f32 v3, vcc, 1.0, v11, 1.0
	v_mul_f32_e32 v14, v3, v13
	v_fma_f32 v15, -v12, v14, v3
	v_fmac_f32_e32 v14, v15, v13
	v_fma_f32 v3, -v12, v14, v3
	v_div_fmas_f32 v3, v3, v13, v14
	v_div_fixup_f32 v3, v3, v11, 1.0
	v_mul_f32_e32 v11, 0xbfb8aa3b, v97
	v_exp_f32_e32 v12, v11
	v_or_b32_e32 v10, 0x43, v2
	v_ashrrev_i32_e32 v11, 31, v10
	v_lshlrev_b64 v[10:11], 13, v[10:11]
	v_add_f32_e32 v13, 1.0, v12
	v_div_scale_f32 v14, s[8:9], v13, v13, 1.0
	v_rcp_f32_e32 v15, v14
	v_lshl_add_u64 v[10:11], v[0:1], 0, v[10:11]
	v_add_co_u32_e32 v10, vcc, s10, v10
	v_cvt_pk_bf16_f32 v3, v3, s0
	s_nop 0
	v_addc_co_u32_e32 v11, vcc, -1, v11, vcc
	global_store_short v[10:11], v3, off offset:-1408
	v_fma_f32 v3, -v14, v15, 1.0
	v_fmac_f32_e32 v15, v3, v15
	v_div_scale_f32 v3, vcc, 1.0, v13, 1.0
	v_mul_f32_e32 v16, v3, v15
	v_fma_f32 v17, -v14, v16, v3
	v_fmac_f32_e32 v16, v17, v15
	v_fma_f32 v3, -v14, v16, v3
	v_div_fmas_f32 v3, v3, v15, v16
	v_div_fixup_f32 v3, v3, v13, 1.0
	v_mul_f32_e32 v13, 0xbfb8aa3b, v96
	v_exp_f32_e32 v14, v13
	v_or_b32_e32 v12, 0x48, v2
	v_ashrrev_i32_e32 v13, 31, v12
	v_lshlrev_b64 v[12:13], 13, v[12:13]
	v_add_f32_e32 v15, 1.0, v14
	v_div_scale_f32 v16, s[8:9], v15, v15, 1.0
	v_rcp_f32_e32 v17, v16
	v_lshl_add_u64 v[12:13], v[0:1], 0, v[12:13]
	v_add_co_u32_e32 v12, vcc, s10, v12
	v_cvt_pk_bf16_f32 v3, v3, s0
	s_nop 0
	v_addc_co_u32_e32 v13, vcc, -1, v13, vcc
	global_store_short v[12:13], v3, off offset:-1408
	v_fma_f32 v3, -v16, v17, 1.0
	v_fmac_f32_e32 v17, v3, v17
	v_div_scale_f32 v3, vcc, 1.0, v15, 1.0
	v_mul_f32_e32 v18, v3, v17
	v_fma_f32 v19, -v16, v18, v3
	v_fmac_f32_e32 v18, v19, v17
	v_fma_f32 v3, -v16, v18, v3
	v_div_fmas_f32 v3, v3, v17, v18
	v_div_fixup_f32 v3, v3, v15, 1.0
	v_mul_f32_e32 v15, 0xbfb8aa3b, v95
	v_exp_f32_e32 v16, v15
	v_or_b32_e32 v14, 0x49, v2
	v_ashrrev_i32_e32 v15, 31, v14
	v_lshlrev_b64 v[14:15], 13, v[14:15]
	v_add_f32_e32 v17, 1.0, v16
	v_div_scale_f32 v18, s[8:9], v17, v17, 1.0
	v_rcp_f32_e32 v19, v18
	v_lshl_add_u64 v[14:15], v[0:1], 0, v[14:15]
	v_add_co_u32_e32 v14, vcc, s10, v14
	v_cvt_pk_bf16_f32 v3, v3, s0
	s_nop 0
	v_addc_co_u32_e32 v15, vcc, -1, v15, vcc
	global_store_short v[14:15], v3, off offset:-1408
	v_fma_f32 v3, -v18, v19, 1.0
	v_fmac_f32_e32 v19, v3, v19
	v_div_scale_f32 v3, vcc, 1.0, v17, 1.0
	v_mul_f32_e32 v20, v3, v19
	v_fma_f32 v21, -v18, v20, v3
	v_fmac_f32_e32 v20, v21, v19
	v_fma_f32 v3, -v18, v20, v3
	v_div_fmas_f32 v3, v3, v19, v20
	v_div_fixup_f32 v3, v3, v17, 1.0
	v_mul_f32_e32 v17, 0xbfb8aa3b, v94
	v_exp_f32_e32 v18, v17
; DI float sigmoidf_(float v) { return 1.f / (1.f + __expf(-v)); }
; DI void phase_in(const Params& p, int L, char* smem) {
;     ...
;     if (cb >= 43) {
;       if (cb < 107) {
;         EPI_BEGINM(acc, 4) p.gates[(size_t)row * 4096 + (col - 2752)] = f2bf(sigmoidf_(v)); EPI_END
	v_or_b32_e32 v16, 0x4a, v2
	v_ashrrev_i32_e32 v17, 31, v16
	v_lshlrev_b64 v[16:17], 13, v[16:17]
	v_add_f32_e32 v19, 1.0, v18
	v_div_scale_f32 v20, s[8:9], v19, v19, 1.0
	v_rcp_f32_e32 v21, v20
	v_lshl_add_u64 v[16:17], v[0:1], 0, v[16:17]
	v_add_co_u32_e32 v16, vcc, s10, v16
	v_cvt_pk_bf16_f32 v3, v3, s0
	s_nop 0
	v_addc_co_u32_e32 v17, vcc, -1, v17, vcc
	global_store_short v[16:17], v3, off offset:-1408
	v_fma_f32 v3, -v20, v21, 1.0
	v_fmac_f32_e32 v21, v3, v21
	v_div_scale_f32 v3, vcc, 1.0, v19, 1.0
	v_mul_f32_e32 v22, v3, v21
	v_fma_f32 v23, -v20, v22, v3
	v_fmac_f32_e32 v22, v23, v21
	v_fma_f32 v3, -v20, v22, v3
	v_div_fmas_f32 v3, v3, v21, v22
	v_div_fixup_f32 v3, v3, v19, 1.0
	v_mul_f32_e32 v19, 0xbfb8aa3b, v93
	v_exp_f32_e32 v20, v19
	v_or_b32_e32 v18, 0x4b, v2
	v_ashrrev_i32_e32 v19, 31, v18
	v_lshlrev_b64 v[18:19], 13, v[18:19]
	v_add_f32_e32 v21, 1.0, v20
	v_div_scale_f32 v22, s[8:9], v21, v21, 1.0
	v_rcp_f32_e32 v23, v22
	v_lshl_add_u64 v[18:19], v[0:1], 0, v[18:19]
	v_add_co_u32_e32 v18, vcc, s10, v18
	v_cvt_pk_bf16_f32 v3, v3, s0
	s_nop 0
	v_addc_co_u32_e32 v19, vcc, -1, v19, vcc
	global_store_short v[18:19], v3, off offset:-1408
	v_fma_f32 v3, -v22, v23, 1.0
	v_fmac_f32_e32 v23, v3, v23
	v_div_scale_f32 v3, vcc, 1.0, v21, 1.0
	v_mul_f32_e32 v24, v3, v23
	v_fma_f32 v25, -v22, v24, v3
	v_fmac_f32_e32 v24, v25, v23
	v_fma_f32 v3, -v22, v24, v3
	v_div_fmas_f32 v3, v3, v23, v24
	v_div_fixup_f32 v3, v3, v21, 1.0
	v_mul_f32_e32 v21, 0xbfb8aa3b, v92
	v_exp_f32_e32 v22, v21
	v_or_b32_e32 v20, 0x50, v2
	v_ashrrev_i32_e32 v21, 31, v20
	v_lshlrev_b64 v[20:21], 13, v[20:21]
	v_add_f32_e32 v23, 1.0, v22
	v_div_scale_f32 v24, s[8:9], v23, v23, 1.0
	v_rcp_f32_e32 v25, v24
	v_lshl_add_u64 v[20:21], v[0:1], 0, v[20:21]
	v_add_co_u32_e32 v20, vcc, s10, v20
	v_cvt_pk_bf16_f32 v3, v3, s0
	s_nop 0
	v_addc_co_u32_e32 v21, vcc, -1, v21, vcc
	global_store_short v[20:21], v3, off offset:-1408
	v_fma_f32 v3, -v24, v25, 1.0
	v_fmac_f32_e32 v25, v3, v25
	v_div_scale_f32 v3, vcc, 1.0, v23, 1.0
	v_mul_f32_e32 v26, v3, v25
	v_fma_f32 v27, -v24, v26, v3
	v_fmac_f32_e32 v26, v27, v25
	v_fma_f32 v3, -v24, v26, v3
	v_div_fmas_f32 v3, v3, v25, v26
	v_div_fixup_f32 v3, v3, v23, 1.0
	v_mul_f32_e32 v23, 0xbfb8aa3b, v91
	v_exp_f32_e32 v24, v23
	v_or_b32_e32 v22, 0x51, v2
	v_ashrrev_i32_e32 v23, 31, v22
	v_lshlrev_b64 v[22:23], 13, v[22:23]
	v_add_f32_e32 v25, 1.0, v24
	v_div_scale_f32 v26, s[8:9], v25, v25, 1.0
	v_rcp_f32_e32 v27, v26
	v_lshl_add_u64 v[22:23], v[0:1], 0, v[22:23]
	v_add_co_u32_e32 v22, vcc, s10, v22
	v_cvt_pk_bf16_f32 v3, v3, s0
	s_nop 0
	v_addc_co_u32_e32 v23, vcc, -1, v23, vcc
	global_store_short v[22:23], v3, off offset:-1408
	v_fma_f32 v3, -v26, v27, 1.0
	v_fmac_f32_e32 v27, v3, v27
	v_div_scale_f32 v3, vcc, 1.0, v25, 1.0
	v_mul_f32_e32 v28, v3, v27
	v_fma_f32 v29, -v26, v28, v3
	v_fmac_f32_e32 v28, v29, v27
	v_fma_f32 v3, -v26, v28, v3
	v_div_fmas_f32 v3, v3, v27, v28
	v_div_fixup_f32 v3, v3, v25, 1.0
	v_mul_f32_e32 v25, 0xbfb8aa3b, v90
	v_exp_f32_e32 v26, v25
	v_or_b32_e32 v24, 0x52, v2
	v_ashrrev_i32_e32 v25, 31, v24
	v_lshlrev_b64 v[24:25], 13, v[24:25]
	v_add_f32_e32 v27, 1.0, v26
	v_div_scale_f32 v28, s[8:9], v27, v27, 1.0
	v_rcp_f32_e32 v29, v28
	v_lshl_add_u64 v[24:25], v[0:1], 0, v[24:25]
	v_add_co_u32_e32 v24, vcc, s10, v24
	v_cvt_pk_bf16_f32 v3, v3, s0
	s_nop 0
	v_addc_co_u32_e32 v25, vcc, -1, v25, vcc
	global_store_short v[24:25], v3, off offset:-1408
	v_fma_f32 v3, -v28, v29, 1.0
	v_fmac_f32_e32 v29, v3, v29
	v_div_scale_f32 v3, vcc, 1.0, v27, 1.0
	v_mul_f32_e32 v30, v3, v29
	v_fma_f32 v31, -v28, v30, v3
	v_fmac_f32_e32 v30, v31, v29
	v_fma_f32 v3, -v28, v30, v3
	v_div_fmas_f32 v3, v3, v29, v30
	v_div_fixup_f32 v3, v3, v27, 1.0
	v_mul_f32_e32 v27, 0xbfb8aa3b, v89
	v_exp_f32_e32 v28, v27
	v_or_b32_e32 v26, 0x53, v2
	v_ashrrev_i32_e32 v27, 31, v26
	v_lshlrev_b64 v[26:27], 13, v[26:27]
	v_add_f32_e32 v29, 1.0, v28
	v_div_scale_f32 v30, s[8:9], v29, v29, 1.0
	v_rcp_f32_e32 v31, v30
	v_lshl_add_u64 v[26:27], v[0:1], 0, v[26:27]
	v_add_co_u32_e32 v26, vcc, s10, v26
	v_cvt_pk_bf16_f32 v3, v3, s0
	s_nop 0
	v_addc_co_u32_e32 v27, vcc, -1, v27, vcc
	global_store_short v[26:27], v3, off offset:-1408
	v_fma_f32 v3, -v30, v31, 1.0
	v_fmac_f32_e32 v31, v3, v31
	v_div_scale_f32 v3, vcc, 1.0, v29, 1.0
	v_mul_f32_e32 v32, v3, v31
	v_fma_f32 v33, -v30, v32, v3
	v_fmac_f32_e32 v32, v33, v31
	v_fma_f32 v3, -v30, v32, v3
	v_div_fmas_f32 v3, v3, v31, v32
	v_div_fixup_f32 v3, v3, v29, 1.0
	v_mul_f32_e32 v29, 0xbfb8aa3b, v88
	v_exp_f32_e32 v30, v29
	v_or_b32_e32 v28, 0x58, v2
	v_ashrrev_i32_e32 v29, 31, v28
	v_lshlrev_b64 v[28:29], 13, v[28:29]
	v_add_f32_e32 v31, 1.0, v30
	v_div_scale_f32 v32, s[8:9], v31, v31, 1.0
	v_rcp_f32_e32 v33, v32
	v_lshl_add_u64 v[28:29], v[0:1], 0, v[28:29]
	v_add_co_u32_e32 v28, vcc, s10, v28
	v_cvt_pk_bf16_f32 v3, v3, s0
	s_nop 0
	v_addc_co_u32_e32 v29, vcc, -1, v29, vcc
	global_store_short v[28:29], v3, off offset:-1408
	v_fma_f32 v3, -v32, v33, 1.0
	v_fmac_f32_e32 v33, v3, v33
	v_div_scale_f32 v3, vcc, 1.0, v31, 1.0
	v_mul_f32_e32 v34, v3, v33
	v_fma_f32 v35, -v32, v34, v3
	v_fmac_f32_e32 v34, v35, v33
	v_fma_f32 v3, -v32, v34, v3
	v_div_fmas_f32 v3, v3, v33, v34
	v_div_fixup_f32 v3, v3, v31, 1.0
	v_mul_f32_e32 v31, 0xbfb8aa3b, v87
	v_exp_f32_e32 v32, v31
	v_or_b32_e32 v30, 0x59, v2
	v_ashrrev_i32_e32 v31, 31, v30
	v_lshlrev_b64 v[30:31], 13, v[30:31]
	v_add_f32_e32 v33, 1.0, v32
	v_div_scale_f32 v34, s[8:9], v33, v33, 1.0
	v_rcp_f32_e32 v35, v34
	v_lshl_add_u64 v[30:31], v[0:1], 0, v[30:31]
	v_add_co_u32_e32 v30, vcc, s10, v30
	v_cvt_pk_bf16_f32 v3, v3, s0
	s_nop 0
	v_addc_co_u32_e32 v31, vcc, -1, v31, vcc
; DI float sigmoidf_(float v) { return 1.f / (1.f + __expf(-v)); }
; DI void phase_in(const Params& p, int L, char* smem) {
;     ...
;     if (cb >= 43) {
;       if (cb < 107) {
;         EPI_BEGINM(acc, 4) p.gates[(size_t)row * 4096 + (col - 2752)] = f2bf(sigmoidf_(v)); EPI_END
	global_store_short v[30:31], v3, off offset:-1408
	v_fma_f32 v3, -v34, v35, 1.0
	v_fmac_f32_e32 v35, v3, v35
	v_div_scale_f32 v3, vcc, 1.0, v33, 1.0
	v_mul_f32_e32 v36, v3, v35
	v_fma_f32 v37, -v34, v36, v3
	v_fmac_f32_e32 v36, v37, v35
	v_fma_f32 v3, -v34, v36, v3
	v_div_fmas_f32 v3, v3, v35, v36
	v_div_fixup_f32 v3, v3, v33, 1.0
	v_mul_f32_e32 v33, 0xbfb8aa3b, v86
	v_exp_f32_e32 v34, v33
	v_or_b32_e32 v32, 0x5a, v2
	v_ashrrev_i32_e32 v33, 31, v32
	v_lshlrev_b64 v[32:33], 13, v[32:33]
	v_add_f32_e32 v35, 1.0, v34
	v_div_scale_f32 v36, s[8:9], v35, v35, 1.0
	v_rcp_f32_e32 v37, v36
	v_lshl_add_u64 v[32:33], v[0:1], 0, v[32:33]
	v_add_co_u32_e32 v32, vcc, s10, v32
	v_cvt_pk_bf16_f32 v3, v3, s0
	s_nop 0
	v_addc_co_u32_e32 v33, vcc, -1, v33, vcc
	global_store_short v[32:33], v3, off offset:-1408
	v_fma_f32 v3, -v36, v37, 1.0
	v_fmac_f32_e32 v37, v3, v37
	v_div_scale_f32 v3, vcc, 1.0, v35, 1.0
	v_mul_f32_e32 v86, v3, v37
	v_fma_f32 v87, -v36, v86, v3
	v_fmac_f32_e32 v86, v87, v37
	v_fma_f32 v3, -v36, v86, v3
	v_div_fmas_f32 v3, v3, v37, v86
	v_div_fixup_f32 v3, v3, v35, 1.0
	v_mul_f32_e32 v35, 0xbfb8aa3b, v85
	v_exp_f32_e32 v36, v35
	v_or_b32_e32 v34, 0x5b, v2
	v_ashrrev_i32_e32 v35, 31, v34
	v_lshlrev_b64 v[34:35], 13, v[34:35]
	v_add_f32_e32 v36, 1.0, v36
	v_div_scale_f32 v37, s[8:9], v36, v36, 1.0
	v_rcp_f32_e32 v85, v37
	v_lshl_add_u64 v[34:35], v[0:1], 0, v[34:35]
	v_add_co_u32_e32 v34, vcc, s10, v34
	v_cvt_pk_bf16_f32 v3, v3, s0
	s_nop 0
	v_addc_co_u32_e32 v35, vcc, -1, v35, vcc
	global_store_short v[34:35], v3, off offset:-1408
	v_fma_f32 v3, -v37, v85, 1.0
	v_fmac_f32_e32 v85, v3, v85
	v_div_scale_f32 v3, vcc, 1.0, v36, 1.0
	v_mul_f32_e32 v86, v3, v85
	v_fma_f32 v87, -v37, v86, v3
	v_fmac_f32_e32 v86, v87, v85
	v_fma_f32 v3, -v37, v86, v3
	v_add_f32_e32 v37, 1.0, v84
	v_div_scale_f32 v84, s[8:9], v37, v37, 1.0
	v_div_fmas_f32 v3, v3, v85, v86
	v_rcp_f32_e32 v85, v84
	v_div_fixup_f32 v3, v3, v36, 1.0
	v_cvt_pk_bf16_f32 v3, v3, s0
	global_store_short v[4:5], v3, off offset:-1344
	v_fma_f32 v3, -v84, v85, 1.0
	v_fmac_f32_e32 v85, v3, v85
	v_div_scale_f32 v3, vcc, 1.0, v37, 1.0
	v_mul_f32_e32 v4, v3, v85
	v_fma_f32 v5, -v84, v4, v3
	v_fmac_f32_e32 v4, v5, v85
	v_mul_f32_e32 v5, 0xbfb8aa3b, v83
	v_exp_f32_e32 v5, v5
	v_fma_f32 v3, -v84, v4, v3
	v_div_fmas_f32 v3, v3, v85, v4
	v_div_fixup_f32 v3, v3, v37, 1.0
	v_add_f32_e32 v4, 1.0, v5
	v_div_scale_f32 v5, s[8:9], v4, v4, 1.0
	v_rcp_f32_e32 v36, v5
	v_cvt_pk_bf16_f32 v3, v3, s0
	global_store_short v[6:7], v3, off offset:-1344
	v_fma_f32 v3, -v5, v36, 1.0
	v_fmac_f32_e32 v36, v3, v36
	v_div_scale_f32 v3, vcc, 1.0, v4, 1.0
	v_mul_f32_e32 v6, v3, v36
	v_fma_f32 v7, -v5, v6, v3
	v_fmac_f32_e32 v6, v7, v36
	v_mul_f32_e32 v7, 0xbfb8aa3b, v82
	v_exp_f32_e32 v7, v7
	v_fma_f32 v3, -v5, v6, v3
	v_div_fmas_f32 v3, v3, v36, v6
	v_div_fixup_f32 v3, v3, v4, 1.0
	v_add_f32_e32 v5, 1.0, v7
	v_div_scale_f32 v6, s[8:9], v5, v5, 1.0
	v_rcp_f32_e32 v7, v6
	v_cvt_pk_bf16_f32 v3, v3, s0
	global_store_short v[8:9], v3, off offset:-1344
	v_fma_f32 v3, -v6, v7, 1.0
	v_fmac_f32_e32 v7, v3, v7
	v_div_scale_f32 v3, vcc, 1.0, v5, 1.0
	v_mul_f32_e32 v4, v3, v7
	v_fma_f32 v8, -v6, v4, v3
	v_fmac_f32_e32 v4, v8, v7
	v_mul_f32_e32 v8, 0xbfb8aa3b, v81
	v_exp_f32_e32 v8, v8
	v_fma_f32 v3, -v6, v4, v3
	v_div_fmas_f32 v3, v3, v7, v4
	v_div_fixup_f32 v3, v3, v5, 1.0
	v_add_f32_e32 v4, 1.0, v8
	v_div_scale_f32 v6, s[8:9], v4, v4, 1.0
	v_rcp_f32_e32 v7, v6
	v_cvt_pk_bf16_f32 v3, v3, s0
	global_store_short v[10:11], v3, off offset:-1344
	v_fma_f32 v3, -v6, v7, 1.0
	v_fmac_f32_e32 v7, v3, v7
	v_div_scale_f32 v3, vcc, 1.0, v4, 1.0
	v_mul_f32_e32 v5, v3, v7
	v_fma_f32 v8, -v6, v5, v3
	v_fmac_f32_e32 v5, v8, v7
	v_mul_f32_e32 v8, 0xbfb8aa3b, v80
	v_exp_f32_e32 v8, v8
	v_fma_f32 v3, -v6, v5, v3
	v_div_fmas_f32 v3, v3, v7, v5
	v_div_fixup_f32 v3, v3, v4, 1.0
	v_add_f32_e32 v5, 1.0, v8
	v_div_scale_f32 v6, s[8:9], v5, v5, 1.0
	v_rcp_f32_e32 v7, v6
	v_cvt_pk_bf16_f32 v3, v3, s0
	global_store_short v[12:13], v3, off offset:-1344
	v_fma_f32 v3, -v6, v7, 1.0
	v_fmac_f32_e32 v7, v3, v7
	v_div_scale_f32 v3, vcc, 1.0, v5, 1.0
	v_mul_f32_e32 v4, v3, v7
	v_fma_f32 v8, -v6, v4, v3
	v_fmac_f32_e32 v4, v8, v7
	v_mul_f32_e32 v8, 0xbfb8aa3b, v79
	v_exp_f32_e32 v8, v8
	v_fma_f32 v3, -v6, v4, v3
	v_div_fmas_f32 v3, v3, v7, v4
	v_div_fixup_f32 v3, v3, v5, 1.0
	v_add_f32_e32 v4, 1.0, v8
	v_div_scale_f32 v6, s[8:9], v4, v4, 1.0
	v_rcp_f32_e32 v7, v6
	v_cvt_pk_bf16_f32 v3, v3, s0
	global_store_short v[14:15], v3, off offset:-1344
	v_fma_f32 v3, -v6, v7, 1.0
	v_fmac_f32_e32 v7, v3, v7
	v_div_scale_f32 v3, vcc, 1.0, v4, 1.0
	v_mul_f32_e32 v5, v3, v7
	v_fma_f32 v8, -v6, v5, v3
	v_fmac_f32_e32 v5, v8, v7
	v_mul_f32_e32 v8, 0xbfb8aa3b, v78
	v_exp_f32_e32 v8, v8
	v_fma_f32 v3, -v6, v5, v3
	v_div_fmas_f32 v3, v3, v7, v5
	v_div_fixup_f32 v3, v3, v4, 1.0
	v_add_f32_e32 v5, 1.0, v8
	v_div_scale_f32 v6, s[8:9], v5, v5, 1.0
	v_rcp_f32_e32 v7, v6
	v_cvt_pk_bf16_f32 v3, v3, s0
	global_store_short v[16:17], v3, off offset:-1344
	v_fma_f32 v3, -v6, v7, 1.0
	v_fmac_f32_e32 v7, v3, v7
	v_div_scale_f32 v3, vcc, 1.0, v5, 1.0
	v_mul_f32_e32 v4, v3, v7
	v_fma_f32 v8, -v6, v4, v3
	v_fmac_f32_e32 v4, v8, v7
	v_mul_f32_e32 v8, 0xbfb8aa3b, v77
	v_exp_f32_e32 v8, v8
	v_fma_f32 v3, -v6, v4, v3
	v_div_fmas_f32 v3, v3, v7, v4
	v_div_fixup_f32 v3, v3, v5, 1.0
	v_add_f32_e32 v4, 1.0, v8
	v_div_scale_f32 v6, s[8:9], v4, v4, 1.0
	v_rcp_f32_e32 v7, v6
	v_cvt_pk_bf16_f32 v3, v3, s0
	global_store_short v[18:19], v3, off offset:-1344
	v_fma_f32 v3, -v6, v7, 1.0
	v_fmac_f32_e32 v7, v3, v7
	v_div_scale_f32 v3, vcc, 1.0, v4, 1.0
	v_mul_f32_e32 v5, v3, v7
	v_fma_f32 v8, -v6, v5, v3
; DI float sigmoidf_(float v) { return 1.f / (1.f + __expf(-v)); }
; DI void phase_in(const Params& p, int L, char* smem) {
;     ...
;     if (cb >= 43) {
;       if (cb < 107) {
;         EPI_BEGINM(acc, 4) p.gates[(size_t)row * 4096 + (col - 2752)] = f2bf(sigmoidf_(v)); EPI_END
	v_fmac_f32_e32 v5, v8, v7
	v_mul_f32_e32 v8, 0xbfb8aa3b, v76
	v_exp_f32_e32 v8, v8
	v_fma_f32 v3, -v6, v5, v3
	v_div_fmas_f32 v3, v3, v7, v5
	v_div_fixup_f32 v3, v3, v4, 1.0
	v_add_f32_e32 v5, 1.0, v8
	v_div_scale_f32 v6, s[8:9], v5, v5, 1.0
	v_rcp_f32_e32 v7, v6
	v_cvt_pk_bf16_f32 v3, v3, s0
	global_store_short v[20:21], v3, off offset:-1344
	v_fma_f32 v3, -v6, v7, 1.0
	v_fmac_f32_e32 v7, v3, v7
	v_div_scale_f32 v3, vcc, 1.0, v5, 1.0
	v_mul_f32_e32 v4, v3, v7
	v_fma_f32 v8, -v6, v4, v3
	v_fmac_f32_e32 v4, v8, v7
	v_mul_f32_e32 v8, 0xbfb8aa3b, v75
	v_exp_f32_e32 v8, v8
	v_fma_f32 v3, -v6, v4, v3
	v_div_fmas_f32 v3, v3, v7, v4
	v_div_fixup_f32 v3, v3, v5, 1.0
	v_add_f32_e32 v4, 1.0, v8
	v_div_scale_f32 v6, s[8:9], v4, v4, 1.0
	v_rcp_f32_e32 v7, v6
	v_cvt_pk_bf16_f32 v3, v3, s0
	global_store_short v[22:23], v3, off offset:-1344
	v_fma_f32 v3, -v6, v7, 1.0
	v_fmac_f32_e32 v7, v3, v7
	v_div_scale_f32 v3, vcc, 1.0, v4, 1.0
	v_mul_f32_e32 v5, v3, v7
	v_fma_f32 v8, -v6, v5, v3
	v_fmac_f32_e32 v5, v8, v7
	v_mul_f32_e32 v8, 0xbfb8aa3b, v74
	v_exp_f32_e32 v8, v8
	v_fma_f32 v3, -v6, v5, v3
	v_div_fmas_f32 v3, v3, v7, v5
	v_div_fixup_f32 v3, v3, v4, 1.0
	v_add_f32_e32 v5, 1.0, v8
	v_div_scale_f32 v6, s[8:9], v5, v5, 1.0
	v_rcp_f32_e32 v7, v6
	v_cvt_pk_bf16_f32 v3, v3, s0
	global_store_short v[24:25], v3, off offset:-1344
	v_fma_f32 v3, -v6, v7, 1.0
	v_fmac_f32_e32 v7, v3, v7
	v_div_scale_f32 v3, vcc, 1.0, v5, 1.0
	v_mul_f32_e32 v4, v3, v7
	v_fma_f32 v8, -v6, v4, v3
	v_fmac_f32_e32 v4, v8, v7
	v_mul_f32_e32 v8, 0xbfb8aa3b, v73
	v_exp_f32_e32 v8, v8
	v_fma_f32 v3, -v6, v4, v3
	v_div_fmas_f32 v3, v3, v7, v4
	v_div_fixup_f32 v3, v3, v5, 1.0
	v_add_f32_e32 v4, 1.0, v8
	v_div_scale_f32 v6, s[8:9], v4, v4, 1.0
	v_rcp_f32_e32 v7, v6
	v_cvt_pk_bf16_f32 v3, v3, s0
	global_store_short v[26:27], v3, off offset:-1344
	v_fma_f32 v3, -v6, v7, 1.0
	v_fmac_f32_e32 v7, v3, v7
	v_div_scale_f32 v3, vcc, 1.0, v4, 1.0
	v_mul_f32_e32 v5, v3, v7
	v_fma_f32 v8, -v6, v5, v3
	v_fmac_f32_e32 v5, v8, v7
	v_mul_f32_e32 v8, 0xbfb8aa3b, v72
	v_exp_f32_e32 v8, v8
	v_fma_f32 v3, -v6, v5, v3
	v_div_fmas_f32 v3, v3, v7, v5
	v_div_fixup_f32 v3, v3, v4, 1.0
	v_add_f32_e32 v5, 1.0, v8
	v_div_scale_f32 v6, s[8:9], v5, v5, 1.0
	v_rcp_f32_e32 v7, v6
	v_cvt_pk_bf16_f32 v3, v3, s0
	global_store_short v[28:29], v3, off offset:-1344
	v_fma_f32 v3, -v6, v7, 1.0
	v_fmac_f32_e32 v7, v3, v7
	v_div_scale_f32 v3, vcc, 1.0, v5, 1.0
	v_mul_f32_e32 v4, v3, v7
	v_fma_f32 v8, -v6, v4, v3
	v_fmac_f32_e32 v4, v8, v7
	v_mul_f32_e32 v8, 0xbfb8aa3b, v71
	v_exp_f32_e32 v8, v8
	v_fma_f32 v3, -v6, v4, v3
	v_div_fmas_f32 v3, v3, v7, v4
	v_div_fixup_f32 v3, v3, v5, 1.0
	v_add_f32_e32 v4, 1.0, v8
	v_div_scale_f32 v6, s[8:9], v4, v4, 1.0
	v_rcp_f32_e32 v7, v6
	v_cvt_pk_bf16_f32 v3, v3, s0
	global_store_short v[30:31], v3, off offset:-1344
	v_fma_f32 v3, -v6, v7, 1.0
	v_fmac_f32_e32 v7, v3, v7
	v_div_scale_f32 v3, vcc, 1.0, v4, 1.0
	v_mul_f32_e32 v5, v3, v7
	v_fma_f32 v8, -v6, v5, v3
	v_fmac_f32_e32 v5, v8, v7
	v_mul_f32_e32 v8, 0xbfb8aa3b, v70
	v_exp_f32_e32 v8, v8
	v_fma_f32 v3, -v6, v5, v3
	v_div_fmas_f32 v3, v3, v7, v5
	v_div_fixup_f32 v3, v3, v4, 1.0
	v_add_f32_e32 v5, 1.0, v8
	v_div_scale_f32 v6, s[8:9], v5, v5, 1.0
	v_rcp_f32_e32 v7, v6
	v_cvt_pk_bf16_f32 v3, v3, s0
	global_store_short v[32:33], v3, off offset:-1344
	v_fma_f32 v3, -v6, v7, 1.0
	v_fmac_f32_e32 v7, v3, v7
	v_div_scale_f32 v3, vcc, 1.0, v5, 1.0
	v_mul_f32_e32 v4, v3, v7
	v_fma_f32 v8, -v6, v4, v3
	v_fmac_f32_e32 v4, v8, v7
	v_fma_f32 v3, -v6, v4, v3
	v_mul_f32_e32 v6, 0xbfb8aa3b, v69
	v_exp_f32_e32 v6, v6
	v_div_fmas_f32 v3, v3, v7, v4
	v_div_fixup_f32 v3, v3, v5, 1.0
	v_cvt_pk_bf16_f32 v3, v3, s0
	v_add_f32_e32 v5, 1.0, v6
	v_div_scale_f32 v6, s[8:9], v5, v5, 1.0
	v_rcp_f32_e32 v7, v6
	global_store_short v[34:35], v3, off offset:-1344
	v_or_b32_e32 v4, 0x60, v2
	v_fma_f32 v3, -v6, v7, 1.0
	v_fmac_f32_e32 v7, v3, v7
	v_div_scale_f32 v3, vcc, 1.0, v5, 1.0
	v_mul_f32_e32 v8, v3, v7
	v_fma_f32 v9, -v6, v8, v3
	v_fmac_f32_e32 v8, v9, v7
	v_fma_f32 v3, -v6, v8, v3
	v_div_fmas_f32 v3, v3, v7, v8
	v_div_fixup_f32 v3, v3, v5, 1.0
	v_mul_f32_e32 v5, 0xbfb8aa3b, v68
	v_exp_f32_e32 v6, v5
	v_ashrrev_i32_e32 v5, 31, v4
	v_lshlrev_b64 v[4:5], 13, v[4:5]
	v_lshl_add_u64 v[4:5], v[0:1], 0, v[4:5]
	v_add_f32_e32 v7, 1.0, v6
	v_div_scale_f32 v8, s[8:9], v7, v7, 1.0
	v_rcp_f32_e32 v9, v8
	v_add_co_u32_e32 v4, vcc, s10, v4
	v_cvt_pk_bf16_f32 v3, v3, s0
	s_nop 0
	v_addc_co_u32_e32 v5, vcc, -1, v5, vcc
	global_store_short v[4:5], v3, off offset:-1408
	v_fma_f32 v3, -v8, v9, 1.0
	v_fmac_f32_e32 v9, v3, v9
	v_div_scale_f32 v3, vcc, 1.0, v7, 1.0
	v_mul_f32_e32 v10, v3, v9
	v_fma_f32 v11, -v8, v10, v3
	v_fmac_f32_e32 v10, v11, v9
	v_fma_f32 v3, -v8, v10, v3
	v_div_fmas_f32 v3, v3, v9, v10
	v_div_fixup_f32 v3, v3, v7, 1.0
	v_mul_f32_e32 v7, 0xbfb8aa3b, v67
	v_exp_f32_e32 v8, v7
	v_or_b32_e32 v6, 0x61, v2
	v_ashrrev_i32_e32 v7, 31, v6
	v_lshlrev_b64 v[6:7], 13, v[6:7]
	v_add_f32_e32 v9, 1.0, v8
	v_div_scale_f32 v10, s[8:9], v9, v9, 1.0
	v_rcp_f32_e32 v11, v10
	v_lshl_add_u64 v[6:7], v[0:1], 0, v[6:7]
	v_add_co_u32_e32 v6, vcc, s10, v6
	v_cvt_pk_bf16_f32 v3, v3, s0
	s_nop 0
	v_addc_co_u32_e32 v7, vcc, -1, v7, vcc
	global_store_short v[6:7], v3, off offset:-1408
	v_fma_f32 v3, -v10, v11, 1.0
	v_fmac_f32_e32 v11, v3, v11
	v_div_scale_f32 v3, vcc, 1.0, v9, 1.0
	v_mul_f32_e32 v12, v3, v11
	v_fma_f32 v13, -v10, v12, v3
	v_fmac_f32_e32 v12, v13, v11
	v_fma_f32 v3, -v10, v12, v3
	v_div_fmas_f32 v3, v3, v11, v12
	v_div_fixup_f32 v3, v3, v9, 1.0
	v_mul_f32_e32 v9, 0xbfb8aa3b, v66
	v_exp_f32_e32 v10, v9
	v_or_b32_e32 v8, 0x62, v2
	v_ashrrev_i32_e32 v9, 31, v8
	v_lshlrev_b64 v[8:9], 13, v[8:9]
; DI float sigmoidf_(float v) { return 1.f / (1.f + __expf(-v)); }
; DI void phase_in(const Params& p, int L, char* smem) {
;     ...
;     if (cb >= 43) {
;       if (cb < 107) {
;         EPI_BEGINM(acc, 4) p.gates[(size_t)row * 4096 + (col - 2752)] = f2bf(sigmoidf_(v)); EPI_END
	v_add_f32_e32 v11, 1.0, v10
	v_div_scale_f32 v12, s[8:9], v11, v11, 1.0
	v_rcp_f32_e32 v13, v12
	v_lshl_add_u64 v[8:9], v[0:1], 0, v[8:9]
	v_add_co_u32_e32 v8, vcc, s10, v8
	v_cvt_pk_bf16_f32 v3, v3, s0
	s_nop 0
	v_addc_co_u32_e32 v9, vcc, -1, v9, vcc
	global_store_short v[8:9], v3, off offset:-1408
	v_fma_f32 v3, -v12, v13, 1.0
	v_fmac_f32_e32 v13, v3, v13
	v_div_scale_f32 v3, vcc, 1.0, v11, 1.0
	v_mul_f32_e32 v14, v3, v13
	v_fma_f32 v15, -v12, v14, v3
	v_fmac_f32_e32 v14, v15, v13
	v_fma_f32 v3, -v12, v14, v3
	v_div_fmas_f32 v3, v3, v13, v14
	v_div_fixup_f32 v3, v3, v11, 1.0
	v_mul_f32_e32 v11, 0xbfb8aa3b, v65
	v_exp_f32_e32 v12, v11
	v_or_b32_e32 v10, 0x63, v2
	v_ashrrev_i32_e32 v11, 31, v10
	v_lshlrev_b64 v[10:11], 13, v[10:11]
	v_add_f32_e32 v13, 1.0, v12
	v_div_scale_f32 v14, s[8:9], v13, v13, 1.0
	v_rcp_f32_e32 v15, v14
	v_lshl_add_u64 v[10:11], v[0:1], 0, v[10:11]
	v_add_co_u32_e32 v10, vcc, s10, v10
	v_cvt_pk_bf16_f32 v3, v3, s0
	s_nop 0
	v_addc_co_u32_e32 v11, vcc, -1, v11, vcc
	global_store_short v[10:11], v3, off offset:-1408
	v_fma_f32 v3, -v14, v15, 1.0
	v_fmac_f32_e32 v15, v3, v15
	v_div_scale_f32 v3, vcc, 1.0, v13, 1.0
	v_mul_f32_e32 v16, v3, v15
	v_fma_f32 v17, -v14, v16, v3
	v_fmac_f32_e32 v16, v17, v15
	v_fma_f32 v3, -v14, v16, v3
	v_div_fmas_f32 v3, v3, v15, v16
	v_div_fixup_f32 v3, v3, v13, 1.0
	v_mul_f32_e32 v13, 0xbfb8aa3b, v64
	v_exp_f32_e32 v14, v13
	v_or_b32_e32 v12, 0x68, v2
	v_ashrrev_i32_e32 v13, 31, v12
	v_lshlrev_b64 v[12:13], 13, v[12:13]
	v_add_f32_e32 v15, 1.0, v14
	v_div_scale_f32 v16, s[8:9], v15, v15, 1.0
	v_rcp_f32_e32 v17, v16
	v_lshl_add_u64 v[12:13], v[0:1], 0, v[12:13]
	v_add_co_u32_e32 v12, vcc, s10, v12
	v_cvt_pk_bf16_f32 v3, v3, s0
	s_nop 0
	v_addc_co_u32_e32 v13, vcc, -1, v13, vcc
	global_store_short v[12:13], v3, off offset:-1408
	v_fma_f32 v3, -v16, v17, 1.0
	v_fmac_f32_e32 v17, v3, v17
	v_div_scale_f32 v3, vcc, 1.0, v15, 1.0
	v_mul_f32_e32 v18, v3, v17
	v_fma_f32 v19, -v16, v18, v3
	v_fmac_f32_e32 v18, v19, v17
	v_fma_f32 v3, -v16, v18, v3
	v_div_fmas_f32 v3, v3, v17, v18
	v_div_fixup_f32 v3, v3, v15, 1.0
	v_mul_f32_e32 v15, 0xbfb8aa3b, v63
	v_exp_f32_e32 v16, v15
	v_or_b32_e32 v14, 0x69, v2
	v_ashrrev_i32_e32 v15, 31, v14
	v_lshlrev_b64 v[14:15], 13, v[14:15]
	v_add_f32_e32 v17, 1.0, v16
	v_div_scale_f32 v18, s[8:9], v17, v17, 1.0
	v_rcp_f32_e32 v19, v18
	v_lshl_add_u64 v[14:15], v[0:1], 0, v[14:15]
	v_add_co_u32_e32 v14, vcc, s10, v14
	v_cvt_pk_bf16_f32 v3, v3, s0
	s_nop 0
	v_addc_co_u32_e32 v15, vcc, -1, v15, vcc
	global_store_short v[14:15], v3, off offset:-1408
	v_fma_f32 v3, -v18, v19, 1.0
	v_fmac_f32_e32 v19, v3, v19
	v_div_scale_f32 v3, vcc, 1.0, v17, 1.0
	v_mul_f32_e32 v20, v3, v19
	v_fma_f32 v21, -v18, v20, v3
	v_fmac_f32_e32 v20, v21, v19
	v_fma_f32 v3, -v18, v20, v3
	v_div_fmas_f32 v3, v3, v19, v20
	v_div_fixup_f32 v3, v3, v17, 1.0
	v_mul_f32_e32 v17, 0xbfb8aa3b, v62
	v_exp_f32_e32 v18, v17
	v_or_b32_e32 v16, 0x6a, v2
	v_ashrrev_i32_e32 v17, 31, v16
	v_lshlrev_b64 v[16:17], 13, v[16:17]
	v_add_f32_e32 v19, 1.0, v18
	v_div_scale_f32 v20, s[8:9], v19, v19, 1.0
	v_rcp_f32_e32 v21, v20
	v_lshl_add_u64 v[16:17], v[0:1], 0, v[16:17]
	v_add_co_u32_e32 v16, vcc, s10, v16
	v_cvt_pk_bf16_f32 v3, v3, s0
	s_nop 0
	v_addc_co_u32_e32 v17, vcc, -1, v17, vcc
	global_store_short v[16:17], v3, off offset:-1408
	v_fma_f32 v3, -v20, v21, 1.0
	v_fmac_f32_e32 v21, v3, v21
	v_div_scale_f32 v3, vcc, 1.0, v19, 1.0
	v_mul_f32_e32 v22, v3, v21
	v_fma_f32 v23, -v20, v22, v3
	v_fmac_f32_e32 v22, v23, v21
	v_fma_f32 v3, -v20, v22, v3
	v_div_fmas_f32 v3, v3, v21, v22
	v_div_fixup_f32 v3, v3, v19, 1.0
	v_mul_f32_e32 v19, 0xbfb8aa3b, v61
	v_exp_f32_e32 v20, v19
	v_or_b32_e32 v18, 0x6b, v2
	v_ashrrev_i32_e32 v19, 31, v18
	v_lshlrev_b64 v[18:19], 13, v[18:19]
	v_add_f32_e32 v21, 1.0, v20
	v_div_scale_f32 v22, s[8:9], v21, v21, 1.0
	v_rcp_f32_e32 v23, v22
	v_lshl_add_u64 v[18:19], v[0:1], 0, v[18:19]
	v_add_co_u32_e32 v18, vcc, s10, v18
	v_cvt_pk_bf16_f32 v3, v3, s0
	s_nop 0
	v_addc_co_u32_e32 v19, vcc, -1, v19, vcc
	global_store_short v[18:19], v3, off offset:-1408
	v_fma_f32 v3, -v22, v23, 1.0
	v_fmac_f32_e32 v23, v3, v23
	v_div_scale_f32 v3, vcc, 1.0, v21, 1.0
	v_mul_f32_e32 v24, v3, v23
	v_fma_f32 v25, -v22, v24, v3
	v_fmac_f32_e32 v24, v25, v23
	v_fma_f32 v3, -v22, v24, v3
	v_div_fmas_f32 v3, v3, v23, v24
	v_div_fixup_f32 v3, v3, v21, 1.0
	v_mul_f32_e32 v21, 0xbfb8aa3b, v60
	v_exp_f32_e32 v22, v21
	v_or_b32_e32 v20, 0x70, v2
	v_ashrrev_i32_e32 v21, 31, v20
	v_lshlrev_b64 v[20:21], 13, v[20:21]
	v_add_f32_e32 v23, 1.0, v22
	v_div_scale_f32 v24, s[8:9], v23, v23, 1.0
	v_rcp_f32_e32 v25, v24
	v_lshl_add_u64 v[20:21], v[0:1], 0, v[20:21]
	v_add_co_u32_e32 v20, vcc, s10, v20
	v_cvt_pk_bf16_f32 v3, v3, s0
	s_nop 0
	v_addc_co_u32_e32 v21, vcc, -1, v21, vcc
	global_store_short v[20:21], v3, off offset:-1408
	v_fma_f32 v3, -v24, v25, 1.0
	v_fmac_f32_e32 v25, v3, v25
	v_div_scale_f32 v3, vcc, 1.0, v23, 1.0
	v_mul_f32_e32 v26, v3, v25
	v_fma_f32 v27, -v24, v26, v3
	v_fmac_f32_e32 v26, v27, v25
	v_fma_f32 v3, -v24, v26, v3
	v_div_fmas_f32 v3, v3, v25, v26
	v_div_fixup_f32 v3, v3, v23, 1.0
	v_mul_f32_e32 v23, 0xbfb8aa3b, v59
	v_exp_f32_e32 v24, v23
	v_or_b32_e32 v22, 0x71, v2
	v_ashrrev_i32_e32 v23, 31, v22
	v_lshlrev_b64 v[22:23], 13, v[22:23]
	v_add_f32_e32 v25, 1.0, v24
	v_div_scale_f32 v26, s[8:9], v25, v25, 1.0
	v_rcp_f32_e32 v27, v26
	v_lshl_add_u64 v[22:23], v[0:1], 0, v[22:23]
	v_add_co_u32_e32 v22, vcc, s10, v22
	v_cvt_pk_bf16_f32 v3, v3, s0
	s_nop 0
	v_addc_co_u32_e32 v23, vcc, -1, v23, vcc
	global_store_short v[22:23], v3, off offset:-1408
	v_fma_f32 v3, -v26, v27, 1.0
	v_fmac_f32_e32 v27, v3, v27
; DI float sigmoidf_(float v) { return 1.f / (1.f + __expf(-v)); }
; DI void phase_in(const Params& p, int L, char* smem) {
;     ...
;     if (cb >= 43) {
;       if (cb < 107) {
;         EPI_BEGINM(acc, 4) p.gates[(size_t)row * 4096 + (col - 2752)] = f2bf(sigmoidf_(v)); EPI_END
	v_div_scale_f32 v3, vcc, 1.0, v25, 1.0
	v_mul_f32_e32 v28, v3, v27
	v_fma_f32 v29, -v26, v28, v3
	v_fmac_f32_e32 v28, v29, v27
	v_fma_f32 v3, -v26, v28, v3
	v_div_fmas_f32 v3, v3, v27, v28
	v_div_fixup_f32 v3, v3, v25, 1.0
	v_mul_f32_e32 v25, 0xbfb8aa3b, v58
	v_exp_f32_e32 v26, v25
	v_or_b32_e32 v24, 0x72, v2
	v_ashrrev_i32_e32 v25, 31, v24
	v_lshlrev_b64 v[24:25], 13, v[24:25]
	v_add_f32_e32 v27, 1.0, v26
	v_div_scale_f32 v28, s[8:9], v27, v27, 1.0
	v_rcp_f32_e32 v29, v28
	v_lshl_add_u64 v[24:25], v[0:1], 0, v[24:25]
	v_add_co_u32_e32 v24, vcc, s10, v24
	v_cvt_pk_bf16_f32 v3, v3, s0
	s_nop 0
	v_addc_co_u32_e32 v25, vcc, -1, v25, vcc
	global_store_short v[24:25], v3, off offset:-1408
	v_fma_f32 v3, -v28, v29, 1.0
	v_fmac_f32_e32 v29, v3, v29
	v_div_scale_f32 v3, vcc, 1.0, v27, 1.0
	v_mul_f32_e32 v30, v3, v29
	v_fma_f32 v31, -v28, v30, v3
	v_fmac_f32_e32 v30, v31, v29
	v_fma_f32 v3, -v28, v30, v3
	v_div_fmas_f32 v3, v3, v29, v30
	v_div_fixup_f32 v3, v3, v27, 1.0
	v_mul_f32_e32 v27, 0xbfb8aa3b, v57
	v_exp_f32_e32 v28, v27
	v_or_b32_e32 v26, 0x73, v2
	v_ashrrev_i32_e32 v27, 31, v26
	v_lshlrev_b64 v[26:27], 13, v[26:27]
	v_add_f32_e32 v29, 1.0, v28
	v_div_scale_f32 v30, s[8:9], v29, v29, 1.0
	v_rcp_f32_e32 v31, v30
	v_lshl_add_u64 v[26:27], v[0:1], 0, v[26:27]
	v_add_co_u32_e32 v26, vcc, s10, v26
	v_cvt_pk_bf16_f32 v3, v3, s0
	s_nop 0
	v_addc_co_u32_e32 v27, vcc, -1, v27, vcc
	global_store_short v[26:27], v3, off offset:-1408
	v_fma_f32 v3, -v30, v31, 1.0
	v_fmac_f32_e32 v31, v3, v31
	v_div_scale_f32 v3, vcc, 1.0, v29, 1.0
	v_mul_f32_e32 v32, v3, v31
	v_fma_f32 v33, -v30, v32, v3
	v_fmac_f32_e32 v32, v33, v31
	v_fma_f32 v3, -v30, v32, v3
	v_div_fmas_f32 v3, v3, v31, v32
	v_div_fixup_f32 v3, v3, v29, 1.0
	v_mul_f32_e32 v29, 0xbfb8aa3b, v56
	v_exp_f32_e32 v30, v29
	v_or_b32_e32 v28, 0x78, v2
	v_ashrrev_i32_e32 v29, 31, v28
	v_lshlrev_b64 v[28:29], 13, v[28:29]
	v_add_f32_e32 v31, 1.0, v30
	v_div_scale_f32 v32, s[8:9], v31, v31, 1.0
	v_rcp_f32_e32 v33, v32
	v_lshl_add_u64 v[28:29], v[0:1], 0, v[28:29]
	v_add_co_u32_e32 v28, vcc, s10, v28
	v_cvt_pk_bf16_f32 v3, v3, s0
	s_nop 0
	v_addc_co_u32_e32 v29, vcc, -1, v29, vcc
	global_store_short v[28:29], v3, off offset:-1408
	v_fma_f32 v3, -v32, v33, 1.0
	v_fmac_f32_e32 v33, v3, v33
	v_div_scale_f32 v3, vcc, 1.0, v31, 1.0
	v_mul_f32_e32 v34, v3, v33
	v_fma_f32 v35, -v32, v34, v3
	v_fmac_f32_e32 v34, v35, v33
	v_fma_f32 v3, -v32, v34, v3
	v_div_fmas_f32 v3, v3, v33, v34
	v_div_fixup_f32 v3, v3, v31, 1.0
	v_mul_f32_e32 v31, 0xbfb8aa3b, v55
	v_exp_f32_e32 v32, v31
	v_or_b32_e32 v30, 0x79, v2
	v_ashrrev_i32_e32 v31, 31, v30
	v_lshlrev_b64 v[30:31], 13, v[30:31]
	v_add_f32_e32 v33, 1.0, v32
	v_div_scale_f32 v34, s[8:9], v33, v33, 1.0
	v_rcp_f32_e32 v35, v34
	v_lshl_add_u64 v[30:31], v[0:1], 0, v[30:31]
	v_add_co_u32_e32 v30, vcc, s10, v30
	v_cvt_pk_bf16_f32 v3, v3, s0
	s_nop 0
	v_addc_co_u32_e32 v31, vcc, -1, v31, vcc
	global_store_short v[30:31], v3, off offset:-1408
	v_fma_f32 v3, -v34, v35, 1.0
	v_fmac_f32_e32 v35, v3, v35
	v_div_scale_f32 v3, vcc, 1.0, v33, 1.0
	v_mul_f32_e32 v36, v3, v35
	v_fma_f32 v37, -v34, v36, v3
	v_fmac_f32_e32 v36, v37, v35
	v_fma_f32 v3, -v34, v36, v3
	v_div_fmas_f32 v3, v3, v35, v36
	v_div_fixup_f32 v3, v3, v33, 1.0
	v_mul_f32_e32 v33, 0xbfb8aa3b, v54
	v_exp_f32_e32 v34, v33
	v_or_b32_e32 v32, 0x7a, v2
	v_ashrrev_i32_e32 v33, 31, v32
	v_lshlrev_b64 v[32:33], 13, v[32:33]
	v_add_f32_e32 v34, 1.0, v34
	v_div_scale_f32 v35, s[8:9], v34, v34, 1.0
	v_rcp_f32_e32 v36, v35
	v_lshl_add_u64 v[32:33], v[0:1], 0, v[32:33]
	v_add_co_u32_e32 v32, vcc, s10, v32
	v_cvt_pk_bf16_f32 v3, v3, s0
	s_nop 0
	v_addc_co_u32_e32 v33, vcc, -1, v33, vcc
	global_store_short v[32:33], v3, off offset:-1408
	v_fma_f32 v3, -v35, v36, 1.0
	v_fmac_f32_e32 v36, v3, v36
	v_div_scale_f32 v3, vcc, 1.0, v34, 1.0
	v_mul_f32_e32 v37, v3, v36
	v_fma_f32 v54, -v35, v37, v3
	v_fmac_f32_e32 v37, v54, v36
	v_fma_f32 v3, -v35, v37, v3
	v_div_fmas_f32 v3, v3, v36, v37
	v_div_fixup_f32 v3, v3, v34, 1.0
	v_cvt_pk_bf16_f32 v34, v3, s0
	v_mul_f32_e32 v3, 0xbfb8aa3b, v53
	v_exp_f32_e32 v35, v3
	v_or_b32_e32 v2, 0x7b, v2
	v_ashrrev_i32_e32 v3, 31, v2
	v_lshlrev_b64 v[2:3], 13, v[2:3]
	v_lshl_add_u64 v[0:1], v[0:1], 0, v[2:3]
	v_add_f32_e32 v2, 1.0, v35
	v_div_scale_f32 v3, s[8:9], v2, v2, 1.0
	v_rcp_f32_e32 v35, v3
	v_add_co_u32_e32 v0, vcc, s10, v0
	s_nop 1
	v_addc_co_u32_e32 v1, vcc, -1, v1, vcc
	global_store_short v[0:1], v34, off offset:-1408
	v_fma_f32 v34, -v3, v35, 1.0
	v_fmac_f32_e32 v35, v34, v35
	v_div_scale_f32 v34, vcc, 1.0, v2, 1.0
	v_mul_f32_e32 v36, v34, v35
	v_fma_f32 v37, -v3, v36, v34
	v_fmac_f32_e32 v36, v37, v35
	v_mul_f32_e32 v37, 0xbfb8aa3b, v52
	v_exp_f32_e32 v37, v37
	v_fma_f32 v3, -v3, v36, v34
	v_div_fmas_f32 v3, v3, v35, v36
	v_div_fixup_f32 v2, v3, v2, 1.0
	v_add_f32_e32 v34, 1.0, v37
	v_div_scale_f32 v35, s[8:9], v34, v34, 1.0
	v_rcp_f32_e32 v36, v35
	v_cvt_pk_bf16_f32 v2, v2, s0
	global_store_short v[4:5], v2, off offset:-1344
	v_fma_f32 v2, -v35, v36, 1.0
	v_fmac_f32_e32 v36, v2, v36
	v_div_scale_f32 v2, vcc, 1.0, v34, 1.0
	v_mul_f32_e32 v3, v2, v36
	v_fma_f32 v4, -v35, v3, v2
	v_fmac_f32_e32 v3, v4, v36
	v_mul_f32_e32 v4, 0xbfb8aa3b, v51
	v_exp_f32_e32 v4, v4
	v_fma_f32 v2, -v35, v3, v2
	v_div_fmas_f32 v2, v2, v36, v3
	v_div_fixup_f32 v2, v2, v34, 1.0
	v_add_f32_e32 v3, 1.0, v4
	v_div_scale_f32 v4, s[8:9], v3, v3, 1.0
	v_rcp_f32_e32 v5, v4
	v_cvt_pk_bf16_f32 v2, v2, s0
	global_store_short v[6:7], v2, off offset:-1344
	v_fma_f32 v2, -v4, v5, 1.0
	v_fmac_f32_e32 v5, v2, v5
	v_div_scale_f32 v2, vcc, 1.0, v3, 1.0
	v_mul_f32_e32 v6, v2, v5
	v_fma_f32 v7, -v4, v6, v2
	v_fmac_f32_e32 v6, v7, v5
; DI float sigmoidf_(float v) { return 1.f / (1.f + __expf(-v)); }
; DI void phase_in(const Params& p, int L, char* smem) {
;     ...
;     if (cb >= 43) {
;       if (cb < 107) {
;         EPI_BEGINM(acc, 4) p.gates[(size_t)row * 4096 + (col - 2752)] = f2bf(sigmoidf_(v)); EPI_END
	v_mul_f32_e32 v7, 0xbfb8aa3b, v50
	v_exp_f32_e32 v7, v7
	v_fma_f32 v2, -v4, v6, v2
	v_div_fmas_f32 v2, v2, v5, v6
	v_div_fixup_f32 v2, v2, v3, 1.0
	v_add_f32_e32 v4, 1.0, v7
	v_div_scale_f32 v5, s[8:9], v4, v4, 1.0
	v_rcp_f32_e32 v6, v5
	v_cvt_pk_bf16_f32 v2, v2, s0
	global_store_short v[8:9], v2, off offset:-1344
	v_fma_f32 v2, -v5, v6, 1.0
	v_fmac_f32_e32 v6, v2, v6
	v_div_scale_f32 v2, vcc, 1.0, v4, 1.0
	v_mul_f32_e32 v3, v2, v6
	v_fma_f32 v7, -v5, v3, v2
	v_fmac_f32_e32 v3, v7, v6
	v_mul_f32_e32 v7, 0xbfb8aa3b, v49
	v_exp_f32_e32 v7, v7
	v_fma_f32 v2, -v5, v3, v2
	v_div_fmas_f32 v2, v2, v6, v3
	v_div_fixup_f32 v2, v2, v4, 1.0
	v_add_f32_e32 v3, 1.0, v7
	v_div_scale_f32 v5, s[8:9], v3, v3, 1.0
	v_rcp_f32_e32 v6, v5
	v_cvt_pk_bf16_f32 v2, v2, s0
	global_store_short v[10:11], v2, off offset:-1344
	v_fma_f32 v2, -v5, v6, 1.0
	v_fmac_f32_e32 v6, v2, v6
	v_div_scale_f32 v2, vcc, 1.0, v3, 1.0
	v_mul_f32_e32 v4, v2, v6
	v_fma_f32 v7, -v5, v4, v2
	v_fmac_f32_e32 v4, v7, v6
	v_mul_f32_e32 v7, 0xbfb8aa3b, v48
	v_exp_f32_e32 v7, v7
	v_fma_f32 v2, -v5, v4, v2
	v_div_fmas_f32 v2, v2, v6, v4
	v_div_fixup_f32 v2, v2, v3, 1.0
	v_add_f32_e32 v4, 1.0, v7
	v_div_scale_f32 v5, s[8:9], v4, v4, 1.0
	v_rcp_f32_e32 v6, v5
	v_cvt_pk_bf16_f32 v2, v2, s0
	global_store_short v[12:13], v2, off offset:-1344
	v_fma_f32 v2, -v5, v6, 1.0
	v_fmac_f32_e32 v6, v2, v6
	v_div_scale_f32 v2, vcc, 1.0, v4, 1.0
	v_mul_f32_e32 v3, v2, v6
	v_fma_f32 v7, -v5, v3, v2
	v_fmac_f32_e32 v3, v7, v6
	v_mul_f32_e32 v7, 0xbfb8aa3b, v47
	v_exp_f32_e32 v7, v7
	v_fma_f32 v2, -v5, v3, v2
	v_div_fmas_f32 v2, v2, v6, v3
	v_div_fixup_f32 v2, v2, v4, 1.0
	v_add_f32_e32 v3, 1.0, v7
	v_div_scale_f32 v5, s[8:9], v3, v3, 1.0
	v_rcp_f32_e32 v6, v5
	v_cvt_pk_bf16_f32 v2, v2, s0
	global_store_short v[14:15], v2, off offset:-1344
	v_fma_f32 v2, -v5, v6, 1.0
	v_fmac_f32_e32 v6, v2, v6
	v_div_scale_f32 v2, vcc, 1.0, v3, 1.0
	v_mul_f32_e32 v4, v2, v6
	v_fma_f32 v7, -v5, v4, v2
	v_fmac_f32_e32 v4, v7, v6
	v_mul_f32_e32 v7, 0xbfb8aa3b, v46
	v_exp_f32_e32 v7, v7
	v_fma_f32 v2, -v5, v4, v2
	v_div_fmas_f32 v2, v2, v6, v4
	v_div_fixup_f32 v2, v2, v3, 1.0
	v_add_f32_e32 v4, 1.0, v7
	v_div_scale_f32 v5, s[8:9], v4, v4, 1.0
	v_rcp_f32_e32 v6, v5
	v_cvt_pk_bf16_f32 v2, v2, s0
	global_store_short v[16:17], v2, off offset:-1344
	v_fma_f32 v2, -v5, v6, 1.0
	v_fmac_f32_e32 v6, v2, v6
	v_div_scale_f32 v2, vcc, 1.0, v4, 1.0
	v_mul_f32_e32 v3, v2, v6
	v_fma_f32 v7, -v5, v3, v2
	v_fmac_f32_e32 v3, v7, v6
	v_mul_f32_e32 v7, 0xbfb8aa3b, v45
	v_exp_f32_e32 v7, v7
	v_fma_f32 v2, -v5, v3, v2
	v_div_fmas_f32 v2, v2, v6, v3
	v_div_fixup_f32 v2, v2, v4, 1.0
	v_add_f32_e32 v3, 1.0, v7
	v_div_scale_f32 v5, s[8:9], v3, v3, 1.0
	v_rcp_f32_e32 v6, v5
	v_cvt_pk_bf16_f32 v2, v2, s0
	global_store_short v[18:19], v2, off offset:-1344
	v_fma_f32 v2, -v5, v6, 1.0
	v_fmac_f32_e32 v6, v2, v6
	v_div_scale_f32 v2, vcc, 1.0, v3, 1.0
	v_mul_f32_e32 v4, v2, v6
	v_fma_f32 v7, -v5, v4, v2
	v_fmac_f32_e32 v4, v7, v6
	v_mul_f32_e32 v7, 0xbfb8aa3b, v44
	v_exp_f32_e32 v7, v7
	v_fma_f32 v2, -v5, v4, v2
	v_div_fmas_f32 v2, v2, v6, v4
	v_div_fixup_f32 v2, v2, v3, 1.0
	v_add_f32_e32 v4, 1.0, v7
	v_div_scale_f32 v5, s[8:9], v4, v4, 1.0
	v_rcp_f32_e32 v6, v5
	v_cvt_pk_bf16_f32 v2, v2, s0
	global_store_short v[20:21], v2, off offset:-1344
	v_fma_f32 v2, -v5, v6, 1.0
	v_fmac_f32_e32 v6, v2, v6
	v_div_scale_f32 v2, vcc, 1.0, v4, 1.0
	v_mul_f32_e32 v3, v2, v6
	v_fma_f32 v7, -v5, v3, v2
	v_fmac_f32_e32 v3, v7, v6
	v_mul_f32_e32 v7, 0xbfb8aa3b, v43
	v_exp_f32_e32 v7, v7
	v_fma_f32 v2, -v5, v3, v2
	v_div_fmas_f32 v2, v2, v6, v3
	v_div_fixup_f32 v2, v2, v4, 1.0
	v_add_f32_e32 v3, 1.0, v7
	v_div_scale_f32 v5, s[8:9], v3, v3, 1.0
	v_rcp_f32_e32 v6, v5
	v_cvt_pk_bf16_f32 v2, v2, s0
	global_store_short v[22:23], v2, off offset:-1344
	v_fma_f32 v2, -v5, v6, 1.0
	v_fmac_f32_e32 v6, v2, v6
	v_div_scale_f32 v2, vcc, 1.0, v3, 1.0
	v_mul_f32_e32 v4, v2, v6
	v_fma_f32 v7, -v5, v4, v2
	v_fmac_f32_e32 v4, v7, v6
	v_mul_f32_e32 v7, 0xbfb8aa3b, v42
	v_exp_f32_e32 v7, v7
	v_fma_f32 v2, -v5, v4, v2
	v_div_fmas_f32 v2, v2, v6, v4
	v_div_fixup_f32 v2, v2, v3, 1.0
	v_add_f32_e32 v4, 1.0, v7
	v_div_scale_f32 v5, s[8:9], v4, v4, 1.0
	v_rcp_f32_e32 v6, v5
	v_cvt_pk_bf16_f32 v2, v2, s0
	global_store_short v[24:25], v2, off offset:-1344
	v_fma_f32 v2, -v5, v6, 1.0
	v_fmac_f32_e32 v6, v2, v6
	v_div_scale_f32 v2, vcc, 1.0, v4, 1.0
	v_mul_f32_e32 v3, v2, v6
	v_fma_f32 v7, -v5, v3, v2
	v_fmac_f32_e32 v3, v7, v6
	v_mul_f32_e32 v7, 0xbfb8aa3b, v41
	v_exp_f32_e32 v7, v7
	v_fma_f32 v2, -v5, v3, v2
	v_div_fmas_f32 v2, v2, v6, v3
	v_div_fixup_f32 v2, v2, v4, 1.0
	v_add_f32_e32 v3, 1.0, v7
	v_div_scale_f32 v5, s[8:9], v3, v3, 1.0
	v_rcp_f32_e32 v6, v5
	v_cvt_pk_bf16_f32 v2, v2, s0
	global_store_short v[26:27], v2, off offset:-1344
	v_fma_f32 v2, -v5, v6, 1.0
	v_fmac_f32_e32 v6, v2, v6
	v_div_scale_f32 v2, vcc, 1.0, v3, 1.0
	v_mul_f32_e32 v4, v2, v6
	v_fma_f32 v7, -v5, v4, v2
	v_fmac_f32_e32 v4, v7, v6
	v_mul_f32_e32 v7, 0xbfb8aa3b, v40
	v_exp_f32_e32 v7, v7
	v_fma_f32 v2, -v5, v4, v2
	v_div_fmas_f32 v2, v2, v6, v4
	v_div_fixup_f32 v2, v2, v3, 1.0
	v_add_f32_e32 v4, 1.0, v7
	v_div_scale_f32 v5, s[8:9], v4, v4, 1.0
	v_rcp_f32_e32 v6, v5
	v_cvt_pk_bf16_f32 v2, v2, s0
	global_store_short v[28:29], v2, off offset:-1344
	v_fma_f32 v2, -v5, v6, 1.0
	v_fmac_f32_e32 v6, v2, v6
	v_div_scale_f32 v2, vcc, 1.0, v4, 1.0
	v_mul_f32_e32 v3, v2, v6
	v_fma_f32 v7, -v5, v3, v2
	v_fmac_f32_e32 v3, v7, v6
	v_mul_f32_e32 v7, 0xbfb8aa3b, v39
	v_exp_f32_e32 v7, v7
	v_fma_f32 v2, -v5, v3, v2
	v_div_fmas_f32 v2, v2, v6, v3
	v_div_fixup_f32 v2, v2, v4, 1.0
	v_add_f32_e32 v3, 1.0, v7
	v_div_scale_f32 v5, s[8:9], v3, v3, 1.0
	v_rcp_f32_e32 v6, v5
	v_cvt_pk_bf16_f32 v2, v2, s0
	global_store_short v[30:31], v2, off offset:-1344
	v_fma_f32 v2, -v5, v6, 1.0
	v_fmac_f32_e32 v6, v2, v6
	v_div_scale_f32 v2, vcc, 1.0, v3, 1.0
	v_mul_f32_e32 v4, v2, v6
	v_fma_f32 v7, -v5, v4, v2
	v_fmac_f32_e32 v4, v7, v6
	v_mul_f32_e32 v7, 0xbfb8aa3b, v38
	v_exp_f32_e32 v7, v7
	v_fma_f32 v2, -v5, v4, v2
	v_div_fmas_f32 v2, v2, v6, v4
	v_div_fixup_f32 v2, v2, v3, 1.0
	v_add_f32_e32 v4, 1.0, v7
	v_div_scale_f32 v5, s[8:9], v4, v4, 1.0
	v_rcp_f32_e32 v6, v5
	v_cvt_pk_bf16_f32 v2, v2, s0
	global_store_short v[32:33], v2, off offset:-1344
	v_fma_f32 v2, -v5, v6, 1.0
	v_fmac_f32_e32 v6, v2, v6
	v_div_scale_f32 v2, vcc, 1.0, v4, 1.0
	v_mul_f32_e32 v3, v2, v6
	v_fma_f32 v7, -v5, v3, v2
	v_fmac_f32_e32 v3, v7, v6
	v_fma_f32 v2, -v5, v3, v2
	v_div_fmas_f32 v2, v2, v6, v3
	v_div_fixup_f32 v2, v2, v4, 1.0
	v_cvt_pk_bf16_f32 v2, v2, s0
	global_store_short v[0:1], v2, off offset:-1344
	s_branch .LBB0_778
.LBB0_1899:
	s_mov_b64 s[2:3], 0
